# adds: norm phase rows processed in descending order (MALL reuse), duplicate lgkmcnt waits removed in GEMM loops, permlane32_swap for cross-half max in MLA loop
# speedup vs baseline: 1.0128x; 1.0040x over previous
; #define GAS __attribute__((address_space(1)))
; DI void phase_norm(const Params& p, const int tid, const float* hlat, const float* g, const float* modl, int sidx, int nrows, const float* pgate  , float pcoef) {
;   const int w = tid >> 6, lane = tid & 63;
;   float* hctx = (float*)(p.ws + OFF_HCTX); bf16_t* XN = (bf16_t*)(p.ws + OFF_XN); const float* pctx = (const float*)(p.ws + OFF_PCTX);
;   f32x4 gv[4];
; #pragma unroll
;   for (int i = 0; i < 4; ++i) gv[i] = *(const GAS f32x4*)(g + (i * 64 + lane) * 4);
;   for (int row0 = (blockIdx.x * 8 + w) * 4; row0 < nrows; row0 += gridDim.x * 32) {
;     float* hp = row0 < TL ? const_cast<float*>(hlat) + (size_t)row0 * D : hctx + (size_t)(row0 - TL) * D; const int b = row0 < TL ? (row0 >> 11) : 16;
;     const float* sh = modl + (size_t)b * NMODW + sidx * 1024; const float* scp = sh + 1024;
;     const bool addp = pgate != nullptr && row0 >= TL;
;     f32x4 xv[4][4]; float ss[4];
; #pragma unroll
;     for (int j = 0; j < 4; ++j)
; #pragma unroll
;       for (int i = 0; i < 4; ++i) xv[j][i] = *(const GAS f32x4*)(hp + (size_t)j * D + (i * 64 + lane) * 4);
;     if (addp) {
.LBB0_330:
	s_and_b32 s3, 0xffff, s2
	v_writelane_b32 v254, s3, 58
	s_add_i32 s3, s57, -9
	s_cmp_lt_u32 s3, 3
	s_cselect_b64 s[4:5], -1, 0
	s_cmp_gt_u32 s3, 2
	s_cselect_b64 s[12:13], -1, 0
	v_writelane_b32 v254, s12, 59
	s_mov_b32 s3, 0x8000
	v_ashrrev_i32_e32 v2, 4, v0
	v_writelane_b32 v254, s13, 60
	v_writelane_b32 v254, s4, 61
	v_readlane_b32 s72, v253, 10
	v_and_b32_e32 v2, -4, v2
	v_writelane_b32 v254, s5, 62
	s_and_b64 s[4:5], s[4:5], s[6:7]
	s_and_b64 s[4:5], s[4:5], exec
	s_cselect_b32 s3, s3, 0x9000
	s_cmp_eq_u32 s57, 0
	s_cselect_b64 s[4:5], -1, 0
	v_writelane_b32 v254, s4, 63
	v_readlane_b32 s73, v253, 11
	s_mov_b64 s[12:13], s[72:73]
	v_writelane_b32 v255, s5, 0
	v_readlane_b32 s4, v254, 57
	s_cmp_eq_u32 s4, 0
	s_cselect_b64 s[4:5], -1, 0
	v_writelane_b32 v255, s4, 1
	v_readlane_b32 s74, v253, 12
	v_readlane_b32 s75, v253, 13
	v_writelane_b32 v255, s5, 2
	v_readlane_b32 s4, v253, 58
	v_readlane_b32 s76, v253, 14
	v_readlane_b32 s77, v253, 15
	v_add_u32_e32 v90, s4, v2
	v_cmp_gt_i32_e32 vcc, s3, v90
	v_readlane_b32 s78, v253, 16
	v_readlane_b32 s79, v253, 17
	v_readlane_b32 s80, v253, 18
	v_readlane_b32 s81, v253, 19
	v_readlane_b32 s82, v253, 20
	v_readlane_b32 s83, v253, 21
	v_readlane_b32 s84, v253, 22
	v_readlane_b32 s85, v253, 23
	v_readlane_b32 s86, v253, 24
	v_readlane_b32 s87, v253, 25
	s_and_saveexec_b64 s[4:5], vcc
	s_cbranch_execz .LBB0_335
	v_sub_u32_e32 v90, s3, v90
	v_add_u32_e32 v90, -4, v90
	v_readlane_b32 s18, v254, 63
	v_readlane_b32 s19, v255, 0
	s_and_b64 s[18:19], s[18:19], exec
	s_cselect_b32 s18, s13, s9
	s_cselect_b32 s19, s12, s8
	v_readlane_b32 s8, v255, 1
	v_readlane_b32 s72, v253, 10
	v_readlane_b32 s9, v255, 2
	v_readlane_b32 s84, v253, 22
	v_readlane_b32 s85, v253, 23
	s_and_b64 s[8:9], s[8:9], exec
	s_mov_b64 s[20:21], s[84:85]
	s_cselect_b32 s8, s20, s10
	v_readlane_b32 s10, v254, 58
	s_cselect_b32 s9, s21, s11
	s_lshl_b32 s10, s10, 12
	v_lshlrev_b32_e32 v0, 2, v0
	s_add_u32 s8, s8, s10
	v_and_b32_e32 v92, 0xfc, v0
	s_addc_u32 s9, s9, 0
	v_lshlrev_b32_e32 v0, 2, v92
	global_load_dwordx4 v[2:5], v0, s[8:9]
	global_load_dwordx4 v[6:9], v0, s[8:9] offset:1024
	global_load_dwordx4 v[10:13], v0, s[8:9] offset:2048
	global_load_dwordx4 v[14:17], v0, s[8:9] offset:3072
	v_xor_b32_e32 v18, 1, v189
	v_cmp_lt_i32_e32 vcc, v18, v215
	v_cndmask_b32_e64 v100, 0.5, 1.0, s[6:7]
	s_add_u32 s6, s0, 0x1000000
	v_cndmask_b32_e32 v18, v189, v18, vcc
	v_lshlrev_b32_e32 v93, 2, v18
	v_xor_b32_e32 v18, 2, v189
	v_cmp_lt_i32_e32 vcc, v18, v215
	v_readlane_b32 s8, v254, 57
	s_addc_u32 s7, s1, 0
	v_cndmask_b32_e32 v18, v189, v18, vcc
	v_cmp_lt_i32_e32 vcc, v252, v215
	v_lshlrev_b32_e32 v95, 2, v18
	s_mulk_i32 s8, 0x3000
	v_cndmask_b32_e32 v18, v189, v252, vcc
	v_cmp_lt_i32_e32 vcc, v225, v215
	v_lshlrev_b32_e32 v97, 2, v18
	s_add_u32 s8, s16, s8
	v_cndmask_b32_e32 v18, v189, v225, vcc
	v_cmp_lt_i32_e32 vcc, v231, v215
	v_lshlrev_b32_e32 v99, 2, v18
	s_addc_u32 s9, s17, 0
	v_cndmask_b32_e32 v18, v189, v231, vcc
	v_cmp_lt_i32_e32 vcc, v233, v215
	v_lshlrev_b32_e32 v152, 2, v18
	v_mov_b32_e32 v19, v1
	v_cndmask_b32_e32 v18, v189, v233, vcc
	v_lshlrev_b32_e32 v153, 2, v18
	v_lshlrev_b32_e32 v18, 1, v92
	v_or_b32_e32 v94, 0x100, v92
	v_or_b32_e32 v96, 0x200, v92
	v_or_b32_e32 v98, 0x300, v92
	s_cmp_lg_u64 s[14:15], 0
	v_lshl_add_u64 v[104:105], s[14:15], 0, v[0:1]
	v_lshl_add_u64 v[106:107], s[6:7], 0, v[18:19]
	v_lshl_add_u64 v[18:19], s[0:1], 0, v[0:1]
	s_mov_b64 s[14:15], 0x21f20000
	s_mov_b64 s[10:11], 0
	s_cselect_b64 s[12:13], -1, 0
	v_mov_b32_e32 v102, v100
	v_mov_b32_e32 v103, v100
	v_lshl_add_u64 v[108:109], v[18:19], 0, s[14:15]
	v_lshlrev_b32_e32 v110, 2, v94
	v_lshlrev_b32_e32 v112, 2, v96
	v_lshlrev_b32_e32 v114, 2, v98
	v_readlane_b32 s73, v253, 11
	v_readlane_b32 s74, v253, 12
	v_readlane_b32 s75, v253, 13
	v_readlane_b32 s76, v253, 14
	v_readlane_b32 s77, v253, 15
	v_readlane_b32 s78, v253, 16
	v_readlane_b32 s79, v253, 17
	v_readlane_b32 s80, v253, 18
	v_readlane_b32 s81, v253, 19
	v_readlane_b32 s82, v253, 20
	v_readlane_b32 s83, v253, 21
	v_readlane_b32 s86, v253, 24
	v_readlane_b32 s87, v253, 25
	s_branch .LBB0_333
.LBB0_332:
	s_or_b64 exec, exec, s[16:17]
	v_min_i32_e32 v0, 0x8000, v90
	v_ashrrev_i32_e32 v0, 11, v0
	v_mul_hi_i32_i24_e32 v85, 0x9000, v0
	v_mul_i32_i24_e32 v84, 0x9000, v0
	s_waitcnt vmcnt(0)
	v_mov_b32_e32 v86, v79
	s_waitcnt vmcnt(14)
	v_mov_b32_e32 v87, v55
	v_lshl_add_u64 v[128:129], s[8:9], 0, v[84:85]
	v_mov_b32_e32 v84, v78
	v_mov_b32_e32 v85, v54
	v_pk_mul_f32 v[86:87], v[86:87], v[86:87]
	s_waitcnt vmcnt(13)
	v_mov_b32_e32 v88, v35
	v_pk_fma_f32 v[84:85], v[84:85], v[84:85], v[86:87]
	v_mov_b32_e32 v86, v80
	v_mov_b32_e32 v87, v56
	v_pk_fma_f32 v[84:85], v[86:87], v[86:87], v[84:85]
	v_mov_b32_e32 v86, v81
	v_mov_b32_e32 v87, v57
	s_waitcnt vmcnt(12)
	v_mov_b32_e32 v89, v19
	v_pk_fma_f32 v[84:85], v[86:87], v[86:87], v[84:85]
	v_mov_b32_e32 v86, v34
	v_mov_b32_e32 v87, v18
	v_pk_mul_f32 v[88:89], v[88:89], v[88:89]
	v_lshl_add_u64 v[124:125], v[128:129], 0, s[46:47]
	v_pk_fma_f32 v[86:87], v[86:87], v[86:87], v[88:89]
	v_mov_b32_e32 v88, v36
	v_mov_b32_e32 v89, v20
	v_pk_fma_f32 v[86:87], v[88:89], v[88:89], v[86:87]
	v_mov_b32_e32 v88, v37
	v_mov_b32_e32 v89, v21
	v_pk_fma_f32 v[132:133], v[88:89], v[88:89], v[86:87]
	s_waitcnt vmcnt(11)
	v_mov_b32_e32 v88, v75
	s_waitcnt vmcnt(10)
	v_mov_b32_e32 v89, v51
	v_mov_b32_e32 v86, v74
	v_mov_b32_e32 v87, v50
	v_pk_mul_f32 v[88:89], v[88:89], v[88:89]
	s_waitcnt vmcnt(9)
; #define GAS __attribute__((address_space(1)))
; DI void phase_norm(const Params& p, const int tid, const float* hlat, const float* g, const float* modl, int sidx, int nrows, const float* pgate  , float pcoef) {
;     ...
;       for (int i = 0; i < 4; ++i) xv[j][i] = *(const GAS f32x4*)(hp + (size_t)j * D + (i * 64 + lane) * 4);
;     if (addp) {
;       f32x4 pg[4], pc[4][4];
; #pragma unroll
;       for (int i = 0; i < 4; ++i) pg[i] = *(const GAS f32x4*)(pgate + (i * 64 + lane) * 4) * pcoef;
; #pragma unroll
;       for (int j = 0; j < 4; ++j)
; #pragma unroll
;         for (int i = 0; i < 4; ++i) pc[j][i] = *(const GAS f32x4*)(pctx + (size_t)(row0 + j - TL) * D + (i * 64 + lane) * 4);
; #pragma unroll
;       for (int j = 0; j < 4; ++j)
; #pragma unroll
;         for (int i = 0; i < 4; ++i) { xv[j][i] = xv[j][i] + pg[i] * pc[j][i]; *(GAS f32x4*)(hp + (size_t)j * D + (i * 64 + lane) * 4) = xv[j][i]; }
;     }
; #pragma unroll
;     for (int j = 0; j < 4; ++j) { float t = 0.f;
; #pragma unroll
;       for (int i = 0; i < 4; ++i) t += xv[j][i][0] * xv[j][i][0] + xv[j][i][1] * xv[j][i][1] + xv[j][i][2] * xv[j][i][2] + xv[j][i][3] * xv[j][i][3];
;       ss[j] = t; }
; #pragma unroll
;     for (int o = 1; o < 64; o <<= 1) {
; #pragma unroll
;       for (int j = 0; j < 4; ++j) ss[j] += __shfl_xor(ss[j], o); }
;     f32x4 gsv[4], s0v[4];
; #pragma unroll
;     for (int i = 0; i < 4; ++i) { const int col = (i * 64 + lane) * 4; gsv[i] = gv[i] * (*(const GAS f32x4*)(scp + col) + 1.f); s0v[i] = *(const GAS f32x4*)(sh + col); }
	v_mov_b32_e32 v118, v39
	v_pk_fma_f32 v[86:87], v[86:87], v[86:87], v[88:89]
	v_mov_b32_e32 v88, v76
	v_mov_b32_e32 v89, v52
	v_pk_fma_f32 v[86:87], v[88:89], v[88:89], v[86:87]
	v_mov_b32_e32 v88, v77
	v_mov_b32_e32 v89, v53
	v_pk_fma_f32 v[134:135], v[88:89], v[88:89], v[86:87]
	v_lshl_add_u64 v[86:87], v[124:125], 0, v[82:83]
	global_load_dwordx4 v[86:89], v[86:87], off
	s_waitcnt vmcnt(9)
	v_mov_b32_e32 v119, v23
	v_mov_b32_e32 v116, v38
	v_mov_b32_e32 v117, v22
	v_pk_mul_f32 v[118:119], v[118:119], v[118:119]
	v_mov_b32_e32 v122, v41
	v_pk_fma_f32 v[116:117], v[116:117], v[116:117], v[118:119]
	v_mov_b32_e32 v118, v40
	v_mov_b32_e32 v119, v24
	v_pk_fma_f32 v[120:121], v[118:119], v[118:119], v[116:117]
	v_lshl_add_u64 v[116:117], v[124:125], 0, v[110:111]
	v_mov_b32_e32 v123, v25
	global_load_dwordx4 v[116:119], v[116:117], off
	v_pk_fma_f32 v[136:137], v[122:123], v[122:123], v[120:121]
	v_lshl_add_u64 v[120:121], v[124:125], 0, v[112:113]
	global_load_dwordx4 v[120:123], v[120:121], off
	s_waitcnt vmcnt(10)
	v_mov_b32_e32 v130, v71
	s_waitcnt vmcnt(9)
	v_mov_b32_e32 v131, v59
	v_mov_b32_e32 v126, v70
	v_mov_b32_e32 v127, v58
	v_pk_mul_f32 v[130:131], v[130:131], v[130:131]
	v_lshl_add_u64 v[124:125], v[124:125], 0, v[114:115]
	v_pk_fma_f32 v[126:127], v[126:127], v[126:127], v[130:131]
	v_mov_b32_e32 v130, v72
	v_mov_b32_e32 v131, v60
	v_pk_fma_f32 v[130:131], v[130:131], v[130:131], v[126:127]
	global_load_dwordx4 v[124:127], v[124:125], off
	v_mov_b32_e32 v138, v73
	v_mov_b32_e32 v139, v61
	s_waitcnt vmcnt(9)
	v_mov_b32_e32 v140, v43
	s_waitcnt vmcnt(8)
	v_mov_b32_e32 v141, v27
	v_pk_fma_f32 v[138:139], v[138:139], v[138:139], v[130:131]
	v_mov_b32_e32 v130, v42
	v_mov_b32_e32 v131, v26
	v_pk_mul_f32 v[140:141], v[140:141], v[140:141]
	s_waitcnt vmcnt(7)
	v_mov_b32_e32 v142, v67
	v_pk_fma_f32 v[130:131], v[130:131], v[130:131], v[140:141]
	v_mov_b32_e32 v140, v44
	v_mov_b32_e32 v141, v28
	v_pk_fma_f32 v[130:131], v[140:141], v[140:141], v[130:131]
	v_mov_b32_e32 v140, v45
	v_mov_b32_e32 v141, v29
	s_waitcnt vmcnt(6)
	v_mov_b32_e32 v143, v63
	v_pk_fma_f32 v[140:141], v[140:141], v[140:141], v[130:131]
	v_mov_b32_e32 v130, v66
	v_mov_b32_e32 v131, v62
	v_pk_mul_f32 v[142:143], v[142:143], v[142:143]
	s_waitcnt vmcnt(5)
	v_mov_b32_e32 v144, v47
	v_pk_fma_f32 v[130:131], v[130:131], v[130:131], v[142:143]
	v_mov_b32_e32 v142, v68
	v_mov_b32_e32 v143, v64
	v_pk_fma_f32 v[130:131], v[142:143], v[142:143], v[130:131]
	v_mov_b32_e32 v142, v69
	v_mov_b32_e32 v143, v65
	s_waitcnt vmcnt(4)
	v_mov_b32_e32 v145, v31
	v_pk_fma_f32 v[142:143], v[142:143], v[142:143], v[130:131]
	v_mov_b32_e32 v130, v46
	v_mov_b32_e32 v131, v30
	v_pk_mul_f32 v[144:145], v[144:145], v[144:145]
	v_lshl_add_u64 v[146:147], v[128:129], 0, v[82:83]
	v_pk_fma_f32 v[144:145], v[130:131], v[130:131], v[144:145]
	global_load_dwordx4 v[128:131], v[146:147], off
	v_mov_b32_e32 v82, v48
	v_mov_b32_e32 v83, v32
	v_pk_fma_f32 v[82:83], v[82:83], v[82:83], v[144:145]
	v_mov_b32_e32 v144, v134
	v_mov_b32_e32 v145, v84
	v_mov_b32_e32 v84, v135
	v_pk_add_f32 v[84:85], v[144:145], v[84:85]
	v_mov_b32_e32 v134, v136
	v_mov_b32_e32 v135, v132
	v_pk_add_f32 v[84:85], v[84:85], v[134:135]
	v_mov_b32_e32 v132, v137
	v_pk_add_f32 v[84:85], v[84:85], v[132:133]
	ds_bpermute_b32 v133, v93, v85
	ds_bpermute_b32 v132, v93, v84
	v_mov_b32_e32 v134, v49
	v_mov_b32_e32 v135, v33
	v_pk_fma_f32 v[136:137], v[134:135], v[134:135], v[82:83]
	v_mov_b32_e32 v164, v142
	s_waitcnt vmcnt(4)
	v_pk_add_f32 v[82:83], v[88:89], 1.0 op_sel_hi:[1,0]
	s_waitcnt lgkmcnt(0)
	v_pk_add_f32 v[88:89], v[84:85], v[132:133]
	ds_bpermute_b32 v133, v95, v89
	ds_bpermute_b32 v132, v95, v88
	v_pk_add_f32 v[84:85], v[86:87], 1.0 op_sel_hi:[1,0]
	v_pk_mul_f32 v[144:145], v[4:5], v[82:83]
	v_pk_mul_f32 v[148:149], v[2:3], v[84:85]
	global_load_dwordx4 v[82:85], v[146:147], off offset:3072
	s_waitcnt lgkmcnt(0)
	v_pk_add_f32 v[86:87], v[88:89], v[132:133]
	ds_bpermute_b32 v89, v97, v87
	ds_bpermute_b32 v88, v97, v86
	v_mov_b32_e32 v165, v138
	s_waitcnt vmcnt(4)
	v_pk_add_f32 v[118:119], v[118:119], 1.0 op_sel_hi:[1,0]
	v_pk_add_f32 v[116:117], v[116:117], 1.0 op_sel_hi:[1,0]
	v_pk_mul_f32 v[150:151], v[8:9], v[118:119]
	s_waitcnt lgkmcnt(0)
	v_pk_add_f32 v[86:87], v[86:87], v[88:89]
	ds_bpermute_b32 v89, v99, v87
	ds_bpermute_b32 v88, v99, v86
	s_waitcnt vmcnt(3)
	v_pk_add_f32 v[118:119], v[120:121], 1.0 op_sel_hi:[1,0]
	v_pk_mul_f32 v[154:155], v[6:7], v[116:117]
	v_pk_add_f32 v[116:117], v[122:123], 1.0 op_sel_hi:[1,0]
	v_pk_mul_f32 v[122:123], v[10:11], v[118:119]
	s_waitcnt lgkmcnt(0)
	v_pk_add_f32 v[118:119], v[86:87], v[88:89]
	global_load_dwordx4 v[132:135], v[146:147], off offset:1024
	global_load_dwordx4 v[86:89], v[146:147], off offset:2048
	ds_bpermute_b32 v157, v152, v119
	ds_bpermute_b32 v156, v152, v118
	v_pk_mul_f32 v[120:121], v[12:13], v[116:117]
	s_waitcnt vmcnt(4)
	v_pk_add_f32 v[116:117], v[126:127], 1.0 op_sel_hi:[1,0]
	v_mov_b32_e32 v138, v143
	v_pk_add_f32 v[138:139], v[164:165], v[138:139]
	s_waitcnt lgkmcnt(0)
	v_pk_add_f32 v[126:127], v[118:119], v[156:157]
	ds_bpermute_b32 v147, v153, v127
	ds_bpermute_b32 v146, v153, v126
	v_mov_b32_e32 v142, v136
	v_mov_b32_e32 v143, v140
	v_pk_add_f32 v[138:139], v[138:139], v[142:143]
	v_mov_b32_e32 v140, v137
	v_pk_add_f32 v[136:137], v[138:139], v[140:141]
	s_mov_b32 s14, 0x358637bd
	ds_bpermute_b32 v139, v93, v137
	ds_bpermute_b32 v138, v93, v136
	s_waitcnt lgkmcnt(2)
	v_pk_add_f32 v[126:127], v[126:127], v[146:147]
	v_mov_b64_e32 v[146:147], s[14:15]
	s_mov_b32 s14, 0x3a800000
	v_pk_fma_f32 v[126:127], v[126:127], s[14:15], v[146:147] op_sel_hi:[1,0,0]
	s_waitcnt lgkmcnt(0)
; #define GAS __attribute__((address_space(1)))
; DI void st4(bf16_t* p, f32x4 v) { u32x2 o = {pk(v[0], v[1]), pk(v[2], v[3])}; *(GAS u32x2*)p = o; }
; DI void phase_norm(const Params& p, const int tid, const float* hlat, const float* g, const float* modl, int sidx, int nrows, const float* pgate  , float pcoef) {
;     ...
;     for (int j = 0; j < 4; ++j) { float t = 0.f;
; #pragma unroll
;       for (int i = 0; i < 4; ++i) t += xv[j][i][0] * xv[j][i][0] + xv[j][i][1] * xv[j][i][1] + xv[j][i][2] * xv[j][i][2] + xv[j][i][3] * xv[j][i][3];
;       ss[j] = t; }
; #pragma unroll
;     for (int o = 1; o < 64; o <<= 1) {
; #pragma unroll
;       for (int j = 0; j < 4; ++j) ss[j] += __shfl_xor(ss[j], o); }
;     f32x4 gsv[4], s0v[4];
; #pragma unroll
;     for (int i = 0; i < 4; ++i) { const int col = (i * 64 + lane) * 4; gsv[i] = gv[i] * (*(const GAS f32x4*)(scp + col) + 1.f); s0v[i] = *(const GAS f32x4*)(sh + col); }
; #pragma unroll
;     for (int i = 0; i < 4; ++i) { const int col = (i * 64 + lane) * 4;
; #pragma unroll
;       for (int j = 0; j < 4; ++j) st4(XN + (size_t)(row0 + j) * D + col, xv[j][i] * rsqrtf(ss[j] * (1.f / 1024.f) + EPS) * gsv[i] + s0v[i]); }
	v_pk_add_f32 v[136:137], v[136:137], v[138:139]
	v_mul_f32_e32 v0, 0x4b800000, v127
	v_cmp_gt_f32_e32 vcc, s45, v127
	ds_bpermute_b32 v139, v95, v137
	ds_bpermute_b32 v138, v95, v136
	v_cndmask_b32_e32 v0, v127, v0, vcc
	v_rsq_f32_e32 v0, v0
	v_pk_add_f32 v[124:125], v[124:125], 1.0 op_sel_hi:[1,0]
	v_add_u32_e32 v158, 1, v90
	v_pk_mul_f32 v[118:119], v[14:15], v[124:125]
	v_lshlrev_b64 v[124:125], 11, v[90:91]
	v_mul_f32_e32 v91, 0x45800000, v0
	v_cndmask_b32_e32 v162, v0, v91, vcc
	v_mul_f32_e32 v0, 0x4b800000, v126
	v_cmp_gt_f32_e32 vcc, s45, v126
	v_pk_mul_f32 v[78:79], v[78:79], v[162:163] op_sel_hi:[1,0]
	v_pk_mul_f32 v[80:81], v[80:81], v[162:163] op_sel_hi:[1,0]
	v_cndmask_b32_e32 v0, v126, v0, vcc
	s_waitcnt lgkmcnt(0)
	v_pk_add_f32 v[126:127], v[136:137], v[138:139]
	ds_bpermute_b32 v137, v97, v127
	ds_bpermute_b32 v136, v97, v126
	s_waitcnt vmcnt(3)
	v_pk_fma_f32 v[80:81], v[144:145], v[80:81], v[130:131]
	v_pk_fma_f32 v[78:79], v[148:149], v[78:79], v[128:129]
	v_rsq_f32_e32 v0, v0
	v_cvt_pk_bf16_f32 v78, v78, v79
	v_cvt_pk_bf16_f32 v79, v80, v81
	s_waitcnt lgkmcnt(0)
	v_pk_add_f32 v[80:81], v[126:127], v[136:137]
	ds_bpermute_b32 v127, v99, v81
	ds_bpermute_b32 v126, v99, v80
	v_lshl_add_u64 v[156:157], v[106:107], 0, v[124:125]
	global_store_dwordx2 v[156:157], v[78:79], off
	v_mul_f32_e32 v78, 0x45800000, v0
	v_cndmask_b32_e32 v78, v0, v78, vcc
	s_waitcnt lgkmcnt(0)
	v_pk_add_f32 v[80:81], v[80:81], v[126:127]
	ds_bpermute_b32 v127, v152, v81
	ds_bpermute_b32 v126, v152, v80
	v_pk_mul_f32 v[74:75], v[74:75], v[78:79] op_sel_hi:[1,0]
	v_pk_mul_f32 v[76:77], v[76:77], v[78:79] op_sel_hi:[1,0]
	v_pk_fma_f32 v[74:75], v[148:149], v[74:75], v[128:129]
	v_pk_fma_f32 v[76:77], v[144:145], v[76:77], v[130:131]
	v_cvt_pk_bf16_f32 v74, v74, v75
	v_cvt_pk_bf16_f32 v75, v76, v77
	s_waitcnt lgkmcnt(0)
	v_pk_add_f32 v[76:77], v[80:81], v[126:127]
	ds_bpermute_b32 v81, v153, v77
	ds_bpermute_b32 v80, v153, v76
	v_ashrrev_i32_e32 v159, 31, v158
	v_lshlrev_b64 v[158:159], 11, v[158:159]
	v_lshl_add_u64 v[160:161], v[106:107], 0, v[158:159]
	global_store_dwordx2 v[160:161], v[74:75], off
	s_waitcnt lgkmcnt(0)
	v_pk_add_f32 v[76:77], v[76:77], v[80:81]
	v_add_u32_e32 v74, 2, v90
	v_pk_fma_f32 v[76:77], v[76:77], s[14:15], v[146:147] op_sel_hi:[1,0,0]
	v_ashrrev_i32_e32 v75, 31, v74
	v_mul_f32_e32 v0, 0x4b800000, v77
	v_cmp_gt_f32_e32 vcc, s45, v77
	v_lshlrev_b64 v[74:75], 11, v[74:75]
	v_lshl_add_u64 v[126:127], v[106:107], 0, v[74:75]
	v_cndmask_b32_e32 v0, v77, v0, vcc
	v_rsq_f32_e32 v0, v0
	v_add_u32_e32 v136, 3, v90
	v_ashrrev_i32_e32 v137, 31, v136
	v_lshlrev_b64 v[80:81], 11, v[136:137]
	v_mul_f32_e32 v77, 0x45800000, v0
	v_cndmask_b32_e32 v138, v0, v77, vcc
	v_mul_f32_e32 v0, 0x4b800000, v76
	v_cmp_gt_f32_e32 vcc, s45, v76
	v_pk_mul_f32 v[70:71], v[70:71], v[138:139] op_sel_hi:[1,0]
	v_pk_mul_f32 v[72:73], v[72:73], v[138:139] op_sel_hi:[1,0]
	v_cndmask_b32_e32 v0, v76, v0, vcc
	v_rsq_f32_e32 v0, v0
	v_pk_fma_f32 v[72:73], v[144:145], v[72:73], v[130:131]
	v_pk_fma_f32 v[70:71], v[148:149], v[70:71], v[128:129]
	v_lshl_add_u64 v[136:137], v[106:107], 0, v[80:81]
	v_cvt_pk_bf16_f32 v70, v70, v71
	v_cvt_pk_bf16_f32 v71, v72, v73
	global_store_dwordx2 v[126:127], v[70:71], off
	v_mul_f32_e32 v70, 0x45800000, v0
	v_cndmask_b32_e32 v70, v0, v70, vcc
	v_pk_mul_f32 v[66:67], v[66:67], v[70:71] op_sel_hi:[1,0]
	v_pk_mul_f32 v[68:69], v[68:69], v[70:71] op_sel_hi:[1,0]
	v_pk_fma_f32 v[66:67], v[148:149], v[66:67], v[128:129]
	v_pk_fma_f32 v[68:69], v[144:145], v[68:69], v[130:131]
	v_cvt_pk_bf16_f32 v66, v66, v67
	v_cvt_pk_bf16_f32 v67, v68, v69
	v_pk_mul_f32 v[54:55], v[54:55], v[162:163] op_sel_hi:[1,0]
	v_pk_mul_f32 v[56:57], v[56:57], v[162:163] op_sel_hi:[1,0]
	global_store_dwordx2 v[136:137], v[66:67], off
	v_lshl_add_u64 v[66:67], s[6:7], 0, v[124:125]
	v_lshlrev_b32_e32 v0, 1, v94
	s_waitcnt vmcnt(5)
; DI void st4(bf16_t* p, f32x4 v) { u32x2 o = {pk(v[0], v[1]), pk(v[2], v[3])}; *(GAS u32x2*)p = o; }
; DI void phase_norm(const Params& p, const int tid, const float* hlat, const float* g, const float* modl, int sidx, int nrows, const float* pgate  , float pcoef) {
;     ...
;   for (int row0 = (blockIdx.x * 8 + w) * 4; row0 < nrows; row0 += gridDim.x * 32) {
;     ...
;     for (int i = 0; i < 4; ++i) { const int col = (i * 64 + lane) * 4;
; #pragma unroll
;       for (int j = 0; j < 4; ++j) st4(XN + (size_t)(row0 + j) * D + col, xv[j][i] * rsqrtf(ss[j] * (1.f / 1024.f) + EPS) * gsv[i] + s0v[i]); }
;   }
	v_pk_fma_f32 v[56:57], v[150:151], v[56:57], v[134:135]
	v_pk_fma_f32 v[54:55], v[154:155], v[54:55], v[132:133]
	v_lshl_add_u64 v[68:69], v[66:67], 0, v[0:1]
	v_cvt_pk_bf16_f32 v54, v54, v55
	v_cvt_pk_bf16_f32 v55, v56, v57
	v_pk_mul_f32 v[50:51], v[50:51], v[78:79] op_sel_hi:[1,0]
	v_pk_mul_f32 v[52:53], v[52:53], v[78:79] op_sel_hi:[1,0]
	global_store_dwordx2 v[68:69], v[54:55], off
	v_lshl_add_u64 v[54:55], s[6:7], 0, v[158:159]
	v_pk_fma_f32 v[52:53], v[150:151], v[52:53], v[134:135]
	v_pk_fma_f32 v[50:51], v[154:155], v[50:51], v[132:133]
	v_lshl_add_u64 v[56:57], v[54:55], 0, v[0:1]
	v_cvt_pk_bf16_f32 v50, v50, v51
	v_cvt_pk_bf16_f32 v51, v52, v53
	global_store_dwordx2 v[56:57], v[50:51], off
	v_pk_mul_f32 v[56:57], v[58:59], v[138:139] op_sel_hi:[1,0]
	v_pk_mul_f32 v[58:59], v[60:61], v[138:139] op_sel_hi:[1,0]
	v_lshl_add_u64 v[50:51], s[6:7], 0, v[74:75]
	v_pk_fma_f32 v[58:59], v[150:151], v[58:59], v[134:135]
	v_pk_fma_f32 v[56:57], v[154:155], v[56:57], v[132:133]
	v_lshl_add_u64 v[52:53], v[50:51], 0, v[0:1]
	v_cvt_pk_bf16_f32 v56, v56, v57
	v_cvt_pk_bf16_f32 v57, v58, v59
	v_pk_mul_f32 v[58:59], v[62:63], v[70:71] op_sel_hi:[1,0]
	v_pk_mul_f32 v[60:61], v[64:65], v[70:71] op_sel_hi:[1,0]
	v_pk_mul_f32 v[34:35], v[34:35], v[162:163] op_sel_hi:[1,0]
	v_pk_mul_f32 v[36:37], v[36:37], v[162:163] op_sel_hi:[1,0]
	global_store_dwordx2 v[52:53], v[56:57], off
	v_lshl_add_u64 v[52:53], s[6:7], 0, v[80:81]
	v_pk_fma_f32 v[60:61], v[150:151], v[60:61], v[134:135]
	v_pk_fma_f32 v[58:59], v[154:155], v[58:59], v[132:133]
	s_waitcnt vmcnt(7)
	v_pk_fma_f32 v[36:37], v[120:121], v[36:37], v[88:89]
	v_pk_fma_f32 v[34:35], v[122:123], v[34:35], v[86:87]
	v_lshl_add_u64 v[56:57], v[52:53], 0, v[0:1]
	v_cvt_pk_bf16_f32 v58, v58, v59
	v_cvt_pk_bf16_f32 v59, v60, v61
	v_lshlrev_b32_e32 v0, 1, v96
	v_cvt_pk_bf16_f32 v34, v34, v35
	v_cvt_pk_bf16_f32 v35, v36, v37
	v_pk_mul_f32 v[36:37], v[38:39], v[78:79] op_sel_hi:[1,0]
	v_pk_mul_f32 v[38:39], v[40:41], v[78:79] op_sel_hi:[1,0]
	global_store_dwordx2 v[56:57], v[58:59], off
	v_lshl_add_u64 v[56:57], v[66:67], 0, v[0:1]
	v_pk_fma_f32 v[38:39], v[120:121], v[38:39], v[88:89]
	v_pk_fma_f32 v[36:37], v[122:123], v[36:37], v[86:87]
	global_store_dwordx2 v[56:57], v[34:35], off
	v_lshl_add_u64 v[34:35], v[54:55], 0, v[0:1]
	v_cvt_pk_bf16_f32 v36, v36, v37
	v_cvt_pk_bf16_f32 v37, v38, v39
	global_store_dwordx2 v[34:35], v[36:37], off
	v_pk_mul_f32 v[36:37], v[42:43], v[138:139] op_sel_hi:[1,0]
	v_pk_mul_f32 v[38:39], v[44:45], v[138:139] op_sel_hi:[1,0]
	v_pk_fma_f32 v[36:37], v[122:123], v[36:37], v[86:87]
	v_pk_fma_f32 v[38:39], v[120:121], v[38:39], v[88:89]
	v_lshl_add_u64 v[34:35], v[50:51], 0, v[0:1]
	v_cvt_pk_bf16_f32 v36, v36, v37
	v_cvt_pk_bf16_f32 v37, v38, v39
	v_pk_mul_f32 v[116:117], v[16:17], v[116:117]
	global_store_dwordx2 v[34:35], v[36:37], off
	v_pk_mul_f32 v[36:37], v[46:47], v[70:71] op_sel_hi:[1,0]
	v_pk_mul_f32 v[38:39], v[48:49], v[70:71] op_sel_hi:[1,0]
	v_pk_mul_f32 v[18:19], v[18:19], v[162:163] op_sel_hi:[1,0]
	v_pk_mul_f32 v[20:21], v[20:21], v[162:163] op_sel_hi:[1,0]
	v_pk_fma_f32 v[38:39], v[120:121], v[38:39], v[88:89]
	v_pk_fma_f32 v[36:37], v[122:123], v[36:37], v[86:87]
	v_pk_fma_f32 v[20:21], v[116:117], v[20:21], v[84:85]
	v_pk_fma_f32 v[18:19], v[118:119], v[18:19], v[82:83]
	v_lshl_add_u64 v[34:35], v[52:53], 0, v[0:1]
	v_cvt_pk_bf16_f32 v36, v36, v37
	v_cvt_pk_bf16_f32 v37, v38, v39
	v_lshlrev_b32_e32 v0, 1, v98
	v_cvt_pk_bf16_f32 v18, v18, v19
	v_cvt_pk_bf16_f32 v19, v20, v21
	v_pk_mul_f32 v[20:21], v[22:23], v[78:79] op_sel_hi:[1,0]
	v_pk_mul_f32 v[22:23], v[24:25], v[78:79] op_sel_hi:[1,0]
	global_store_dwordx2 v[34:35], v[36:37], off
	v_lshl_add_u64 v[34:35], v[66:67], 0, v[0:1]
	v_pk_fma_f32 v[22:23], v[116:117], v[22:23], v[84:85]
	v_pk_fma_f32 v[20:21], v[118:119], v[20:21], v[82:83]
	global_store_dwordx2 v[34:35], v[18:19], off
	v_lshl_add_u64 v[18:19], v[54:55], 0, v[0:1]
	v_cvt_pk_bf16_f32 v20, v20, v21
	v_cvt_pk_bf16_f32 v21, v22, v23
	global_store_dwordx2 v[18:19], v[20:21], off
	v_pk_mul_f32 v[20:21], v[26:27], v[138:139] op_sel_hi:[1,0]
	v_pk_mul_f32 v[22:23], v[28:29], v[138:139] op_sel_hi:[1,0]
	v_pk_fma_f32 v[20:21], v[118:119], v[20:21], v[82:83]
	v_pk_fma_f32 v[22:23], v[116:117], v[22:23], v[84:85]
	v_lshl_add_u64 v[18:19], v[50:51], 0, v[0:1]
	v_cvt_pk_bf16_f32 v20, v20, v21
	v_cvt_pk_bf16_f32 v21, v22, v23
	global_store_dwordx2 v[18:19], v[20:21], off
	v_pk_mul_f32 v[20:21], v[30:31], v[70:71] op_sel_hi:[1,0]
	v_pk_mul_f32 v[22:23], v[32:33], v[70:71] op_sel_hi:[1,0]
	v_subrev_u32_e32 v90, s91, v90
	v_pk_fma_f32 v[22:23], v[116:117], v[22:23], v[84:85]
	v_pk_fma_f32 v[20:21], v[118:119], v[20:21], v[82:83]
	v_cmp_gt_i32_e32 vcc, 0, v90
	v_lshl_add_u64 v[18:19], v[52:53], 0, v[0:1]
	v_cvt_pk_bf16_f32 v20, v20, v21
	v_cvt_pk_bf16_f32 v21, v22, v23
	s_or_b64 s[10:11], vcc, s[10:11]
	global_store_dwordx2 v[18:19], v[20:21], off
	s_andn2_b64 exec, exec, s[10:11]
	s_cbranch_execz .LBB0_335

; #define PG8_STAGE(bufoff, gbase, voff) do { _Pragma("unroll") for (int _i = 0; _i < 2; ++_i) \
;     __builtin_amdgcn_global_load_lds((const unsigned*)((const char*)(gbase) + (voff)[_i]), (LAS unsigned*)(lds + (bufoff) + ldsw + _i * 8192), 16, 0, 0); } while (0)
; #define PG8_LDA(dst, b, h) do { _Pragma("unroll") for (int m = 0; m < 4; ++m) _Pragma("unroll") for (int k = 0; k < 2; ++k) dst[m][k] = *(const LAS bf16x8*)(lds + PG8_SA(b, h) + aoff + m * 2048 + k * 1024); } while (0)
; #define PG8_LDB(dst, b, h) do { _Pragma("unroll") for (int n = 0; n < 2; ++n) _Pragma("unroll") for (int k = 0; k < 2; ++k) dst[n][k] = *(const LAS bf16x8*)(lds + PG8_SB(b, h) + boff + n * 2048 + k * 1024); } while (0)
; #define PG8_MMA(ai, bj, At, Bt) do { __builtin_amdgcn_s_setprio(1); _Pragma("unroll") for (int m = 0; m < 4; ++m) _Pragma("unroll") for (int n = 0; n < 2; ++n) _Pragma("unroll") for (int k = 0; k < 2; ++k) \
;     acc[ai][bj][m][n] = __builtin_amdgcn_mfma_f32_16x16x32_bf16(Bt[n][k], At[m][k], acc[ai][bj][m][n], 0, 0, 0); __builtin_amdgcn_s_setprio(0); } while (0)
; #define PG8_WAIT_V(n) asm volatile("s_waitcnt vmcnt(" #n ")" ::: "memory")
; #define PG8_WAIT_L(n) asm volatile("s_waitcnt lgkmcnt(" #n ")" ::: "memory")
; #define PG8_BAR __builtin_amdgcn_s_barrier()
; #define PG8_SCHED __builtin_amdgcn_sched_barrier(0)
; template <class Epi, class Sched>
; DI void gemm_phase(LAS unsigned char* lds, const int tid, const Gemm g, const Sched& S, const Epi& E) {
;     ...
;       PG8_LDB(B0, 0, 0); PG8_SCHED; PG8_LDA(At, 0, 0); PG8_STAGE(PG8_SA(1, 1), a1 + hstepA, voffA);
;       PG8_WAIT_L(8); PG8_BAR; PG8_WAIT_L(0); PG8_MMA(0, 0, At, B0); PG8_BAR; PG8_SCHED;
;       PG8_LDB(B1, 0, 1); PG8_STAGE(PG8_SB(0, 0), b2, voffB);
;       PG8_BAR; PG8_WAIT_L(0); PG8_MMA(0, 1, At, B1); PG8_BAR;
;       PG8_LDA(At, 0, 1); PG8_STAGE(PG8_SA(0, 0), a2, voffA);
;       PG8_BAR; PG8_WAIT_L(0); PG8_MMA(1, 0, At, B0); PG8_BAR; PG8_SCHED;
;       PG8_STAGE(PG8_SB(0, 1), b2 + hstepB, voffB);
;       PG8_WAIT_V(6); PG8_BAR; PG8_MMA(1, 1, At, B1); PG8_BAR;
.LBB0_387:
	s_add_u32 s14, s16, 0xfffc0080
	s_addc_u32 s15, s17, -1
	s_add_i32 s46, 0, 0x10000
	v_add_u32_e32 v0, s46, v140
	ds_read_b128 v[142:145], v0
	ds_read_b128 v[146:149], v0 offset:1024
	ds_read_b128 v[150:153], v0 offset:2048
	ds_read_b128 v[154:157], v0 offset:3072
	s_cmp_eq_u32 s44, 12
	s_cselect_b32 s19, s7, s15
	s_cselect_b32 s18, s40, s14
	s_cselect_b32 s15, s1, s43
	s_cselect_b32 s14, s41, s42
	s_add_i32 m0, s27, 0xc000
	ds_read_b128 v[158:161], v141
	ds_read_b128 v[162:165], v141 offset:1024
	ds_read_b128 v[166:169], v141 offset:2048
	ds_read_b128 v[170:173], v141 offset:3072
	ds_read_b128 v[174:177], v141 offset:4096
	ds_read_b128 v[178:181], v141 offset:5120
	ds_read_b128 v[182:185], v141 offset:6144
	ds_read_b128 v[202:205], v141 offset:7168
	global_load_lds_dwordx4 v136, s[16:17]
	s_add_i32 m0, s27, 0xe000
	s_nop 0
	global_load_lds_dwordx4 v134, s[16:17]
	s_waitcnt lgkmcnt(8)
	s_barrier
	s_waitcnt lgkmcnt(0)
	s_setprio 1
	v_mfma_f32_16x16x32_bf16 v[126:129], v[142:145], v[158:161], v[126:129]
	v_mfma_f32_16x16x32_bf16 v[122:125], v[150:153], v[158:161], v[122:125]
	v_mfma_f32_16x16x32_bf16 v[110:113], v[142:145], v[166:169], v[110:113]
	v_mfma_f32_16x16x32_bf16 v[106:109], v[150:153], v[166:169], v[106:109]
	v_mfma_f32_16x16x32_bf16 v[94:97], v[142:145], v[174:177], v[94:97]
	v_mfma_f32_16x16x32_bf16 v[90:93], v[150:153], v[174:177], v[90:93]
	v_mfma_f32_16x16x32_bf16 v[78:81], v[142:145], v[182:185], v[78:81]
	v_mfma_f32_16x16x32_bf16 v[74:77], v[150:153], v[182:185], v[74:77]
	v_mfma_f32_16x16x32_bf16 v[126:129], v[146:149], v[162:165], v[126:129]
	v_mfma_f32_16x16x32_bf16 v[122:125], v[154:157], v[162:165], v[122:125]
	v_mfma_f32_16x16x32_bf16 v[110:113], v[146:149], v[170:173], v[110:113]
	v_mfma_f32_16x16x32_bf16 v[106:109], v[154:157], v[170:173], v[106:109]
	v_mfma_f32_16x16x32_bf16 v[94:97], v[146:149], v[178:181], v[94:97]
	v_mfma_f32_16x16x32_bf16 v[90:93], v[154:157], v[178:181], v[90:93]
	v_mfma_f32_16x16x32_bf16 v[78:81], v[146:149], v[202:205], v[78:81]
	v_mfma_f32_16x16x32_bf16 v[74:77], v[154:157], v[202:205], v[74:77]
	s_setprio 0
	s_barrier
	s_add_i32 s48, 0, 0x14000
	s_add_i32 s46, s46, s24
	v_add_u32_e32 v0, s48, v140
	s_add_u32 s98, s14, s50
	s_addc_u32 s99, s15, s51
	s_mov_b32 m0, s46
	ds_read_b128 v[206:209], v0
	ds_read_b128 v[210:213], v0 offset:1024
	ds_read_b128 v[226:229], v0 offset:2048
	ds_read_b128 v[238:241], v0 offset:3072
	global_load_lds_dwordx4 v132, s[14:15]
	s_add_i32 m0, s46, 0x2000
	s_nop 0
	global_load_lds_dwordx4 v130, s[14:15]
	s_barrier
	s_waitcnt lgkmcnt(0)
	s_setprio 1
	v_mfma_f32_16x16x32_bf16 v[118:121], v[206:209], v[158:161], v[118:121]
	v_mfma_f32_16x16x32_bf16 v[114:117], v[226:229], v[158:161], v[114:117]
	v_mfma_f32_16x16x32_bf16 v[102:105], v[206:209], v[166:169], v[102:105]
	v_mfma_f32_16x16x32_bf16 v[98:101], v[226:229], v[166:169], v[98:101]
	v_mfma_f32_16x16x32_bf16 v[86:89], v[206:209], v[174:177], v[86:89]
	v_mfma_f32_16x16x32_bf16 v[82:85], v[226:229], v[174:177], v[82:85]
	v_mfma_f32_16x16x32_bf16 v[70:73], v[206:209], v[182:185], v[70:73]
	v_mfma_f32_16x16x32_bf16 v[66:69], v[226:229], v[182:185], v[66:69]
	v_mfma_f32_16x16x32_bf16 v[118:121], v[210:213], v[162:165], v[118:121]
	v_mfma_f32_16x16x32_bf16 v[114:117], v[238:241], v[162:165], v[114:117]
	v_mfma_f32_16x16x32_bf16 v[102:105], v[210:213], v[170:173], v[102:105]
	v_mfma_f32_16x16x32_bf16 v[98:101], v[238:241], v[170:173], v[98:101]
	v_mfma_f32_16x16x32_bf16 v[86:89], v[210:213], v[178:181], v[86:89]
	v_mfma_f32_16x16x32_bf16 v[82:85], v[238:241], v[178:181], v[82:85]
	v_mfma_f32_16x16x32_bf16 v[70:73], v[210:213], v[202:205], v[70:73]
	v_mfma_f32_16x16x32_bf16 v[66:69], v[238:241], v[202:205], v[66:69]
	s_setprio 0
	s_mov_b32 m0, s27
	s_add_u32 s100, s18, s50
	s_addc_u32 s101, s19, s51
	s_barrier
	ds_read_b128 v[158:161], v141 offset:16384
	ds_read_b128 v[162:165], v141 offset:17408
	ds_read_b128 v[166:169], v141 offset:18432
	ds_read_b128 v[170:173], v141 offset:19456
	ds_read_b128 v[174:177], v141 offset:20480
	ds_read_b128 v[178:181], v141 offset:21504
	ds_read_b128 v[182:185], v141 offset:22528
	ds_read_b128 v[202:205], v141 offset:23552
	global_load_lds_dwordx4 v132, s[18:19]
	s_mov_b32 m0, s28
	s_nop 0
	global_load_lds_dwordx4 v130, s[18:19]
	s_barrier
	s_waitcnt lgkmcnt(0)
	s_setprio 1
	v_mfma_f32_16x16x32_bf16 v[62:65], v[142:145], v[158:161], v[62:65]
	v_mfma_f32_16x16x32_bf16 v[58:61], v[150:153], v[158:161], v[58:61]
	v_mfma_f32_16x16x32_bf16 v[46:49], v[142:145], v[166:169], v[46:49]
	v_mfma_f32_16x16x32_bf16 v[42:45], v[150:153], v[166:169], v[42:45]
	v_mfma_f32_16x16x32_bf16 v[30:33], v[142:145], v[174:177], v[30:33]
	v_mfma_f32_16x16x32_bf16 v[26:29], v[150:153], v[174:177], v[26:29]
	v_mfma_f32_16x16x32_bf16 v[14:17], v[142:145], v[182:185], v[14:17]
	v_mfma_f32_16x16x32_bf16 v[10:13], v[150:153], v[182:185], v[10:13]
	v_mfma_f32_16x16x32_bf16 v[62:65], v[146:149], v[162:165], v[62:65]
	v_mfma_f32_16x16x32_bf16 v[58:61], v[154:157], v[162:165], v[58:61]
	v_mfma_f32_16x16x32_bf16 v[46:49], v[146:149], v[170:173], v[46:49]
	v_mfma_f32_16x16x32_bf16 v[42:45], v[154:157], v[170:173], v[42:45]
	v_mfma_f32_16x16x32_bf16 v[30:33], v[146:149], v[178:181], v[30:33]
	v_mfma_f32_16x16x32_bf16 v[26:29], v[154:157], v[178:181], v[26:29]
	v_mfma_f32_16x16x32_bf16 v[14:17], v[146:149], v[202:205], v[14:17]
	v_mfma_f32_16x16x32_bf16 v[10:13], v[154:157], v[202:205], v[10:13]
	s_setprio 0
	s_barrier
	s_add_u32 s46, s14, 0x40000
	s_addc_u32 s47, s15, 0
	s_add_i32 s48, s48, s24
	s_mov_b32 m0, s48
	s_nop 0
	global_load_lds_dwordx4 v132, s[46:47]
	s_add_i32 m0, s48, 0x2000
	s_nop 0
	global_load_lds_dwordx4 v130, s[46:47]
	s_waitcnt vmcnt(6)
	s_barrier
; #define PG8_STAGE(bufoff, gbase, voff) do { _Pragma("unroll") for (int _i = 0; _i < 2; ++_i) \
;     __builtin_amdgcn_global_load_lds((const unsigned*)((const char*)(gbase) + (voff)[_i]), (LAS unsigned*)(lds + (bufoff) + ldsw + _i * 8192), 16, 0, 0); } while (0)
; #define PG8_LDA(dst, b, h) do { _Pragma("unroll") for (int m = 0; m < 4; ++m) _Pragma("unroll") for (int k = 0; k < 2; ++k) dst[m][k] = *(const LAS bf16x8*)(lds + PG8_SA(b, h) + aoff + m * 2048 + k * 1024); } while (0)
; #define PG8_LDB(dst, b, h) do { _Pragma("unroll") for (int n = 0; n < 2; ++n) _Pragma("unroll") for (int k = 0; k < 2; ++k) dst[n][k] = *(const LAS bf16x8*)(lds + PG8_SB(b, h) + boff + n * 2048 + k * 1024); } while (0)
; #define PG8_MMA(ai, bj, At, Bt) do { __builtin_amdgcn_s_setprio(1); _Pragma("unroll") for (int m = 0; m < 4; ++m) _Pragma("unroll") for (int n = 0; n < 2; ++n) _Pragma("unroll") for (int k = 0; k < 2; ++k) \
;     acc[ai][bj][m][n] = __builtin_amdgcn_mfma_f32_16x16x32_bf16(Bt[n][k], At[m][k], acc[ai][bj][m][n], 0, 0, 0); __builtin_amdgcn_s_setprio(0); } while (0)
; #define PG8_WAIT_V(n) asm volatile("s_waitcnt vmcnt(" #n ")" ::: "memory")
; #define PG8_WAIT_L(n) asm volatile("s_waitcnt lgkmcnt(" #n ")" ::: "memory")
; #define PG8_BAR __builtin_amdgcn_s_barrier()
; #define PG8_SCHED __builtin_amdgcn_sched_barrier(0)
; template <class Epi, class Sched>
; DI void gemm_phase(LAS unsigned char* lds, const int tid, const Gemm g, const Sched& S, const Epi& E) {
;     ...
;       PG8_WAIT_V(6); PG8_BAR; PG8_MMA(1, 1, At, B1); PG8_BAR;
;       PG8_LDB(B0, 1, 0); PG8_SCHED; PG8_LDA(At, 1, 0); PG8_STAGE(PG8_SA(0, 1), a2 + hstepA, voffA);
;       PG8_WAIT_L(8); PG8_BAR; PG8_WAIT_L(0); PG8_MMA(0, 0, At, B0); PG8_BAR; PG8_SCHED;
;       PG8_LDB(B1, 1, 1); PG8_STAGE(PG8_SB(1, 0), b3, voffB);
;       PG8_BAR; PG8_WAIT_L(0); PG8_MMA(0, 1, At, B1); PG8_BAR;
;       PG8_LDA(At, 1, 1); PG8_STAGE(PG8_SA(1, 0), a3, voffA);
;       PG8_BAR; PG8_WAIT_L(0); PG8_MMA(1, 0, At, B0); PG8_BAR; PG8_SCHED;
	s_setprio 1
	v_mfma_f32_16x16x32_bf16 v[54:57], v[206:209], v[158:161], v[54:57]
	v_mfma_f32_16x16x32_bf16 v[50:53], v[226:229], v[158:161], v[50:53]
	v_mfma_f32_16x16x32_bf16 v[38:41], v[206:209], v[166:169], v[38:41]
	v_mfma_f32_16x16x32_bf16 v[34:37], v[226:229], v[166:169], v[34:37]
	v_mfma_f32_16x16x32_bf16 v[22:25], v[206:209], v[174:177], v[22:25]
	v_mfma_f32_16x16x32_bf16 v[18:21], v[226:229], v[174:177], v[18:21]
	v_mfma_f32_16x16x32_bf16 v[6:9], v[206:209], v[182:185], v[6:9]
	v_mfma_f32_16x16x32_bf16 v[2:5], v[226:229], v[182:185], v[2:5]
	v_mfma_f32_16x16x32_bf16 v[54:57], v[210:213], v[162:165], v[54:57]
	v_mfma_f32_16x16x32_bf16 v[50:53], v[238:241], v[162:165], v[50:53]
	v_mfma_f32_16x16x32_bf16 v[38:41], v[210:213], v[170:173], v[38:41]
	v_mfma_f32_16x16x32_bf16 v[34:37], v[238:241], v[170:173], v[34:37]
	v_mfma_f32_16x16x32_bf16 v[22:25], v[210:213], v[178:181], v[22:25]
	v_mfma_f32_16x16x32_bf16 v[18:21], v[238:241], v[178:181], v[18:21]
	v_mfma_f32_16x16x32_bf16 v[6:9], v[210:213], v[202:205], v[6:9]
	v_mfma_f32_16x16x32_bf16 v[2:5], v[238:241], v[202:205], v[2:5]
	s_setprio 0
	s_add_i32 s46, 0, 0x18000
	v_add_u32_e32 v0, s46, v140
	s_barrier
	ds_read_b128 v[142:145], v0
	ds_read_b128 v[146:149], v0 offset:1024
	ds_read_b128 v[150:153], v0 offset:2048
	ds_read_b128 v[154:157], v0 offset:3072
	s_add_u32 s18, s18, 0x40000
	s_addc_u32 s19, s19, 0
	s_mov_b32 m0, s29
	ds_read_b128 v[158:161], v141 offset:32768
	ds_read_b128 v[162:165], v141 offset:33792
	ds_read_b128 v[166:169], v141 offset:34816
	ds_read_b128 v[170:173], v141 offset:35840
	ds_read_b128 v[174:177], v141 offset:36864
	ds_read_b128 v[178:181], v141 offset:37888
	ds_read_b128 v[182:185], v141 offset:38912
	ds_read_b128 v[202:205], v141 offset:39936
	global_load_lds_dwordx4 v132, s[18:19]
	s_mov_b32 m0, s30
	s_nop 0
	global_load_lds_dwordx4 v130, s[18:19]
	s_waitcnt lgkmcnt(8)
	s_barrier
	s_waitcnt lgkmcnt(0)
	s_setprio 1
	v_mfma_f32_16x16x32_bf16 v[126:129], v[142:145], v[158:161], v[126:129]
	v_mfma_f32_16x16x32_bf16 v[122:125], v[150:153], v[158:161], v[122:125]
	v_mfma_f32_16x16x32_bf16 v[110:113], v[142:145], v[166:169], v[110:113]
	v_mfma_f32_16x16x32_bf16 v[106:109], v[150:153], v[166:169], v[106:109]
	v_mfma_f32_16x16x32_bf16 v[94:97], v[142:145], v[174:177], v[94:97]
	v_mfma_f32_16x16x32_bf16 v[90:93], v[150:153], v[174:177], v[90:93]
	v_mfma_f32_16x16x32_bf16 v[78:81], v[142:145], v[182:185], v[78:81]
	v_mfma_f32_16x16x32_bf16 v[74:77], v[150:153], v[182:185], v[74:77]
	v_mfma_f32_16x16x32_bf16 v[126:129], v[146:149], v[162:165], v[126:129]
	v_mfma_f32_16x16x32_bf16 v[122:125], v[154:157], v[162:165], v[122:125]
	v_mfma_f32_16x16x32_bf16 v[110:113], v[146:149], v[170:173], v[110:113]
	v_mfma_f32_16x16x32_bf16 v[106:109], v[154:157], v[170:173], v[106:109]
	v_mfma_f32_16x16x32_bf16 v[94:97], v[146:149], v[178:181], v[94:97]
	v_mfma_f32_16x16x32_bf16 v[90:93], v[154:157], v[178:181], v[90:93]
	v_mfma_f32_16x16x32_bf16 v[78:81], v[146:149], v[202:205], v[78:81]
	v_mfma_f32_16x16x32_bf16 v[74:77], v[154:157], v[202:205], v[74:77]
	s_setprio 0
	s_barrier
	s_add_i32 s18, 0, 0x1c000
	s_add_i32 s19, s46, s24
	v_add_u32_e32 v0, s18, v140
	s_mov_b32 m0, s19
	ds_read_b128 v[206:209], v0
	ds_read_b128 v[210:213], v0 offset:1024
	ds_read_b128 v[226:229], v0 offset:2048
	ds_read_b128 v[238:241], v0 offset:3072
	global_load_lds_dwordx4 v132, s[98:99]
	s_add_i32 m0, s19, 0x2000
	s_nop 0
	global_load_lds_dwordx4 v130, s[98:99]
	s_barrier
	s_waitcnt lgkmcnt(0)
	s_setprio 1
	v_mfma_f32_16x16x32_bf16 v[118:121], v[206:209], v[158:161], v[118:121]
	v_mfma_f32_16x16x32_bf16 v[114:117], v[226:229], v[158:161], v[114:117]
	v_mfma_f32_16x16x32_bf16 v[102:105], v[206:209], v[166:169], v[102:105]
	v_mfma_f32_16x16x32_bf16 v[98:101], v[226:229], v[166:169], v[98:101]
	v_mfma_f32_16x16x32_bf16 v[86:89], v[206:209], v[174:177], v[86:89]
	v_mfma_f32_16x16x32_bf16 v[82:85], v[226:229], v[174:177], v[82:85]
	v_mfma_f32_16x16x32_bf16 v[70:73], v[206:209], v[182:185], v[70:73]
	v_mfma_f32_16x16x32_bf16 v[66:69], v[226:229], v[182:185], v[66:69]
	v_mfma_f32_16x16x32_bf16 v[118:121], v[210:213], v[162:165], v[118:121]
	v_mfma_f32_16x16x32_bf16 v[114:117], v[238:241], v[162:165], v[114:117]
	v_mfma_f32_16x16x32_bf16 v[102:105], v[210:213], v[170:173], v[102:105]
	v_mfma_f32_16x16x32_bf16 v[98:101], v[238:241], v[170:173], v[98:101]
	v_mfma_f32_16x16x32_bf16 v[86:89], v[210:213], v[178:181], v[86:89]
	v_mfma_f32_16x16x32_bf16 v[82:85], v[238:241], v[178:181], v[82:85]
	v_mfma_f32_16x16x32_bf16 v[70:73], v[210:213], v[202:205], v[70:73]
	v_mfma_f32_16x16x32_bf16 v[66:69], v[238:241], v[202:205], v[66:69]
	s_setprio 0
	s_mov_b32 m0, s36
	s_barrier
	ds_read_b128 v[158:161], v141 offset:49152
	ds_read_b128 v[162:165], v141 offset:50176
	ds_read_b128 v[166:169], v141 offset:51200
	ds_read_b128 v[170:173], v141 offset:52224
	ds_read_b128 v[174:177], v141 offset:53248
	ds_read_b128 v[178:181], v141 offset:54272
	ds_read_b128 v[182:185], v141 offset:55296
	ds_read_b128 v[202:205], v141 offset:56320
	global_load_lds_dwordx4 v132, s[100:101]
	s_mov_b32 m0, s37
	s_nop 0
	global_load_lds_dwordx4 v130, s[100:101]
	s_barrier
; #define GAS __attribute__((address_space(1)))
; DI unsigned pk(float a, float b) { f32x2 v = {a, b}; return __builtin_bit_cast(unsigned, __builtin_convertvector(v, bf16x2_t)); }
; #define PG8_STAGE(bufoff, gbase, voff) do { _Pragma("unroll") for (int _i = 0; _i < 2; ++_i) \
;     __builtin_amdgcn_global_load_lds((const unsigned*)((const char*)(gbase) + (voff)[_i]), (LAS unsigned*)(lds + (bufoff) + ldsw + _i * 8192), 16, 0, 0); } while (0)
; #define PG8_MMA(ai, bj, At, Bt) do { __builtin_amdgcn_s_setprio(1); _Pragma("unroll") for (int m = 0; m < 4; ++m) _Pragma("unroll") for (int n = 0; n < 2; ++n) _Pragma("unroll") for (int k = 0; k < 2; ++k) \
;     acc[ai][bj][m][n] = __builtin_amdgcn_mfma_f32_16x16x32_bf16(Bt[n][k], At[m][k], acc[ai][bj][m][n], 0, 0, 0); __builtin_amdgcn_s_setprio(0); } while (0)
; #define PG8_WAIT_V(n) asm volatile("s_waitcnt vmcnt(" #n ")" ::: "memory")
; #define PG8_WAIT_L(n) asm volatile("s_waitcnt lgkmcnt(" #n ")" ::: "memory")
; #define PG8_BAR __builtin_amdgcn_s_barrier()
; #define PG8_SCHED __builtin_amdgcn_sched_barrier(0)
; #define ROWS_LOOP _Pragma("unroll") for (int ai = 0; ai < 2; ++ai) _Pragma("unroll") for (int m = 0; m < 4; ++m)
; template <class Epi, class Sched>
; DI void gemm_phase(LAS unsigned char* lds, const int tid, const Gemm g, const Sched& S, const Epi& E) {
;     ...
;       PG8_BAR; PG8_WAIT_L(0); PG8_MMA(1, 0, At, B0); PG8_BAR; PG8_SCHED;
;       PG8_STAGE(PG8_SB(1, 1), b3 + hstepB, voffB);
;       PG8_WAIT_V(6); PG8_BAR; PG8_MMA(1, 1, At, B1); PG8_BAR;
;     }
;   DI void operator()(const AccT& acc, const Unit& u, int wr, int wc, int fr, int fq) const {
;     const char* base = (const char*)(HID + (size_t)u.pm * 256 * DFF + u.pn * 128);
;     const unsigned o0 = (unsigned)((wr * 64 + fr) * DFF + wc * 32 + fq * 8) * 2u;
;     ROWS_LOOP {
;       char* rb = (char*)base + (size_t)(ai * 128 + m * 16) * DFF * 2;
;       f32x4 h[2];
; #pragma unroll
;       for (int n = 0; n < 2; ++n) {
;         const f32x4 gt = acc[ai][0][m][n], up = acc[ai][1][m][n];
; #pragma unroll
;         for (int e = 0; e < 4; ++e) h[n][e] = gt[e] * __builtin_amdgcn_rcpf(1.f + __expf(-gt[e])) * up[e];
;       }
;       u32x4 o = {pk(h[0][0], h[0][1]), pk(h[0][2], h[0][3]), pk(h[1][0], h[1][1]), pk(h[1][2], h[1][3])};
;       *(GAS u32x4*)(rb + o0) = o;
;     }
	s_waitcnt lgkmcnt(0)
	s_setprio 1
	v_mfma_f32_16x16x32_bf16 v[62:65], v[142:145], v[158:161], v[62:65]
	v_mfma_f32_16x16x32_bf16 v[58:61], v[150:153], v[158:161], v[58:61]
	v_mfma_f32_16x16x32_bf16 v[46:49], v[142:145], v[166:169], v[46:49]
	v_mfma_f32_16x16x32_bf16 v[42:45], v[150:153], v[166:169], v[42:45]
	v_mfma_f32_16x16x32_bf16 v[30:33], v[142:145], v[174:177], v[30:33]
	v_mfma_f32_16x16x32_bf16 v[26:29], v[150:153], v[174:177], v[26:29]
	v_mfma_f32_16x16x32_bf16 v[14:17], v[142:145], v[182:185], v[14:17]
	v_mfma_f32_16x16x32_bf16 v[10:13], v[150:153], v[182:185], v[10:13]
	v_mfma_f32_16x16x32_bf16 v[62:65], v[146:149], v[162:165], v[62:65]
	v_mfma_f32_16x16x32_bf16 v[58:61], v[154:157], v[162:165], v[58:61]
	v_mfma_f32_16x16x32_bf16 v[46:49], v[146:149], v[170:173], v[46:49]
	v_mfma_f32_16x16x32_bf16 v[42:45], v[154:157], v[170:173], v[42:45]
	v_mfma_f32_16x16x32_bf16 v[30:33], v[146:149], v[178:181], v[30:33]
	v_mfma_f32_16x16x32_bf16 v[26:29], v[154:157], v[178:181], v[26:29]
	v_mfma_f32_16x16x32_bf16 v[14:17], v[146:149], v[202:205], v[14:17]
	v_mfma_f32_16x16x32_bf16 v[10:13], v[154:157], v[202:205], v[10:13]
	s_setprio 0
	s_barrier
	s_add_u32 s14, s14, 0x40080
	s_addc_u32 s15, s15, 0
	s_add_i32 s18, s18, s24
	s_mov_b32 m0, s18
	s_nop 0
	global_load_lds_dwordx4 v132, s[14:15]
	s_add_i32 m0, s18, 0x2000
	s_nop 0
	global_load_lds_dwordx4 v130, s[14:15]
	s_waitcnt vmcnt(6)
	s_barrier
	s_setprio 1
	v_mfma_f32_16x16x32_bf16 v[54:57], v[206:209], v[158:161], v[54:57]
	v_mfma_f32_16x16x32_bf16 v[50:53], v[226:229], v[158:161], v[50:53]
	v_mfma_f32_16x16x32_bf16 v[38:41], v[206:209], v[166:169], v[38:41]
	v_mfma_f32_16x16x32_bf16 v[34:37], v[226:229], v[166:169], v[34:37]
	v_mfma_f32_16x16x32_bf16 v[22:25], v[206:209], v[174:177], v[22:25]
	v_mfma_f32_16x16x32_bf16 v[18:21], v[226:229], v[174:177], v[18:21]
	v_mfma_f32_16x16x32_bf16 v[6:9], v[206:209], v[182:185], v[6:9]
	v_mfma_f32_16x16x32_bf16 v[2:5], v[226:229], v[182:185], v[2:5]
	v_mfma_f32_16x16x32_bf16 v[54:57], v[210:213], v[162:165], v[54:57]
	v_mfma_f32_16x16x32_bf16 v[50:53], v[238:241], v[162:165], v[50:53]
	v_mfma_f32_16x16x32_bf16 v[38:41], v[210:213], v[170:173], v[38:41]
	v_mfma_f32_16x16x32_bf16 v[34:37], v[238:241], v[170:173], v[34:37]
	v_mfma_f32_16x16x32_bf16 v[22:25], v[210:213], v[178:181], v[22:25]
	v_mfma_f32_16x16x32_bf16 v[18:21], v[238:241], v[178:181], v[18:21]
	v_mfma_f32_16x16x32_bf16 v[6:9], v[210:213], v[202:205], v[6:9]
	v_mfma_f32_16x16x32_bf16 v[2:5], v[238:241], v[202:205], v[2:5]
	s_setprio 0
	s_add_i32 s44, s44, 2
	s_add_u32 s42, s42, 0x100
	s_addc_u32 s43, s43, 0
	s_add_u32 s16, s16, 0x100
	s_addc_u32 s17, s17, 0
	s_cmp_gt_u32 s44, 13
	s_barrier
	s_cbranch_scc0 .LBB0_387
	v_mul_f32_e32 v139, 0xbfb8aa3b, v126
	v_exp_f32_e32 v139, v139
	v_mul_f32_e32 v142, 0xbfb8aa3b, v127
	v_exp_f32_e32 v143, v142
	s_mul_i32 s7, s12, 0x160000
	v_add_f32_e32 v139, 1.0, v139
	v_rcp_f32_e32 v142, v139
	v_add_f32_e32 v139, 1.0, v143
	v_rcp_f32_e32 v143, v139
	s_mul_hi_i32 s1, s12, 0x160000
	s_add_u32 s7, s31, s7
	v_mov_b32_e32 v0, v1
	v_pk_mul_f32 v[126:127], v[126:127], v[142:143]
	v_mul_f32_e32 v142, 0xbfb8aa3b, v128
	v_mul_f32_e32 v143, 0xbfb8aa3b, v129
	v_exp_f32_e32 v142, v142
	v_exp_f32_e32 v143, v143
	v_pk_mul_f32 v[118:119], v[126:127], v[118:119]
	s_addc_u32 s1, s34, s1
	v_add_f32_e32 v126, 1.0, v142
	v_add_f32_e32 v127, 1.0, v143
	v_mul_f32_e32 v142, 0xbfb8aa3b, v122
	v_mul_f32_e32 v143, 0xbfb8aa3b, v123
	v_rcp_f32_e32 v126, v126
	v_rcp_f32_e32 v127, v127
	v_exp_f32_e32 v142, v142
	v_exp_f32_e32 v143, v143
	s_lshl_b32 s12, s13, 7
	v_pk_mul_f32 v[126:127], v[128:129], v[126:127]
	v_add_f32_e32 v128, 1.0, v142
	v_add_f32_e32 v129, 1.0, v143
	v_mul_f32_e32 v142, 0xbfb8aa3b, v124
	v_mul_f32_e32 v143, 0xbfb8aa3b, v125
	v_exp_f32_e32 v142, v142
	v_exp_f32_e32 v143, v143
	v_rcp_f32_e32 v128, v128
	v_rcp_f32_e32 v129, v129
	v_add_f32_e32 v142, 1.0, v142
	v_add_f32_e32 v143, 1.0, v143
	v_rcp_f32_e32 v142, v142
	v_rcp_f32_e32 v143, v143
	v_pk_mul_f32 v[122:123], v[122:123], v[128:129]
	s_ashr_i32 s13, s12, 31
	v_pk_mul_f32 v[122:123], v[122:123], v[114:115]
	v_pk_mul_f32 v[114:115], v[124:125], v[142:143]
	v_mbcnt_lo_u32_b32 v0, -1, v0
	v_pk_mul_f32 v[124:125], v[114:115], v[116:117]
	v_mul_f32_e32 v115, 0xbfb8aa3b, v110
	v_exp_f32_e32 v116, v115
	v_mul_f32_e32 v115, 0xbfb8aa3b, v111
	v_exp_f32_e32 v117, v115
	s_lshl_b64 s[12:13], s[12:13], 1
	v_mbcnt_hi_u32_b32 v0, -1, v0
	s_add_u32 s12, s7, s12
	s_addc_u32 s13, s1, s13
	v_and_or_b32 v138, v0, 15, s35
	s_movk_i32 s1, 0x1600
	v_add_f32_e32 v116, 1.0, v116
	v_and_b32_e32 v0, -16, v0
	v_mul_lo_u32 v138, v138, s1
	v_pk_mul_f32 v[120:121], v[126:127], v[120:121]
	v_cvt_pk_bf16_f32 v114, v118, v119
	v_rcp_f32_e32 v118, v116
	v_add_f32_e32 v116, 1.0, v117
	v_add3_u32 v0, v0, s38, v138
	v_cvt_pk_bf16_f32 v115, v120, v121
	v_rcp_f32_e32 v119, v116
	v_cvt_pk_bf16_f32 v116, v122, v123
	v_cvt_pk_bf16_f32 v117, v124, v125
	v_lshl_add_u64 v[138:139], s[12:13], 0, v[0:1]
	global_store_dwordx4 v0, v[114:117], s[12:13]
	v_mul_f32_e32 v0, 0xbfb8aa3b, v112
	v_exp_f32_e32 v0, v0
	v_mul_f32_e32 v114, 0xbfb8aa3b, v113
	v_exp_f32_e32 v114, v114
	v_pk_mul_f32 v[110:111], v[110:111], v[118:119]
	v_add_f32_e32 v0, 1.0, v0
	v_pk_mul_f32 v[102:103], v[110:111], v[102:103]
	v_rcp_f32_e32 v110, v0
	v_add_f32_e32 v0, 1.0, v114
	v_rcp_f32_e32 v111, v0
	v_mul_f32_e32 v0, 0xbfb8aa3b, v106
	v_exp_f32_e32 v0, v0
	v_mul_f32_e32 v114, 0xbfb8aa3b, v107
	v_exp_f32_e32 v114, v114
	v_pk_mul_f32 v[110:111], v[112:113], v[110:111]
	v_add_f32_e32 v0, 1.0, v0
	v_mul_f32_e32 v113, 0xbfb8aa3b, v108
	v_rcp_f32_e32 v112, v0
	v_add_f32_e32 v0, 1.0, v114
; #define GAS __attribute__((address_space(1)))
; DI unsigned pk(float a, float b) { f32x2 v = {a, b}; return __builtin_bit_cast(unsigned, __builtin_convertvector(v, bf16x2_t)); }
; #define ROWS_LOOP _Pragma("unroll") for (int ai = 0; ai < 2; ++ai) _Pragma("unroll") for (int m = 0; m < 4; ++m)
;   DI void operator()(const AccT& acc, const Unit& u, int wr, int wc, int fr, int fq) const {
;     ...
;     ROWS_LOOP {
;       char* rb = (char*)base + (size_t)(ai * 128 + m * 16) * DFF * 2;
;       f32x4 h[2];
; #pragma unroll
;       for (int n = 0; n < 2; ++n) {
;         const f32x4 gt = acc[ai][0][m][n], up = acc[ai][1][m][n];
; #pragma unroll
;         for (int e = 0; e < 4; ++e) h[n][e] = gt[e] * __builtin_amdgcn_rcpf(1.f + __expf(-gt[e])) * up[e];
;       }
;       u32x4 o = {pk(h[0][0], h[0][1]), pk(h[0][2], h[0][3]), pk(h[1][0], h[1][1]), pk(h[1][2], h[1][3])};
;       *(GAS u32x4*)(rb + o0) = o;
;     }
	v_exp_f32_e32 v114, v113
	v_mul_f32_e32 v113, 0xbfb8aa3b, v109
	v_exp_f32_e32 v115, v113
	v_rcp_f32_e32 v113, v0
	v_add_f32_e32 v0, 1.0, v114
	v_rcp_f32_e32 v114, v0
	v_add_f32_e32 v0, 1.0, v115
	v_rcp_f32_e32 v115, v0
	v_pk_mul_f32 v[106:107], v[106:107], v[112:113]
	v_mul_f32_e32 v0, 0xbfb8aa3b, v94
	v_pk_mul_f32 v[106:107], v[106:107], v[98:99]
	v_pk_mul_f32 v[98:99], v[108:109], v[114:115]
	v_exp_f32_e32 v0, v0
	v_pk_mul_f32 v[108:109], v[98:99], v[100:101]
	v_mul_f32_e32 v101, 0xbfb8aa3b, v95
	v_cvt_pk_bf16_f32 v98, v102, v103
	v_exp_f32_e32 v103, v101
	v_pk_mul_f32 v[104:105], v[110:111], v[104:105]
	v_add_f32_e32 v0, 1.0, v0
	s_mov_b32 s1, 0x16000
	v_cvt_pk_bf16_f32 v99, v104, v105
	v_rcp_f32_e32 v102, v0
	v_add_f32_e32 v0, 1.0, v103
	v_add_co_u32_e32 v104, vcc, s1, v138
	v_cvt_pk_bf16_f32 v100, v106, v107
	v_cvt_pk_bf16_f32 v101, v108, v109
	v_rcp_f32_e32 v103, v0
	v_addc_co_u32_e32 v105, vcc, 0, v139, vcc
	v_mul_f32_e32 v0, 0xbfb8aa3b, v96
	global_store_dwordx4 v[104:105], v[98:101], off
	v_exp_f32_e32 v0, v0
	v_pk_mul_f32 v[94:95], v[94:95], v[102:103]
	v_mul_f32_e32 v98, 0xbfb8aa3b, v97
	v_exp_f32_e32 v98, v98
	v_add_f32_e32 v0, 1.0, v0
	v_pk_mul_f32 v[86:87], v[94:95], v[86:87]
	v_rcp_f32_e32 v94, v0
	v_add_f32_e32 v0, 1.0, v98
	v_rcp_f32_e32 v95, v0
	v_mul_f32_e32 v0, 0xbfb8aa3b, v90
	v_exp_f32_e32 v0, v0
	v_mul_f32_e32 v98, 0xbfb8aa3b, v91
	v_exp_f32_e32 v98, v98
	v_pk_mul_f32 v[94:95], v[96:97], v[94:95]
	v_add_f32_e32 v0, 1.0, v0
	v_mul_f32_e32 v97, 0xbfb8aa3b, v92
	v_rcp_f32_e32 v96, v0
	v_add_f32_e32 v0, 1.0, v98
	v_exp_f32_e32 v98, v97
	v_mul_f32_e32 v97, 0xbfb8aa3b, v93
	v_exp_f32_e32 v99, v97
	v_rcp_f32_e32 v97, v0
	v_add_f32_e32 v0, 1.0, v98
	v_rcp_f32_e32 v98, v0
	v_add_f32_e32 v0, 1.0, v99
	v_rcp_f32_e32 v99, v0
	v_pk_mul_f32 v[90:91], v[90:91], v[96:97]
	v_mul_f32_e32 v0, 0xbfb8aa3b, v78
	v_pk_mul_f32 v[90:91], v[90:91], v[82:83]
	v_pk_mul_f32 v[82:83], v[92:93], v[98:99]
	v_exp_f32_e32 v0, v0
	v_pk_mul_f32 v[92:93], v[82:83], v[84:85]
	v_mul_f32_e32 v85, 0xbfb8aa3b, v79
	v_cvt_pk_bf16_f32 v82, v86, v87
	v_exp_f32_e32 v87, v85
	v_pk_mul_f32 v[88:89], v[94:95], v[88:89]
	v_add_f32_e32 v0, 1.0, v0
	s_mov_b32 s1, 0x2c000
	v_cvt_pk_bf16_f32 v83, v88, v89
	v_rcp_f32_e32 v86, v0
	v_add_f32_e32 v0, 1.0, v87
	v_add_co_u32_e32 v88, vcc, s1, v138
	v_cvt_pk_bf16_f32 v84, v90, v91
	v_cvt_pk_bf16_f32 v85, v92, v93
	v_rcp_f32_e32 v87, v0
	v_addc_co_u32_e32 v89, vcc, 0, v139, vcc
	v_mul_f32_e32 v0, 0xbfb8aa3b, v80
	global_store_dwordx4 v[88:89], v[82:85], off
	v_exp_f32_e32 v0, v0
	v_pk_mul_f32 v[78:79], v[78:79], v[86:87]
	v_mul_f32_e32 v82, 0xbfb8aa3b, v81
	v_exp_f32_e32 v82, v82
	v_add_f32_e32 v0, 1.0, v0
	v_pk_mul_f32 v[70:71], v[78:79], v[70:71]
	v_rcp_f32_e32 v78, v0
	v_add_f32_e32 v0, 1.0, v82
	v_rcp_f32_e32 v79, v0
	v_mul_f32_e32 v0, 0xbfb8aa3b, v74
	v_exp_f32_e32 v0, v0
	v_mul_f32_e32 v82, 0xbfb8aa3b, v75
	v_exp_f32_e32 v82, v82
	v_pk_mul_f32 v[78:79], v[80:81], v[78:79]
	v_add_f32_e32 v0, 1.0, v0
	v_mul_f32_e32 v81, 0xbfb8aa3b, v76
	v_rcp_f32_e32 v80, v0
	v_add_f32_e32 v0, 1.0, v82
	v_exp_f32_e32 v82, v81
	v_mul_f32_e32 v81, 0xbfb8aa3b, v77
	v_exp_f32_e32 v83, v81
	v_rcp_f32_e32 v81, v0
	v_add_f32_e32 v0, 1.0, v82
	v_rcp_f32_e32 v82, v0
	v_add_f32_e32 v0, 1.0, v83
	v_rcp_f32_e32 v83, v0
	v_pk_mul_f32 v[74:75], v[74:75], v[80:81]
	v_mul_f32_e32 v0, 0xbfb8aa3b, v62
	v_pk_mul_f32 v[74:75], v[74:75], v[66:67]
	v_pk_mul_f32 v[66:67], v[76:77], v[82:83]
	v_exp_f32_e32 v0, v0
	v_pk_mul_f32 v[76:77], v[66:67], v[68:69]
	v_mul_f32_e32 v69, 0xbfb8aa3b, v63
	v_cvt_pk_bf16_f32 v66, v70, v71
	v_exp_f32_e32 v71, v69
	v_pk_mul_f32 v[72:73], v[78:79], v[72:73]
	v_add_f32_e32 v0, 1.0, v0
	s_mov_b32 s1, 0x42000
	v_cvt_pk_bf16_f32 v67, v72, v73
	v_rcp_f32_e32 v70, v0
	v_add_f32_e32 v0, 1.0, v71
	v_add_co_u32_e32 v72, vcc, s1, v138
	v_cvt_pk_bf16_f32 v68, v74, v75
	v_cvt_pk_bf16_f32 v69, v76, v77
	v_rcp_f32_e32 v71, v0
	v_addc_co_u32_e32 v73, vcc, 0, v139, vcc
	v_mul_f32_e32 v0, 0xbfb8aa3b, v64
	global_store_dwordx4 v[72:73], v[66:69], off
	v_exp_f32_e32 v0, v0
	v_pk_mul_f32 v[62:63], v[62:63], v[70:71]
	v_mul_f32_e32 v66, 0xbfb8aa3b, v65
	v_exp_f32_e32 v66, v66
	v_add_f32_e32 v0, 1.0, v0
	v_pk_mul_f32 v[54:55], v[62:63], v[54:55]
	v_rcp_f32_e32 v62, v0
	v_add_f32_e32 v0, 1.0, v66
	v_rcp_f32_e32 v63, v0
	v_mul_f32_e32 v0, 0xbfb8aa3b, v58
	v_exp_f32_e32 v0, v0
	v_mul_f32_e32 v66, 0xbfb8aa3b, v59
	v_exp_f32_e32 v66, v66
	v_pk_mul_f32 v[62:63], v[64:65], v[62:63]
	v_add_f32_e32 v0, 1.0, v0
	v_mul_f32_e32 v65, 0xbfb8aa3b, v60
	v_rcp_f32_e32 v64, v0
	v_add_f32_e32 v0, 1.0, v66
	v_exp_f32_e32 v66, v65
	v_mul_f32_e32 v65, 0xbfb8aa3b, v61
	v_exp_f32_e32 v67, v65
	v_rcp_f32_e32 v65, v0
	v_add_f32_e32 v0, 1.0, v66
	v_rcp_f32_e32 v66, v0
	v_add_f32_e32 v0, 1.0, v67
	v_rcp_f32_e32 v67, v0
	v_pk_mul_f32 v[58:59], v[58:59], v[64:65]
	v_mul_f32_e32 v0, 0xbfb8aa3b, v46
	v_pk_mul_f32 v[58:59], v[58:59], v[50:51]
	v_pk_mul_f32 v[50:51], v[60:61], v[66:67]
	v_exp_f32_e32 v0, v0
	v_pk_mul_f32 v[60:61], v[50:51], v[52:53]
; #define GAS __attribute__((address_space(1)))
; DI unsigned pk(float a, float b) { f32x2 v = {a, b}; return __builtin_bit_cast(unsigned, __builtin_convertvector(v, bf16x2_t)); }
; #define ROWS_LOOP _Pragma("unroll") for (int ai = 0; ai < 2; ++ai) _Pragma("unroll") for (int m = 0; m < 4; ++m)
; template <class Epi, class Sched>
; DI void gemm_phase(LAS unsigned char* lds, const int tid, const Gemm g, const Sched& S, const Epi& E) {
;     ...
;     { int z_e = 0; asm volatile("" : "+v"(z_e)); const int lane_e = __builtin_amdgcn_mbcnt_hi(~0u, __builtin_amdgcn_mbcnt_lo(~0u, (unsigned)z_e));
;       E(acc, cur, wr, wc, lane_e & 15, lane_e >> 4); }
;     if (!has_next) break;
;   DI void operator()(const AccT& acc, const Unit& u, int wr, int wc, int fr, int fq) const {
;     ...
;     ROWS_LOOP {
;       char* rb = (char*)base + (size_t)(ai * 128 + m * 16) * DFF * 2;
;       f32x4 h[2];
; #pragma unroll
;       for (int n = 0; n < 2; ++n) {
;         const f32x4 gt = acc[ai][0][m][n], up = acc[ai][1][m][n];
; #pragma unroll
;         for (int e = 0; e < 4; ++e) h[n][e] = gt[e] * __builtin_amdgcn_rcpf(1.f + __expf(-gt[e])) * up[e];
;       }
;       u32x4 o = {pk(h[0][0], h[0][1]), pk(h[0][2], h[0][3]), pk(h[1][0], h[1][1]), pk(h[1][2], h[1][3])};
;       *(GAS u32x4*)(rb + o0) = o;
;     }
	v_mul_f32_e32 v53, 0xbfb8aa3b, v47
	v_cvt_pk_bf16_f32 v50, v54, v55
	v_exp_f32_e32 v55, v53
	v_pk_mul_f32 v[56:57], v[62:63], v[56:57]
	v_add_f32_e32 v0, 1.0, v0
	s_mov_b32 s1, 0xb0000
	v_cvt_pk_bf16_f32 v51, v56, v57
	v_rcp_f32_e32 v54, v0
	v_add_f32_e32 v0, 1.0, v55
	v_add_co_u32_e32 v56, vcc, s1, v138
	v_cvt_pk_bf16_f32 v52, v58, v59
	v_cvt_pk_bf16_f32 v53, v60, v61
	v_rcp_f32_e32 v55, v0
	v_addc_co_u32_e32 v57, vcc, 0, v139, vcc
	v_mul_f32_e32 v0, 0xbfb8aa3b, v48
	global_store_dwordx4 v[56:57], v[50:53], off
	v_exp_f32_e32 v0, v0
	v_pk_mul_f32 v[46:47], v[46:47], v[54:55]
	v_mul_f32_e32 v50, 0xbfb8aa3b, v49
	v_exp_f32_e32 v50, v50
	v_add_f32_e32 v0, 1.0, v0
	v_pk_mul_f32 v[38:39], v[46:47], v[38:39]
	v_rcp_f32_e32 v46, v0
	v_add_f32_e32 v0, 1.0, v50
	v_rcp_f32_e32 v47, v0
	v_mul_f32_e32 v0, 0xbfb8aa3b, v42
	v_exp_f32_e32 v0, v0
	v_mul_f32_e32 v50, 0xbfb8aa3b, v43
	v_exp_f32_e32 v50, v50
	v_pk_mul_f32 v[46:47], v[48:49], v[46:47]
	v_add_f32_e32 v0, 1.0, v0
	v_mul_f32_e32 v49, 0xbfb8aa3b, v44
	v_rcp_f32_e32 v48, v0
	v_add_f32_e32 v0, 1.0, v50
	v_exp_f32_e32 v50, v49
	v_mul_f32_e32 v49, 0xbfb8aa3b, v45
	v_exp_f32_e32 v51, v49
	v_rcp_f32_e32 v49, v0
	v_add_f32_e32 v0, 1.0, v50
	v_rcp_f32_e32 v50, v0
	v_add_f32_e32 v0, 1.0, v51
	v_rcp_f32_e32 v51, v0
	v_pk_mul_f32 v[42:43], v[42:43], v[48:49]
	v_mul_f32_e32 v0, 0xbfb8aa3b, v30
	v_pk_mul_f32 v[42:43], v[42:43], v[34:35]
	v_pk_mul_f32 v[34:35], v[44:45], v[50:51]
	v_exp_f32_e32 v0, v0
	v_pk_mul_f32 v[44:45], v[34:35], v[36:37]
	v_mul_f32_e32 v37, 0xbfb8aa3b, v31
	v_cvt_pk_bf16_f32 v34, v38, v39
	v_exp_f32_e32 v39, v37
	v_pk_mul_f32 v[40:41], v[46:47], v[40:41]
	v_add_f32_e32 v0, 1.0, v0
	s_mov_b32 s1, 0xc6000
	v_cvt_pk_bf16_f32 v35, v40, v41
	v_rcp_f32_e32 v38, v0
	v_add_f32_e32 v0, 1.0, v39
	v_add_co_u32_e32 v40, vcc, s1, v138
	v_cvt_pk_bf16_f32 v36, v42, v43
	v_cvt_pk_bf16_f32 v37, v44, v45
	v_rcp_f32_e32 v39, v0
	v_addc_co_u32_e32 v41, vcc, 0, v139, vcc
	v_mul_f32_e32 v0, 0xbfb8aa3b, v32
	global_store_dwordx4 v[40:41], v[34:37], off
	v_exp_f32_e32 v0, v0
	v_pk_mul_f32 v[30:31], v[30:31], v[38:39]
	v_mul_f32_e32 v34, 0xbfb8aa3b, v33
	v_exp_f32_e32 v34, v34
	v_add_f32_e32 v0, 1.0, v0
	v_pk_mul_f32 v[22:23], v[30:31], v[22:23]
	v_rcp_f32_e32 v30, v0
	v_add_f32_e32 v0, 1.0, v34
	v_rcp_f32_e32 v31, v0
	v_mul_f32_e32 v0, 0xbfb8aa3b, v26
	v_exp_f32_e32 v0, v0
	v_mul_f32_e32 v34, 0xbfb8aa3b, v27
	v_exp_f32_e32 v34, v34
	v_pk_mul_f32 v[30:31], v[32:33], v[30:31]
	v_add_f32_e32 v0, 1.0, v0
	v_mul_f32_e32 v33, 0xbfb8aa3b, v28
	v_rcp_f32_e32 v32, v0
	v_add_f32_e32 v0, 1.0, v34
	v_exp_f32_e32 v34, v33
	v_mul_f32_e32 v33, 0xbfb8aa3b, v29
	v_exp_f32_e32 v35, v33
	v_rcp_f32_e32 v33, v0
	v_add_f32_e32 v0, 1.0, v34
	v_rcp_f32_e32 v34, v0
	v_add_f32_e32 v0, 1.0, v35
	v_rcp_f32_e32 v35, v0
	v_pk_mul_f32 v[26:27], v[26:27], v[32:33]
	v_mul_f32_e32 v0, 0xbfb8aa3b, v14
	v_pk_mul_f32 v[26:27], v[26:27], v[18:19]
	v_pk_mul_f32 v[18:19], v[28:29], v[34:35]
	v_exp_f32_e32 v0, v0
	v_pk_mul_f32 v[28:29], v[18:19], v[20:21]
	v_mul_f32_e32 v21, 0xbfb8aa3b, v15
	v_cvt_pk_bf16_f32 v18, v22, v23
	v_exp_f32_e32 v23, v21
	v_pk_mul_f32 v[24:25], v[30:31], v[24:25]
	v_add_f32_e32 v0, 1.0, v0
	s_mov_b32 s1, 0xdc000
	v_cvt_pk_bf16_f32 v19, v24, v25
	v_rcp_f32_e32 v22, v0
	v_add_f32_e32 v0, 1.0, v23
	v_add_co_u32_e32 v24, vcc, s1, v138
	v_cvt_pk_bf16_f32 v20, v26, v27
	v_cvt_pk_bf16_f32 v21, v28, v29
	v_rcp_f32_e32 v23, v0
	v_addc_co_u32_e32 v25, vcc, 0, v139, vcc
	v_mul_f32_e32 v0, 0xbfb8aa3b, v16
	global_store_dwordx4 v[24:25], v[18:21], off
	v_exp_f32_e32 v0, v0
	v_pk_mul_f32 v[14:15], v[14:15], v[22:23]
	v_mul_f32_e32 v18, 0xbfb8aa3b, v17
	v_exp_f32_e32 v18, v18
	v_add_f32_e32 v0, 1.0, v0
	v_pk_mul_f32 v[6:7], v[14:15], v[6:7]
	v_rcp_f32_e32 v14, v0
	v_add_f32_e32 v0, 1.0, v18
	v_rcp_f32_e32 v15, v0
	v_mul_f32_e32 v0, 0xbfb8aa3b, v10
	v_exp_f32_e32 v0, v0
	v_mul_f32_e32 v18, 0xbfb8aa3b, v11
	v_exp_f32_e32 v18, v18
	v_pk_mul_f32 v[14:15], v[16:17], v[14:15]
	v_add_f32_e32 v0, 1.0, v0
	v_mul_f32_e32 v17, 0xbfb8aa3b, v12
	v_rcp_f32_e32 v16, v0
	v_add_f32_e32 v0, 1.0, v18
	v_exp_f32_e32 v18, v17
	v_mul_f32_e32 v17, 0xbfb8aa3b, v13
	v_exp_f32_e32 v19, v17
	v_rcp_f32_e32 v17, v0
	v_add_f32_e32 v0, 1.0, v18
	v_rcp_f32_e32 v18, v0
	v_add_f32_e32 v0, 1.0, v19
	v_rcp_f32_e32 v19, v0
	v_pk_mul_f32 v[10:11], v[10:11], v[16:17]
	v_pk_mul_f32 v[8:9], v[14:15], v[8:9]
	v_pk_mul_f32 v[10:11], v[10:11], v[2:3]
	v_pk_mul_f32 v[2:3], v[12:13], v[18:19]
	s_mov_b32 s13, s0
	v_pk_mul_f32 v[12:13], v[2:3], v[4:5]
	v_cvt_pk_bf16_f32 v2, v6, v7
	v_add_co_u32_e32 v6, vcc, 0xf2000, v138
	v_cvt_pk_bf16_f32 v3, v8, v9
	s_nop 0
	v_addc_co_u32_e32 v7, vcc, 0, v139, vcc
	v_cvt_pk_bf16_f32 v4, v10, v11
	v_cvt_pk_bf16_f32 v5, v12, v13
	s_and_b64 vcc, exec, s[4:5]
	s_mov_b32 s12, s6
	s_mov_b64 s[16:17], s[10:11]
	s_mov_b64 s[18:19], s[8:9]
	global_store_dwordx4 v[6:7], v[2:5], off
	s_cbranch_vccz .LBB0_384
	s_waitcnt vmcnt(0)
	s_cmpk_gt_u32 s3, 0xff
	s_cbranch_scc1 .LBB0_391
	s_barrier

; #define PG8_STAGE(bufoff, gbase, voff) do { _Pragma("unroll") for (int _i = 0; _i < 2; ++_i) \
;     __builtin_amdgcn_global_load_lds((const unsigned*)((const char*)(gbase) + (voff)[_i]), (LAS unsigned*)(lds + (bufoff) + ldsw + _i * 8192), 16, 0, 0); } while (0)
; #define PG8_LDA(dst, b, h) do { _Pragma("unroll") for (int m = 0; m < 4; ++m) _Pragma("unroll") for (int k = 0; k < 2; ++k) dst[m][k] = *(const LAS bf16x8*)(lds + PG8_SA(b, h) + aoff + m * 2048 + k * 1024); } while (0)
; #define PG8_LDB(dst, b, h) do { _Pragma("unroll") for (int n = 0; n < 2; ++n) _Pragma("unroll") for (int k = 0; k < 2; ++k) dst[n][k] = *(const LAS bf16x8*)(lds + PG8_SB(b, h) + boff + n * 2048 + k * 1024); } while (0)
; #define PG8_WAIT_V(n) asm volatile("s_waitcnt vmcnt(" #n ")" ::: "memory")
; #define PG8_WAIT_L(n) asm volatile("s_waitcnt lgkmcnt(" #n ")" ::: "memory")
; #define PG8_BAR __builtin_amdgcn_s_barrier()
; template <class Epi, class Sched>
; DI void gemm_phase(LAS unsigned char* lds, const int tid, const Gemm g, const Sched& S, const Epi& E) {
;     ...
;   for (;;) {
;     const bool has_next = S.next(ui + 1, nxt);
;     const char* nA = has_next ? (const char*)g.A + (size_t)nxt.pm * tstepA : cA; const char* nB = has_next ? (const char*)g.Bt + (size_t)nxt.pn * tstepB : cB;
; #pragma unroll 1
;     for (int t = 0; t < nt; t += 2) {
;       const bool last = (t == nt - 2);
;       const char* a1 = cA + (size_t)(t + 1) * kstep;
;       const char* a2 = last ? nA : cA + (size_t)(t + 2) * kstep; const char* b2 = last ? nB : cB + (size_t)(t + 2) * kstep;
;       const char* a3 = a2 + kstep; const char* b3 = b2 + kstep;
;       PG8_LDB(B0, 0, 0); PG8_SCHED; PG8_LDA(At, 0, 0); PG8_STAGE(PG8_SA(1, 1), a1 + hstepA, voffA);
;       PG8_WAIT_L(8); PG8_BAR; PG8_WAIT_L(0); PG8_MMA(0, 0, At, B0); PG8_BAR; PG8_SCHED;
;       PG8_LDB(B1, 0, 1); PG8_STAGE(PG8_SB(0, 0), b2, voffB);
;       PG8_BAR; PG8_WAIT_L(0); PG8_MMA(0, 1, At, B1); PG8_BAR;
;       PG8_LDA(At, 0, 1); PG8_STAGE(PG8_SA(0, 0), a2, voffA);
;       PG8_BAR; PG8_WAIT_L(0); PG8_MMA(1, 0, At, B0); PG8_BAR; PG8_SCHED;
;       PG8_STAGE(PG8_SB(0, 1), b2 + hstepB, voffB);
;       PG8_WAIT_V(6); PG8_BAR; PG8_MMA(1, 1, At, B1); PG8_BAR;
;       PG8_LDB(B0, 1, 0); PG8_SCHED; PG8_LDA(At, 1, 0); PG8_STAGE(PG8_SA(0, 1), a2 + hstepA, voffA);
;       PG8_WAIT_L(8); PG8_BAR; PG8_WAIT_L(0); PG8_MMA(0, 0, At, B0); PG8_BAR; PG8_SCHED;
.LBB0_447:
	s_add_u32 s14, s12, 0xfffc0080
	s_addc_u32 s15, s13, -1
	s_add_i32 s44, 0, 0x10000
	v_add_u32_e32 v0, s44, v142
	ds_read_b128 v[144:147], v0
	ds_read_b128 v[148:151], v0 offset:1024
	ds_read_b128 v[152:155], v0 offset:2048
	ds_read_b128 v[156:159], v0 offset:3072
	s_cmp_eq_u32 s43, 12
	s_cselect_b32 s17, s7, s15
	s_cselect_b32 s16, s39, s14
	s_cselect_b32 s15, s1, s42
	s_cselect_b32 s14, s40, s41
	s_add_i32 m0, s23, 0xc000
	ds_read_b128 v[160:163], v143
	ds_read_b128 v[164:167], v143 offset:1024
	ds_read_b128 v[168:171], v143 offset:2048
	ds_read_b128 v[172:175], v143 offset:3072
	ds_read_b128 v[176:179], v143 offset:4096
	ds_read_b128 v[180:183], v143 offset:5120
	ds_read_b128 v[202:205], v143 offset:6144
	ds_read_b128 v[206:209], v143 offset:7168
	global_load_lds_dwordx4 v140, s[12:13]
	s_add_i32 m0, s23, 0xe000
	s_nop 0
	global_load_lds_dwordx4 v138, s[12:13]
	s_waitcnt lgkmcnt(8)
	s_barrier
	s_waitcnt lgkmcnt(0)
	s_setprio 1
	v_mfma_f32_16x16x32_bf16 v[126:129], v[144:147], v[160:163], v[126:129]
	v_mfma_f32_16x16x32_bf16 v[122:125], v[152:155], v[160:163], v[122:125]
	v_mfma_f32_16x16x32_bf16 v[118:121], v[144:147], v[168:171], v[118:121]
	v_mfma_f32_16x16x32_bf16 v[114:117], v[152:155], v[168:171], v[114:117]
	v_mfma_f32_16x16x32_bf16 v[102:105], v[144:147], v[176:179], v[102:105]
	v_mfma_f32_16x16x32_bf16 v[98:101], v[152:155], v[176:179], v[98:101]
	v_mfma_f32_16x16x32_bf16 v[86:89], v[144:147], v[202:205], v[86:89]
	v_mfma_f32_16x16x32_bf16 v[82:85], v[152:155], v[202:205], v[82:85]
	v_mfma_f32_16x16x32_bf16 v[126:129], v[148:151], v[164:167], v[126:129]
	v_mfma_f32_16x16x32_bf16 v[122:125], v[156:159], v[164:167], v[122:125]
	v_mfma_f32_16x16x32_bf16 v[118:121], v[148:151], v[172:175], v[118:121]
	v_mfma_f32_16x16x32_bf16 v[114:117], v[156:159], v[172:175], v[114:117]
	v_mfma_f32_16x16x32_bf16 v[102:105], v[148:151], v[180:183], v[102:105]
	v_mfma_f32_16x16x32_bf16 v[98:101], v[156:159], v[180:183], v[98:101]
	v_mfma_f32_16x16x32_bf16 v[86:89], v[148:151], v[206:209], v[86:89]
	v_mfma_f32_16x16x32_bf16 v[82:85], v[156:159], v[206:209], v[82:85]
	s_setprio 0
	s_barrier
	s_add_i32 s48, 0, 0x14000
	s_add_i32 s44, s44, s22
	v_add_u32_e32 v0, s48, v142
	s_add_u32 s98, s14, s50
	s_addc_u32 s99, s15, s51
	s_mov_b32 m0, s44
	ds_read_b128 v[210:213], v0
	ds_read_b128 v[226:229], v0 offset:1024
	ds_read_b128 v[238:241], v0 offset:2048
	ds_read_b128 v[242:245], v0 offset:3072
	global_load_lds_dwordx4 v134, s[14:15]
	s_add_i32 m0, s44, 0x2000
	s_nop 0
	global_load_lds_dwordx4 v130, s[14:15]
	s_barrier
	s_waitcnt lgkmcnt(0)
	s_setprio 1
	v_mfma_f32_16x16x32_bf16 v[110:113], v[210:213], v[160:163], v[110:113]
	v_mfma_f32_16x16x32_bf16 v[106:109], v[238:241], v[160:163], v[106:109]
	v_mfma_f32_16x16x32_bf16 v[94:97], v[210:213], v[168:171], v[94:97]
	v_mfma_f32_16x16x32_bf16 v[90:93], v[238:241], v[168:171], v[90:93]
	v_mfma_f32_16x16x32_bf16 v[78:81], v[210:213], v[176:179], v[78:81]
	v_mfma_f32_16x16x32_bf16 v[74:77], v[238:241], v[176:179], v[74:77]
	v_mfma_f32_16x16x32_bf16 v[70:73], v[210:213], v[202:205], v[70:73]
	v_mfma_f32_16x16x32_bf16 v[66:69], v[238:241], v[202:205], v[66:69]
	v_mfma_f32_16x16x32_bf16 v[110:113], v[226:229], v[164:167], v[110:113]
	v_mfma_f32_16x16x32_bf16 v[106:109], v[242:245], v[164:167], v[106:109]
	v_mfma_f32_16x16x32_bf16 v[94:97], v[226:229], v[172:175], v[94:97]
	v_mfma_f32_16x16x32_bf16 v[90:93], v[242:245], v[172:175], v[90:93]
	v_mfma_f32_16x16x32_bf16 v[78:81], v[226:229], v[180:183], v[78:81]
	v_mfma_f32_16x16x32_bf16 v[74:77], v[242:245], v[180:183], v[74:77]
	v_mfma_f32_16x16x32_bf16 v[70:73], v[226:229], v[206:209], v[70:73]
	v_mfma_f32_16x16x32_bf16 v[66:69], v[242:245], v[206:209], v[66:69]
	s_setprio 0
	s_mov_b32 m0, s23
	s_add_u32 s100, s16, s50
	s_addc_u32 s101, s17, s51
	s_barrier
	ds_read_b128 v[160:163], v143 offset:16384
	ds_read_b128 v[164:167], v143 offset:17408
	ds_read_b128 v[168:171], v143 offset:18432
	ds_read_b128 v[172:175], v143 offset:19456
	ds_read_b128 v[176:179], v143 offset:20480
	ds_read_b128 v[180:183], v143 offset:21504
	ds_read_b128 v[202:205], v143 offset:22528
	ds_read_b128 v[206:209], v143 offset:23552
	global_load_lds_dwordx4 v136, s[16:17]
	s_mov_b32 m0, s24
	s_nop 0
	global_load_lds_dwordx4 v132, s[16:17]
	s_barrier
	s_waitcnt lgkmcnt(0)
	s_setprio 1
	v_mfma_f32_16x16x32_bf16 v[62:65], v[144:147], v[160:163], v[62:65]
	v_mfma_f32_16x16x32_bf16 v[58:61], v[152:155], v[160:163], v[58:61]
	v_mfma_f32_16x16x32_bf16 v[54:57], v[144:147], v[168:171], v[54:57]
	v_mfma_f32_16x16x32_bf16 v[50:53], v[152:155], v[168:171], v[50:53]
	v_mfma_f32_16x16x32_bf16 v[38:41], v[144:147], v[176:179], v[38:41]
	v_mfma_f32_16x16x32_bf16 v[34:37], v[152:155], v[176:179], v[34:37]
	v_mfma_f32_16x16x32_bf16 v[22:25], v[144:147], v[202:205], v[22:25]
	v_mfma_f32_16x16x32_bf16 v[18:21], v[152:155], v[202:205], v[18:21]
	v_mfma_f32_16x16x32_bf16 v[62:65], v[148:151], v[164:167], v[62:65]
	v_mfma_f32_16x16x32_bf16 v[58:61], v[156:159], v[164:167], v[58:61]
	v_mfma_f32_16x16x32_bf16 v[54:57], v[148:151], v[172:175], v[54:57]
	v_mfma_f32_16x16x32_bf16 v[50:53], v[156:159], v[172:175], v[50:53]
	v_mfma_f32_16x16x32_bf16 v[38:41], v[148:151], v[180:183], v[38:41]
	v_mfma_f32_16x16x32_bf16 v[34:37], v[156:159], v[180:183], v[34:37]
	v_mfma_f32_16x16x32_bf16 v[22:25], v[148:151], v[206:209], v[22:25]
	v_mfma_f32_16x16x32_bf16 v[18:21], v[156:159], v[206:209], v[18:21]
	s_setprio 0
	s_barrier
	s_add_u32 s46, s14, 0x40000
	s_addc_u32 s47, s15, 0
	s_add_i32 s44, s48, s22
	s_mov_b32 m0, s44
	s_nop 0
	global_load_lds_dwordx4 v134, s[46:47]
	s_add_i32 m0, s44, 0x2000
	s_nop 0
	global_load_lds_dwordx4 v130, s[46:47]
	s_waitcnt vmcnt(6)
	s_barrier
; #define PG8_STAGE(bufoff, gbase, voff) do { _Pragma("unroll") for (int _i = 0; _i < 2; ++_i) \
;     __builtin_amdgcn_global_load_lds((const unsigned*)((const char*)(gbase) + (voff)[_i]), (LAS unsigned*)(lds + (bufoff) + ldsw + _i * 8192), 16, 0, 0); } while (0)
; #define PG8_LDA(dst, b, h) do { _Pragma("unroll") for (int m = 0; m < 4; ++m) _Pragma("unroll") for (int k = 0; k < 2; ++k) dst[m][k] = *(const LAS bf16x8*)(lds + PG8_SA(b, h) + aoff + m * 2048 + k * 1024); } while (0)
; #define PG8_LDB(dst, b, h) do { _Pragma("unroll") for (int n = 0; n < 2; ++n) _Pragma("unroll") for (int k = 0; k < 2; ++k) dst[n][k] = *(const LAS bf16x8*)(lds + PG8_SB(b, h) + boff + n * 2048 + k * 1024); } while (0)
; #define PG8_MMA(ai, bj, At, Bt) do { __builtin_amdgcn_s_setprio(1); _Pragma("unroll") for (int m = 0; m < 4; ++m) _Pragma("unroll") for (int n = 0; n < 2; ++n) _Pragma("unroll") for (int k = 0; k < 2; ++k) \
;     acc[ai][bj][m][n] = __builtin_amdgcn_mfma_f32_16x16x32_bf16(Bt[n][k], At[m][k], acc[ai][bj][m][n], 0, 0, 0); __builtin_amdgcn_s_setprio(0); } while (0)
; #define PG8_WAIT_V(n) asm volatile("s_waitcnt vmcnt(" #n ")" ::: "memory")
; #define PG8_WAIT_L(n) asm volatile("s_waitcnt lgkmcnt(" #n ")" ::: "memory")
; #define PG8_BAR __builtin_amdgcn_s_barrier()
; #define PG8_SCHED __builtin_amdgcn_sched_barrier(0)
; template <class Epi, class Sched>
; DI void gemm_phase(LAS unsigned char* lds, const int tid, const Gemm g, const Sched& S, const Epi& E) {
;     ...
;       PG8_WAIT_V(6); PG8_BAR; PG8_MMA(1, 1, At, B1); PG8_BAR;
;       PG8_LDB(B0, 1, 0); PG8_SCHED; PG8_LDA(At, 1, 0); PG8_STAGE(PG8_SA(0, 1), a2 + hstepA, voffA);
;       PG8_WAIT_L(8); PG8_BAR; PG8_WAIT_L(0); PG8_MMA(0, 0, At, B0); PG8_BAR; PG8_SCHED;
;       PG8_LDB(B1, 1, 1); PG8_STAGE(PG8_SB(1, 0), b3, voffB);
;       PG8_BAR; PG8_WAIT_L(0); PG8_MMA(0, 1, At, B1); PG8_BAR;
;       PG8_LDA(At, 1, 1); PG8_STAGE(PG8_SA(1, 0), a3, voffA);
;       PG8_BAR; PG8_WAIT_L(0); PG8_MMA(1, 0, At, B0); PG8_BAR; PG8_SCHED;
	s_setprio 1
	v_mfma_f32_16x16x32_bf16 v[46:49], v[210:213], v[160:163], v[46:49]
	v_mfma_f32_16x16x32_bf16 v[42:45], v[238:241], v[160:163], v[42:45]
	v_mfma_f32_16x16x32_bf16 v[30:33], v[210:213], v[168:171], v[30:33]
	v_mfma_f32_16x16x32_bf16 v[26:29], v[238:241], v[168:171], v[26:29]
	v_mfma_f32_16x16x32_bf16 v[14:17], v[210:213], v[176:179], v[14:17]
	v_mfma_f32_16x16x32_bf16 v[10:13], v[238:241], v[176:179], v[10:13]
	v_mfma_f32_16x16x32_bf16 v[6:9], v[210:213], v[202:205], v[6:9]
	v_mfma_f32_16x16x32_bf16 v[2:5], v[238:241], v[202:205], v[2:5]
	v_mfma_f32_16x16x32_bf16 v[46:49], v[226:229], v[164:167], v[46:49]
	v_mfma_f32_16x16x32_bf16 v[42:45], v[242:245], v[164:167], v[42:45]
	v_mfma_f32_16x16x32_bf16 v[30:33], v[226:229], v[172:175], v[30:33]
	v_mfma_f32_16x16x32_bf16 v[26:29], v[242:245], v[172:175], v[26:29]
	v_mfma_f32_16x16x32_bf16 v[14:17], v[226:229], v[180:183], v[14:17]
	v_mfma_f32_16x16x32_bf16 v[10:13], v[242:245], v[180:183], v[10:13]
	v_mfma_f32_16x16x32_bf16 v[6:9], v[226:229], v[206:209], v[6:9]
	v_mfma_f32_16x16x32_bf16 v[2:5], v[242:245], v[206:209], v[2:5]
	s_setprio 0
	s_add_i32 s44, 0, 0x18000
	v_add_u32_e32 v0, s44, v142
	s_barrier
	ds_read_b128 v[144:147], v0
	ds_read_b128 v[148:151], v0 offset:1024
	ds_read_b128 v[152:155], v0 offset:2048
	ds_read_b128 v[156:159], v0 offset:3072
	s_add_u32 s16, s16, 0x40000
	s_addc_u32 s17, s17, 0
	s_mov_b32 m0, s25
	ds_read_b128 v[160:163], v143 offset:32768
	ds_read_b128 v[164:167], v143 offset:33792
	ds_read_b128 v[168:171], v143 offset:34816
	ds_read_b128 v[172:175], v143 offset:35840
	ds_read_b128 v[176:179], v143 offset:36864
	ds_read_b128 v[180:183], v143 offset:37888
	ds_read_b128 v[202:205], v143 offset:38912
	ds_read_b128 v[206:209], v143 offset:39936
	global_load_lds_dwordx4 v136, s[16:17]
	s_mov_b32 m0, s26
	s_nop 0
	global_load_lds_dwordx4 v132, s[16:17]
	s_waitcnt lgkmcnt(8)
	s_barrier
	s_waitcnt lgkmcnt(0)
	s_setprio 1
	v_mfma_f32_16x16x32_bf16 v[126:129], v[144:147], v[160:163], v[126:129]
	v_mfma_f32_16x16x32_bf16 v[122:125], v[152:155], v[160:163], v[122:125]
	v_mfma_f32_16x16x32_bf16 v[118:121], v[144:147], v[168:171], v[118:121]
	v_mfma_f32_16x16x32_bf16 v[114:117], v[152:155], v[168:171], v[114:117]
	v_mfma_f32_16x16x32_bf16 v[102:105], v[144:147], v[176:179], v[102:105]
	v_mfma_f32_16x16x32_bf16 v[98:101], v[152:155], v[176:179], v[98:101]
	v_mfma_f32_16x16x32_bf16 v[86:89], v[144:147], v[202:205], v[86:89]
	v_mfma_f32_16x16x32_bf16 v[82:85], v[152:155], v[202:205], v[82:85]
	v_mfma_f32_16x16x32_bf16 v[126:129], v[148:151], v[164:167], v[126:129]
	v_mfma_f32_16x16x32_bf16 v[122:125], v[156:159], v[164:167], v[122:125]
	v_mfma_f32_16x16x32_bf16 v[118:121], v[148:151], v[172:175], v[118:121]
	v_mfma_f32_16x16x32_bf16 v[114:117], v[156:159], v[172:175], v[114:117]
	v_mfma_f32_16x16x32_bf16 v[102:105], v[148:151], v[180:183], v[102:105]
	v_mfma_f32_16x16x32_bf16 v[98:101], v[156:159], v[180:183], v[98:101]
	v_mfma_f32_16x16x32_bf16 v[86:89], v[148:151], v[206:209], v[86:89]
	v_mfma_f32_16x16x32_bf16 v[82:85], v[156:159], v[206:209], v[82:85]
	s_setprio 0
	s_barrier
	s_add_i32 s16, 0, 0x1c000
	s_add_i32 s17, s44, s22
	v_add_u32_e32 v0, s16, v142
	s_mov_b32 m0, s17
	ds_read_b128 v[210:213], v0
	ds_read_b128 v[226:229], v0 offset:1024
	ds_read_b128 v[238:241], v0 offset:2048
	ds_read_b128 v[242:245], v0 offset:3072
	global_load_lds_dwordx4 v134, s[98:99]
	s_add_i32 m0, s17, 0x2000
	s_nop 0
	global_load_lds_dwordx4 v130, s[98:99]
	s_barrier
; #define PG8_STAGE(bufoff, gbase, voff) do { _Pragma("unroll") for (int _i = 0; _i < 2; ++_i) \
;     __builtin_amdgcn_global_load_lds((const unsigned*)((const char*)(gbase) + (voff)[_i]), (LAS unsigned*)(lds + (bufoff) + ldsw + _i * 8192), 16, 0, 0); } while (0)
; #define PG8_LDA(dst, b, h) do { _Pragma("unroll") for (int m = 0; m < 4; ++m) _Pragma("unroll") for (int k = 0; k < 2; ++k) dst[m][k] = *(const LAS bf16x8*)(lds + PG8_SA(b, h) + aoff + m * 2048 + k * 1024); } while (0)
; #define PG8_LDB(dst, b, h) do { _Pragma("unroll") for (int n = 0; n < 2; ++n) _Pragma("unroll") for (int k = 0; k < 2; ++k) dst[n][k] = *(const LAS bf16x8*)(lds + PG8_SB(b, h) + boff + n * 2048 + k * 1024); } while (0)
; #define PG8_MMA(ai, bj, At, Bt) do { __builtin_amdgcn_s_setprio(1); _Pragma("unroll") for (int m = 0; m < 4; ++m) _Pragma("unroll") for (int n = 0; n < 2; ++n) _Pragma("unroll") for (int k = 0; k < 2; ++k) \
;     acc[ai][bj][m][n] = __builtin_amdgcn_mfma_f32_16x16x32_bf16(Bt[n][k], At[m][k], acc[ai][bj][m][n], 0, 0, 0); __builtin_amdgcn_s_setprio(0); } while (0)
; #define PG8_WAIT_V(n) asm volatile("s_waitcnt vmcnt(" #n ")" ::: "memory")
; template <class Epi, class Sched>
; DI void gemm_phase(LAS unsigned char* lds, const int tid, const Gemm g, const Sched& S, const Epi& E) {
;     ...
;       PG8_WAIT_L(8); PG8_BAR; PG8_WAIT_L(0); PG8_MMA(0, 0, At, B0); PG8_BAR; PG8_SCHED;
;       PG8_LDB(B1, 1, 1); PG8_STAGE(PG8_SB(1, 0), b3, voffB);
;       PG8_BAR; PG8_WAIT_L(0); PG8_MMA(0, 1, At, B1); PG8_BAR;
;       PG8_LDA(At, 1, 1); PG8_STAGE(PG8_SA(1, 0), a3, voffA);
;       PG8_BAR; PG8_WAIT_L(0); PG8_MMA(1, 0, At, B0); PG8_BAR; PG8_SCHED;
;       PG8_STAGE(PG8_SB(1, 1), b3 + hstepB, voffB);
;       PG8_WAIT_V(6); PG8_BAR; PG8_MMA(1, 1, At, B1); PG8_BAR;
;     }
;     { int z_e = 0; asm volatile("" : "+v"(z_e)); const int lane_e = __builtin_amdgcn_mbcnt_hi(~0u, __builtin_amdgcn_mbcnt_lo(~0u, (unsigned)z_e));
;       E(acc, cur, wr, wc, lane_e & 15, lane_e >> 4); }
;     if (!has_next) break;
;   DI void operator()(const AccT& acc, const Unit& u, int wr, int wc, int fr, int fq) const {
;     const bool lat = u.pn < 128;
;     const int ld = lat ? 4096 : 512, snoff = lat ? 2048 : 256;
;     const char* base = (const char*)((lat ? ZTL + ((size_t)(u.pn >> 3) * 256 * 4096 + (u.pn & 7) * 256) : ZTC + (size_t)(u.pn - 128) * 256 * 512) + (size_t)(u.pm * 128) * ld + wr * snoff);
	s_waitcnt lgkmcnt(0)
	s_setprio 1
	v_mfma_f32_16x16x32_bf16 v[110:113], v[210:213], v[160:163], v[110:113]
	v_mfma_f32_16x16x32_bf16 v[106:109], v[238:241], v[160:163], v[106:109]
	v_mfma_f32_16x16x32_bf16 v[94:97], v[210:213], v[168:171], v[94:97]
	v_mfma_f32_16x16x32_bf16 v[90:93], v[238:241], v[168:171], v[90:93]
	v_mfma_f32_16x16x32_bf16 v[78:81], v[210:213], v[176:179], v[78:81]
	v_mfma_f32_16x16x32_bf16 v[74:77], v[238:241], v[176:179], v[74:77]
	v_mfma_f32_16x16x32_bf16 v[70:73], v[210:213], v[202:205], v[70:73]
	v_mfma_f32_16x16x32_bf16 v[66:69], v[238:241], v[202:205], v[66:69]
	v_mfma_f32_16x16x32_bf16 v[110:113], v[226:229], v[164:167], v[110:113]
	v_mfma_f32_16x16x32_bf16 v[106:109], v[242:245], v[164:167], v[106:109]
	v_mfma_f32_16x16x32_bf16 v[94:97], v[226:229], v[172:175], v[94:97]
	v_mfma_f32_16x16x32_bf16 v[90:93], v[242:245], v[172:175], v[90:93]
	v_mfma_f32_16x16x32_bf16 v[78:81], v[226:229], v[180:183], v[78:81]
	v_mfma_f32_16x16x32_bf16 v[74:77], v[242:245], v[180:183], v[74:77]
	v_mfma_f32_16x16x32_bf16 v[70:73], v[226:229], v[206:209], v[70:73]
	v_mfma_f32_16x16x32_bf16 v[66:69], v[242:245], v[206:209], v[66:69]
	s_setprio 0
	s_mov_b32 m0, s31
	s_barrier
	ds_read_b128 v[160:163], v143 offset:49152
	ds_read_b128 v[164:167], v143 offset:50176
	ds_read_b128 v[168:171], v143 offset:51200
	ds_read_b128 v[172:175], v143 offset:52224
	ds_read_b128 v[176:179], v143 offset:53248
	ds_read_b128 v[180:183], v143 offset:54272
	ds_read_b128 v[202:205], v143 offset:55296
	ds_read_b128 v[206:209], v143 offset:56320
	global_load_lds_dwordx4 v136, s[100:101]
	s_mov_b32 m0, s34
	s_nop 0
	global_load_lds_dwordx4 v132, s[100:101]
	s_barrier
	s_waitcnt lgkmcnt(0)
	s_setprio 1
	v_mfma_f32_16x16x32_bf16 v[62:65], v[144:147], v[160:163], v[62:65]
	v_mfma_f32_16x16x32_bf16 v[58:61], v[152:155], v[160:163], v[58:61]
	v_mfma_f32_16x16x32_bf16 v[54:57], v[144:147], v[168:171], v[54:57]
	v_mfma_f32_16x16x32_bf16 v[50:53], v[152:155], v[168:171], v[50:53]
	v_mfma_f32_16x16x32_bf16 v[38:41], v[144:147], v[176:179], v[38:41]
	v_mfma_f32_16x16x32_bf16 v[34:37], v[152:155], v[176:179], v[34:37]
	v_mfma_f32_16x16x32_bf16 v[22:25], v[144:147], v[202:205], v[22:25]
	v_mfma_f32_16x16x32_bf16 v[18:21], v[152:155], v[202:205], v[18:21]
	v_mfma_f32_16x16x32_bf16 v[62:65], v[148:151], v[164:167], v[62:65]
	v_mfma_f32_16x16x32_bf16 v[58:61], v[156:159], v[164:167], v[58:61]
	v_mfma_f32_16x16x32_bf16 v[54:57], v[148:151], v[172:175], v[54:57]
	v_mfma_f32_16x16x32_bf16 v[50:53], v[156:159], v[172:175], v[50:53]
	v_mfma_f32_16x16x32_bf16 v[38:41], v[148:151], v[180:183], v[38:41]
	v_mfma_f32_16x16x32_bf16 v[34:37], v[156:159], v[180:183], v[34:37]
	v_mfma_f32_16x16x32_bf16 v[22:25], v[148:151], v[206:209], v[22:25]
	v_mfma_f32_16x16x32_bf16 v[18:21], v[156:159], v[206:209], v[18:21]
	s_setprio 0
	s_barrier
	s_add_u32 s14, s14, 0x40080
	s_addc_u32 s15, s15, 0
	s_add_i32 s16, s16, s22
	s_mov_b32 m0, s16
	s_nop 0
	global_load_lds_dwordx4 v134, s[14:15]
	s_add_i32 m0, s16, 0x2000
	s_nop 0
	global_load_lds_dwordx4 v130, s[14:15]
	s_waitcnt vmcnt(6)
	s_barrier
	s_setprio 1
	v_mfma_f32_16x16x32_bf16 v[46:49], v[210:213], v[160:163], v[46:49]
	v_mfma_f32_16x16x32_bf16 v[42:45], v[238:241], v[160:163], v[42:45]
	v_mfma_f32_16x16x32_bf16 v[30:33], v[210:213], v[168:171], v[30:33]
	v_mfma_f32_16x16x32_bf16 v[26:29], v[238:241], v[168:171], v[26:29]
	v_mfma_f32_16x16x32_bf16 v[14:17], v[210:213], v[176:179], v[14:17]
	v_mfma_f32_16x16x32_bf16 v[10:13], v[238:241], v[176:179], v[10:13]
	v_mfma_f32_16x16x32_bf16 v[6:9], v[210:213], v[202:205], v[6:9]
	v_mfma_f32_16x16x32_bf16 v[2:5], v[238:241], v[202:205], v[2:5]
	v_mfma_f32_16x16x32_bf16 v[46:49], v[226:229], v[164:167], v[46:49]
	v_mfma_f32_16x16x32_bf16 v[42:45], v[242:245], v[164:167], v[42:45]
	v_mfma_f32_16x16x32_bf16 v[30:33], v[226:229], v[172:175], v[30:33]
	v_mfma_f32_16x16x32_bf16 v[26:29], v[242:245], v[172:175], v[26:29]
	v_mfma_f32_16x16x32_bf16 v[14:17], v[226:229], v[180:183], v[14:17]
	v_mfma_f32_16x16x32_bf16 v[10:13], v[242:245], v[180:183], v[10:13]
	v_mfma_f32_16x16x32_bf16 v[6:9], v[226:229], v[206:209], v[6:9]
	v_mfma_f32_16x16x32_bf16 v[2:5], v[242:245], v[206:209], v[2:5]
	s_setprio 0
	s_add_i32 s43, s43, 2
	s_add_u32 s41, s41, 0x100
	s_addc_u32 s42, s42, 0
	s_add_u32 s12, s12, 0x100
	s_addc_u32 s13, s13, 0
	s_cmp_gt_u32 s43, 13
	s_barrier
	s_cbranch_scc0 .LBB0_447
	v_mov_b32_e32 v0, v1
	s_cmpk_gt_i32 s38, 0x7f
	s_mov_b64 s[14:15], -1
	s_cbranch_scc0 .LBB0_450
	s_add_i32 s96, s38, 0xffffff80
	s_lshl_b64 s[12:13], s[96:97], 18
	s_add_u32 s12, s29, s12
	s_addc_u32 s13, s30, s13
	s_mov_b64 s[14:15], 0

; #define PG8_STAGE(bufoff, gbase, voff) do { _Pragma("unroll") for (int _i = 0; _i < 2; ++_i) \
;     __builtin_amdgcn_global_load_lds((const unsigned*)((const char*)(gbase) + (voff)[_i]), (LAS unsigned*)(lds + (bufoff) + ldsw + _i * 8192), 16, 0, 0); } while (0)
; #define PG8_LDA(dst, b, h) do { _Pragma("unroll") for (int m = 0; m < 4; ++m) _Pragma("unroll") for (int k = 0; k < 2; ++k) dst[m][k] = *(const LAS bf16x8*)(lds + PG8_SA(b, h) + aoff + m * 2048 + k * 1024); } while (0)
; #define PG8_LDB(dst, b, h) do { _Pragma("unroll") for (int n = 0; n < 2; ++n) _Pragma("unroll") for (int k = 0; k < 2; ++k) dst[n][k] = *(const LAS bf16x8*)(lds + PG8_SB(b, h) + boff + n * 2048 + k * 1024); } while (0)
; #define PG8_MMA(ai, bj, At, Bt) do { __builtin_amdgcn_s_setprio(1); _Pragma("unroll") for (int m = 0; m < 4; ++m) _Pragma("unroll") for (int n = 0; n < 2; ++n) _Pragma("unroll") for (int k = 0; k < 2; ++k) \
;     acc[ai][bj][m][n] = __builtin_amdgcn_mfma_f32_16x16x32_bf16(Bt[n][k], At[m][k], acc[ai][bj][m][n], 0, 0, 0); __builtin_amdgcn_s_setprio(0); } while (0)
; #define PG8_WAIT_L(n) asm volatile("s_waitcnt lgkmcnt(" #n ")" ::: "memory")
; #define PG8_BAR __builtin_amdgcn_s_barrier()
; template <class Epi, class Sched>
; DI void gemm_phase(LAS unsigned char* lds, const int tid, const Gemm g, const Sched& S, const Epi& E) {
;     ...
;   for (;;) {
;     const bool has_next = S.next(ui + 1, nxt);
;     const char* nA = has_next ? (const char*)g.A + (size_t)nxt.pm * tstepA : cA; const char* nB = has_next ? (const char*)g.Bt + (size_t)nxt.pn * tstepB : cB;
; #pragma unroll 1
;     for (int t = 0; t < nt; t += 2) {
;       const bool last = (t == nt - 2);
;       const char* a1 = cA + (size_t)(t + 1) * kstep;
;       const char* a2 = last ? nA : cA + (size_t)(t + 2) * kstep; const char* b2 = last ? nB : cB + (size_t)(t + 2) * kstep;
;       const char* a3 = a2 + kstep; const char* b3 = b2 + kstep;
;       PG8_LDB(B0, 0, 0); PG8_SCHED; PG8_LDA(At, 0, 0); PG8_STAGE(PG8_SA(1, 1), a1 + hstepA, voffA);
;       PG8_WAIT_L(8); PG8_BAR; PG8_WAIT_L(0); PG8_MMA(0, 0, At, B0); PG8_BAR; PG8_SCHED;
;       PG8_LDB(B1, 0, 1); PG8_STAGE(PG8_SB(0, 0), b2, voffB);
;       PG8_BAR; PG8_WAIT_L(0); PG8_MMA(0, 1, At, B1); PG8_BAR;
;       PG8_LDA(At, 0, 1); PG8_STAGE(PG8_SA(0, 0), a2, voffA);
;       PG8_BAR; PG8_WAIT_L(0); PG8_MMA(1, 0, At, B0); PG8_BAR; PG8_SCHED;
.LBB0_467:
	s_add_u32 s14, s0, 0xfffc0080
	s_addc_u32 s15, s1, -1
	s_add_i32 s39, 0, 0x10000
	v_add_u32_e32 v0, s39, v239
	ds_read_b128 v[130:133], v0
	ds_read_b128 v[134:137], v0 offset:1024
	ds_read_b128 v[138:141], v0 offset:2048
	ds_read_b128 v[142:145], v0 offset:3072
	s_cmp_eq_u32 s38, 12
	s_cselect_b32 s31, s7, s15
	s_cselect_b32 s30, s9, s14
	s_cselect_b32 s15, s23, s35
	s_cselect_b32 s14, s25, s34
	s_add_i32 m0, s41, 0xc000
	ds_read_b128 v[146:149], v241
	ds_read_b128 v[150:153], v241 offset:1024
	ds_read_b128 v[154:157], v241 offset:2048
	ds_read_b128 v[158:161], v241 offset:3072
	ds_read_b128 v[162:165], v241 offset:4096
	ds_read_b128 v[166:169], v241 offset:5120
	ds_read_b128 v[170:173], v241 offset:6144
	ds_read_b128 v[174:177], v241 offset:7168
	global_load_lds_dwordx4 v208, s[0:1]
	s_add_i32 m0, s41, 0xe000
	s_nop 0
	global_load_lds_dwordx4 v206, s[0:1]
	s_waitcnt lgkmcnt(8)
	s_barrier
	s_waitcnt lgkmcnt(0)
	s_setprio 1
	v_mfma_f32_16x16x32_bf16 v[126:129], v[130:133], v[146:149], v[126:129]
	v_mfma_f32_16x16x32_bf16 v[122:125], v[138:141], v[146:149], v[122:125]
	v_mfma_f32_16x16x32_bf16 v[110:113], v[130:133], v[154:157], v[110:113]
	v_mfma_f32_16x16x32_bf16 v[106:109], v[138:141], v[154:157], v[106:109]
	v_mfma_f32_16x16x32_bf16 v[94:97], v[130:133], v[162:165], v[94:97]
	v_mfma_f32_16x16x32_bf16 v[90:93], v[138:141], v[162:165], v[90:93]
	v_mfma_f32_16x16x32_bf16 v[78:81], v[130:133], v[170:173], v[78:81]
	v_mfma_f32_16x16x32_bf16 v[74:77], v[138:141], v[170:173], v[74:77]
	v_mfma_f32_16x16x32_bf16 v[126:129], v[134:137], v[150:153], v[126:129]
	v_mfma_f32_16x16x32_bf16 v[122:125], v[142:145], v[150:153], v[122:125]
	v_mfma_f32_16x16x32_bf16 v[110:113], v[134:137], v[158:161], v[110:113]
	v_mfma_f32_16x16x32_bf16 v[106:109], v[142:145], v[158:161], v[106:109]
	v_mfma_f32_16x16x32_bf16 v[94:97], v[134:137], v[166:169], v[94:97]
	v_mfma_f32_16x16x32_bf16 v[90:93], v[142:145], v[166:169], v[90:93]
	v_mfma_f32_16x16x32_bf16 v[78:81], v[134:137], v[174:177], v[78:81]
	v_mfma_f32_16x16x32_bf16 v[74:77], v[142:145], v[174:177], v[74:77]
	s_setprio 0
	s_barrier
	s_add_i32 s79, 0, 0x14000
	s_add_i32 s39, s39, s40
	v_add_u32_e32 v0, s79, v239
	s_add_u32 s98, s14, s50
	s_addc_u32 s99, s15, s51
	s_mov_b32 m0, s39
	ds_read_b128 v[178:181], v0
	ds_read_b128 v[182:185], v0 offset:1024
	ds_read_b128 v[210:213], v0 offset:2048
	ds_read_b128 v[226:229], v0 offset:3072
	global_load_lds_dwordx4 v202, s[14:15]
	s_add_i32 m0, s39, 0x2000
	s_nop 0
	global_load_lds_dwordx4 v204, s[14:15]
	s_barrier
	s_waitcnt lgkmcnt(0)
	s_setprio 1
	v_mfma_f32_16x16x32_bf16 v[118:121], v[178:181], v[146:149], v[118:121]
	v_mfma_f32_16x16x32_bf16 v[114:117], v[210:213], v[146:149], v[114:117]
	v_mfma_f32_16x16x32_bf16 v[102:105], v[178:181], v[154:157], v[102:105]
	v_mfma_f32_16x16x32_bf16 v[98:101], v[210:213], v[154:157], v[98:101]
	v_mfma_f32_16x16x32_bf16 v[86:89], v[178:181], v[162:165], v[86:89]
	v_mfma_f32_16x16x32_bf16 v[82:85], v[210:213], v[162:165], v[82:85]
	v_mfma_f32_16x16x32_bf16 v[70:73], v[178:181], v[170:173], v[70:73]
	v_mfma_f32_16x16x32_bf16 v[66:69], v[210:213], v[170:173], v[66:69]
	v_mfma_f32_16x16x32_bf16 v[118:121], v[182:185], v[150:153], v[118:121]
	v_mfma_f32_16x16x32_bf16 v[114:117], v[226:229], v[150:153], v[114:117]
	v_mfma_f32_16x16x32_bf16 v[102:105], v[182:185], v[158:161], v[102:105]
	v_mfma_f32_16x16x32_bf16 v[98:101], v[226:229], v[158:161], v[98:101]
	v_mfma_f32_16x16x32_bf16 v[86:89], v[182:185], v[166:169], v[86:89]
	v_mfma_f32_16x16x32_bf16 v[82:85], v[226:229], v[166:169], v[82:85]
	v_mfma_f32_16x16x32_bf16 v[70:73], v[182:185], v[174:177], v[70:73]
	v_mfma_f32_16x16x32_bf16 v[66:69], v[226:229], v[174:177], v[66:69]
	s_setprio 0
	s_mov_b32 m0, s41
	s_add_u32 s100, s30, s50
	s_addc_u32 s101, s31, s51
	s_barrier
	ds_read_b128 v[146:149], v241 offset:16384
	ds_read_b128 v[150:153], v241 offset:17408
	ds_read_b128 v[154:157], v241 offset:18432
	ds_read_b128 v[158:161], v241 offset:19456
	ds_read_b128 v[162:165], v241 offset:20480
	ds_read_b128 v[166:169], v241 offset:21504
	ds_read_b128 v[170:173], v241 offset:22528
	ds_read_b128 v[174:177], v241 offset:23552
	global_load_lds_dwordx4 v202, s[30:31]
	s_mov_b32 m0, s42
	s_nop 0
	global_load_lds_dwordx4 v204, s[30:31]
	s_barrier
	s_waitcnt lgkmcnt(0)
	s_setprio 1
	v_mfma_f32_16x16x32_bf16 v[62:65], v[130:133], v[146:149], v[62:65]
	v_mfma_f32_16x16x32_bf16 v[58:61], v[138:141], v[146:149], v[58:61]
	v_mfma_f32_16x16x32_bf16 v[46:49], v[130:133], v[154:157], v[46:49]
	v_mfma_f32_16x16x32_bf16 v[42:45], v[138:141], v[154:157], v[42:45]
	v_mfma_f32_16x16x32_bf16 v[30:33], v[130:133], v[162:165], v[30:33]
	v_mfma_f32_16x16x32_bf16 v[26:29], v[138:141], v[162:165], v[26:29]
	v_mfma_f32_16x16x32_bf16 v[14:17], v[130:133], v[170:173], v[14:17]
	v_mfma_f32_16x16x32_bf16 v[10:13], v[138:141], v[170:173], v[10:13]
	v_mfma_f32_16x16x32_bf16 v[62:65], v[134:137], v[150:153], v[62:65]
	v_mfma_f32_16x16x32_bf16 v[58:61], v[142:145], v[150:153], v[58:61]
	v_mfma_f32_16x16x32_bf16 v[46:49], v[134:137], v[158:161], v[46:49]
	v_mfma_f32_16x16x32_bf16 v[42:45], v[142:145], v[158:161], v[42:45]
	v_mfma_f32_16x16x32_bf16 v[30:33], v[134:137], v[166:169], v[30:33]
	v_mfma_f32_16x16x32_bf16 v[26:29], v[142:145], v[166:169], v[26:29]
	v_mfma_f32_16x16x32_bf16 v[14:17], v[134:137], v[174:177], v[14:17]
	v_mfma_f32_16x16x32_bf16 v[10:13], v[142:145], v[174:177], v[10:13]
	s_setprio 0
	s_barrier
	s_add_u32 s82, s14, 0x40000
	s_addc_u32 s83, s15, 0
	s_add_i32 s39, s79, s40
	s_mov_b32 m0, s39
	s_nop 0
	global_load_lds_dwordx4 v202, s[82:83]
	s_add_i32 m0, s39, 0x2000
	s_nop 0
	global_load_lds_dwordx4 v204, s[82:83]
	s_waitcnt vmcnt(6)
	s_barrier
; #define PG8_STAGE(bufoff, gbase, voff) do { _Pragma("unroll") for (int _i = 0; _i < 2; ++_i) \
;     __builtin_amdgcn_global_load_lds((const unsigned*)((const char*)(gbase) + (voff)[_i]), (LAS unsigned*)(lds + (bufoff) + ldsw + _i * 8192), 16, 0, 0); } while (0)
; #define PG8_LDA(dst, b, h) do { _Pragma("unroll") for (int m = 0; m < 4; ++m) _Pragma("unroll") for (int k = 0; k < 2; ++k) dst[m][k] = *(const LAS bf16x8*)(lds + PG8_SA(b, h) + aoff + m * 2048 + k * 1024); } while (0)
; #define PG8_LDB(dst, b, h) do { _Pragma("unroll") for (int n = 0; n < 2; ++n) _Pragma("unroll") for (int k = 0; k < 2; ++k) dst[n][k] = *(const LAS bf16x8*)(lds + PG8_SB(b, h) + boff + n * 2048 + k * 1024); } while (0)
; #define PG8_MMA(ai, bj, At, Bt) do { __builtin_amdgcn_s_setprio(1); _Pragma("unroll") for (int m = 0; m < 4; ++m) _Pragma("unroll") for (int n = 0; n < 2; ++n) _Pragma("unroll") for (int k = 0; k < 2; ++k) \
;     acc[ai][bj][m][n] = __builtin_amdgcn_mfma_f32_16x16x32_bf16(Bt[n][k], At[m][k], acc[ai][bj][m][n], 0, 0, 0); __builtin_amdgcn_s_setprio(0); } while (0)
; #define PG8_WAIT_V(n) asm volatile("s_waitcnt vmcnt(" #n ")" ::: "memory")
; #define PG8_WAIT_L(n) asm volatile("s_waitcnt lgkmcnt(" #n ")" ::: "memory")
; #define PG8_BAR __builtin_amdgcn_s_barrier()
; #define PG8_SCHED __builtin_amdgcn_sched_barrier(0)
; template <class Epi, class Sched>
; DI void gemm_phase(LAS unsigned char* lds, const int tid, const Gemm g, const Sched& S, const Epi& E) {
;     ...
;       PG8_WAIT_V(6); PG8_BAR; PG8_MMA(1, 1, At, B1); PG8_BAR;
;       PG8_LDB(B0, 1, 0); PG8_SCHED; PG8_LDA(At, 1, 0); PG8_STAGE(PG8_SA(0, 1), a2 + hstepA, voffA);
;       PG8_WAIT_L(8); PG8_BAR; PG8_WAIT_L(0); PG8_MMA(0, 0, At, B0); PG8_BAR; PG8_SCHED;
;       PG8_LDB(B1, 1, 1); PG8_STAGE(PG8_SB(1, 0), b3, voffB);
;       PG8_BAR; PG8_WAIT_L(0); PG8_MMA(0, 1, At, B1); PG8_BAR;
;       PG8_LDA(At, 1, 1); PG8_STAGE(PG8_SA(1, 0), a3, voffA);
;       PG8_BAR; PG8_WAIT_L(0); PG8_MMA(1, 0, At, B0); PG8_BAR; PG8_SCHED;
	s_setprio 1
	v_mfma_f32_16x16x32_bf16 v[54:57], v[178:181], v[146:149], v[54:57]
	v_mfma_f32_16x16x32_bf16 v[50:53], v[210:213], v[146:149], v[50:53]
	v_mfma_f32_16x16x32_bf16 v[38:41], v[178:181], v[154:157], v[38:41]
	v_mfma_f32_16x16x32_bf16 v[34:37], v[210:213], v[154:157], v[34:37]
	v_mfma_f32_16x16x32_bf16 v[22:25], v[178:181], v[162:165], v[22:25]
	v_mfma_f32_16x16x32_bf16 v[18:21], v[210:213], v[162:165], v[18:21]
	v_mfma_f32_16x16x32_bf16 v[6:9], v[178:181], v[170:173], v[6:9]
	v_mfma_f32_16x16x32_bf16 v[2:5], v[210:213], v[170:173], v[2:5]
	v_mfma_f32_16x16x32_bf16 v[54:57], v[182:185], v[150:153], v[54:57]
	v_mfma_f32_16x16x32_bf16 v[50:53], v[226:229], v[150:153], v[50:53]
	v_mfma_f32_16x16x32_bf16 v[38:41], v[182:185], v[158:161], v[38:41]
	v_mfma_f32_16x16x32_bf16 v[34:37], v[226:229], v[158:161], v[34:37]
	v_mfma_f32_16x16x32_bf16 v[22:25], v[182:185], v[166:169], v[22:25]
	v_mfma_f32_16x16x32_bf16 v[18:21], v[226:229], v[166:169], v[18:21]
	v_mfma_f32_16x16x32_bf16 v[6:9], v[182:185], v[174:177], v[6:9]
	v_mfma_f32_16x16x32_bf16 v[2:5], v[226:229], v[174:177], v[2:5]
	s_setprio 0
	s_add_i32 s39, 0, 0x18000
	v_add_u32_e32 v0, s39, v239
	s_barrier
	ds_read_b128 v[130:133], v0
	ds_read_b128 v[134:137], v0 offset:1024
	ds_read_b128 v[138:141], v0 offset:2048
	ds_read_b128 v[142:145], v0 offset:3072
	s_add_u32 s30, s30, 0x40000
	s_addc_u32 s31, s31, 0
	s_mov_b32 m0, s43
	ds_read_b128 v[146:149], v241 offset:32768
	ds_read_b128 v[150:153], v241 offset:33792
	ds_read_b128 v[154:157], v241 offset:34816
	ds_read_b128 v[158:161], v241 offset:35840
	ds_read_b128 v[162:165], v241 offset:36864
	ds_read_b128 v[166:169], v241 offset:37888
	ds_read_b128 v[170:173], v241 offset:38912
	ds_read_b128 v[174:177], v241 offset:39936
	global_load_lds_dwordx4 v202, s[30:31]
	s_mov_b32 m0, s44
	s_nop 0
	global_load_lds_dwordx4 v204, s[30:31]
	s_waitcnt lgkmcnt(8)
	s_barrier
	s_waitcnt lgkmcnt(0)
	s_setprio 1
	v_mfma_f32_16x16x32_bf16 v[126:129], v[130:133], v[146:149], v[126:129]
	v_mfma_f32_16x16x32_bf16 v[122:125], v[138:141], v[146:149], v[122:125]
	v_mfma_f32_16x16x32_bf16 v[110:113], v[130:133], v[154:157], v[110:113]
	v_mfma_f32_16x16x32_bf16 v[106:109], v[138:141], v[154:157], v[106:109]
	v_mfma_f32_16x16x32_bf16 v[94:97], v[130:133], v[162:165], v[94:97]
	v_mfma_f32_16x16x32_bf16 v[90:93], v[138:141], v[162:165], v[90:93]
	v_mfma_f32_16x16x32_bf16 v[78:81], v[130:133], v[170:173], v[78:81]
	v_mfma_f32_16x16x32_bf16 v[74:77], v[138:141], v[170:173], v[74:77]
	v_mfma_f32_16x16x32_bf16 v[126:129], v[134:137], v[150:153], v[126:129]
	v_mfma_f32_16x16x32_bf16 v[122:125], v[142:145], v[150:153], v[122:125]
	v_mfma_f32_16x16x32_bf16 v[110:113], v[134:137], v[158:161], v[110:113]
	v_mfma_f32_16x16x32_bf16 v[106:109], v[142:145], v[158:161], v[106:109]
	v_mfma_f32_16x16x32_bf16 v[94:97], v[134:137], v[166:169], v[94:97]
	v_mfma_f32_16x16x32_bf16 v[90:93], v[142:145], v[166:169], v[90:93]
	v_mfma_f32_16x16x32_bf16 v[78:81], v[134:137], v[174:177], v[78:81]
	v_mfma_f32_16x16x32_bf16 v[74:77], v[142:145], v[174:177], v[74:77]
	s_setprio 0
	s_barrier
	s_add_i32 s30, 0, 0x1c000
	s_add_i32 s31, s39, s40
	v_add_u32_e32 v0, s30, v239
	s_mov_b32 m0, s31
	ds_read_b128 v[178:181], v0
	ds_read_b128 v[182:185], v0 offset:1024
	ds_read_b128 v[210:213], v0 offset:2048
	ds_read_b128 v[226:229], v0 offset:3072
	global_load_lds_dwordx4 v202, s[98:99]
	s_add_i32 m0, s31, 0x2000
	s_nop 0
	global_load_lds_dwordx4 v204, s[98:99]
	s_barrier
	s_waitcnt lgkmcnt(0)
	s_setprio 1
	v_mfma_f32_16x16x32_bf16 v[118:121], v[178:181], v[146:149], v[118:121]
	v_mfma_f32_16x16x32_bf16 v[114:117], v[210:213], v[146:149], v[114:117]
	v_mfma_f32_16x16x32_bf16 v[102:105], v[178:181], v[154:157], v[102:105]
	v_mfma_f32_16x16x32_bf16 v[98:101], v[210:213], v[154:157], v[98:101]
	v_mfma_f32_16x16x32_bf16 v[86:89], v[178:181], v[162:165], v[86:89]
	v_mfma_f32_16x16x32_bf16 v[82:85], v[210:213], v[162:165], v[82:85]
	v_mfma_f32_16x16x32_bf16 v[70:73], v[178:181], v[170:173], v[70:73]
	v_mfma_f32_16x16x32_bf16 v[66:69], v[210:213], v[170:173], v[66:69]
	v_mfma_f32_16x16x32_bf16 v[118:121], v[182:185], v[150:153], v[118:121]
	v_mfma_f32_16x16x32_bf16 v[114:117], v[226:229], v[150:153], v[114:117]
	v_mfma_f32_16x16x32_bf16 v[102:105], v[182:185], v[158:161], v[102:105]
	v_mfma_f32_16x16x32_bf16 v[98:101], v[226:229], v[158:161], v[98:101]
	v_mfma_f32_16x16x32_bf16 v[86:89], v[182:185], v[166:169], v[86:89]
	v_mfma_f32_16x16x32_bf16 v[82:85], v[226:229], v[166:169], v[82:85]
	v_mfma_f32_16x16x32_bf16 v[70:73], v[182:185], v[174:177], v[70:73]
	v_mfma_f32_16x16x32_bf16 v[66:69], v[226:229], v[174:177], v[66:69]
	s_setprio 0
	s_mov_b32 m0, s66
	s_barrier
	ds_read_b128 v[146:149], v241 offset:49152
	ds_read_b128 v[150:153], v241 offset:50176
	ds_read_b128 v[154:157], v241 offset:51200
	ds_read_b128 v[158:161], v241 offset:52224
	ds_read_b128 v[162:165], v241 offset:53248
	ds_read_b128 v[166:169], v241 offset:54272
	ds_read_b128 v[170:173], v241 offset:55296
	ds_read_b128 v[174:177], v241 offset:56320
	global_load_lds_dwordx4 v202, s[100:101]
	s_mov_b32 m0, s67
	s_nop 0
	global_load_lds_dwordx4 v204, s[100:101]
	s_barrier
; #define GAS __attribute__((address_space(1)))
; #define PG8_STAGE(bufoff, gbase, voff) do { _Pragma("unroll") for (int _i = 0; _i < 2; ++_i) \
;     __builtin_amdgcn_global_load_lds((const unsigned*)((const char*)(gbase) + (voff)[_i]), (LAS unsigned*)(lds + (bufoff) + ldsw + _i * 8192), 16, 0, 0); } while (0)
; #define PG8_WAIT_V(n) asm volatile("s_waitcnt vmcnt(" #n ")" ::: "memory")
; #define PG8_WAIT_L(n) asm volatile("s_waitcnt lgkmcnt(" #n ")" ::: "memory")
; #define PG8_BAR __builtin_amdgcn_s_barrier()
; #define PG8_SCHED __builtin_amdgcn_sched_barrier(0)
; template <class Epi, class Sched>
; DI void gemm_phase(LAS unsigned char* lds, const int tid, const Gemm g, const Sched& S, const Epi& E) {
;     ...
;       PG8_BAR; PG8_WAIT_L(0); PG8_MMA(1, 0, At, B0); PG8_BAR; PG8_SCHED;
;       PG8_STAGE(PG8_SB(1, 1), b3 + hstepB, voffB);
;       PG8_WAIT_V(6); PG8_BAR; PG8_MMA(1, 1, At, B1); PG8_BAR;
;     }
;     { int z_e = 0; asm volatile("" : "+v"(z_e)); const int lane_e = __builtin_amdgcn_mbcnt_hi(~0u, __builtin_amdgcn_mbcnt_lo(~0u, (unsigned)z_e));
;       E(acc, cur, wr, wc, lane_e & 15, lane_e >> 4); }
;   DI void operator()(const AccT& acc, const Unit& u, int wr, int wc, int fr, int fq) const {
;     ...
;     } else if (wc == 2) {
;       const char* base = (const char*)(KR + (size_t)rowb * 32);
;       const char* sb = (const char*)(ssq_kr + rowb);
;       const unsigned o0 = (rl0 * 32u + fq * 8) * 4u, ro0 = (rl0 * 16u + fq * 4) * 4u;
;       const char* cb = (const char*)(cosM + posb * 16), *sbp = (const char*)(sinM + posb * 16);
;       f32x4 gv[2];
; #pragma unroll
;       for (int n = 0; n < 2; ++n) gv[n] = ld4p((const char*)(g_mk + 64) + n * 16, fq * 32u);
; #pragma unroll
;       for (int aim = 0; aim < 4; ++aim) { const int ai = aim >> 1, m0 = (aim & 1) * 2;
;         f32x2 cc[4][2], sn[4][2];
; #pragma unroll
;         for (int m = m0; m < m0 + 2; ++m)
; #pragma unroll
;           for (int n = 0; n < 2; ++n) { cc[m][n] = ld2p(cb + ((ai * 128 + m * 16) * 16 + n * 2) * 4, ro0); sn[m][n] = ld2p(sbp + ((ai * 128 + m * 16) * 16 + n * 2) * 4, ro0); }
; #pragma unroll
;         for (int m = m0; m < m0 + 2; ++m) {
;           const float ss = lane_ssq(acc, ai, m, 1.f);
;           if (fq == 0) *(GAS float*)((char*)sb + (size_t)(ai * 128 + m * 16) * 4 + rl0 * 4u) = ss;
	s_waitcnt lgkmcnt(0)
	s_setprio 1
	v_mfma_f32_16x16x32_bf16 v[62:65], v[130:133], v[146:149], v[62:65]
	v_mfma_f32_16x16x32_bf16 v[58:61], v[138:141], v[146:149], v[58:61]
	v_mfma_f32_16x16x32_bf16 v[46:49], v[130:133], v[154:157], v[46:49]
	v_mfma_f32_16x16x32_bf16 v[42:45], v[138:141], v[154:157], v[42:45]
	v_mfma_f32_16x16x32_bf16 v[30:33], v[130:133], v[162:165], v[30:33]
	v_mfma_f32_16x16x32_bf16 v[26:29], v[138:141], v[162:165], v[26:29]
	v_mfma_f32_16x16x32_bf16 v[14:17], v[130:133], v[170:173], v[14:17]
	v_mfma_f32_16x16x32_bf16 v[10:13], v[138:141], v[170:173], v[10:13]
	v_mfma_f32_16x16x32_bf16 v[62:65], v[134:137], v[150:153], v[62:65]
	v_mfma_f32_16x16x32_bf16 v[58:61], v[142:145], v[150:153], v[58:61]
	v_mfma_f32_16x16x32_bf16 v[46:49], v[134:137], v[158:161], v[46:49]
	v_mfma_f32_16x16x32_bf16 v[42:45], v[142:145], v[158:161], v[42:45]
	v_mfma_f32_16x16x32_bf16 v[30:33], v[134:137], v[166:169], v[30:33]
	v_mfma_f32_16x16x32_bf16 v[26:29], v[142:145], v[166:169], v[26:29]
	v_mfma_f32_16x16x32_bf16 v[14:17], v[134:137], v[174:177], v[14:17]
	v_mfma_f32_16x16x32_bf16 v[10:13], v[142:145], v[174:177], v[10:13]
	s_setprio 0
	s_barrier
	s_add_u32 s14, s14, 0x40080
	s_addc_u32 s15, s15, 0
	s_add_i32 s30, s30, s40
	s_mov_b32 m0, s30
	s_nop 0
	global_load_lds_dwordx4 v202, s[14:15]
	s_add_i32 m0, s30, 0x2000
	s_nop 0
	global_load_lds_dwordx4 v204, s[14:15]
	s_waitcnt vmcnt(6)
	s_barrier
	s_setprio 1
	v_mfma_f32_16x16x32_bf16 v[54:57], v[178:181], v[146:149], v[54:57]
	v_mfma_f32_16x16x32_bf16 v[50:53], v[210:213], v[146:149], v[50:53]
	v_mfma_f32_16x16x32_bf16 v[38:41], v[178:181], v[154:157], v[38:41]
	v_mfma_f32_16x16x32_bf16 v[34:37], v[210:213], v[154:157], v[34:37]
	v_mfma_f32_16x16x32_bf16 v[22:25], v[178:181], v[162:165], v[22:25]
	v_mfma_f32_16x16x32_bf16 v[18:21], v[210:213], v[162:165], v[18:21]
	v_mfma_f32_16x16x32_bf16 v[6:9], v[178:181], v[170:173], v[6:9]
	v_mfma_f32_16x16x32_bf16 v[2:5], v[210:213], v[170:173], v[2:5]
	v_mfma_f32_16x16x32_bf16 v[54:57], v[182:185], v[150:153], v[54:57]
	v_mfma_f32_16x16x32_bf16 v[50:53], v[226:229], v[150:153], v[50:53]
	v_mfma_f32_16x16x32_bf16 v[38:41], v[182:185], v[158:161], v[38:41]
	v_mfma_f32_16x16x32_bf16 v[34:37], v[226:229], v[158:161], v[34:37]
	v_mfma_f32_16x16x32_bf16 v[22:25], v[182:185], v[166:169], v[22:25]
	v_mfma_f32_16x16x32_bf16 v[18:21], v[226:229], v[166:169], v[18:21]
	v_mfma_f32_16x16x32_bf16 v[6:9], v[182:185], v[174:177], v[6:9]
	v_mfma_f32_16x16x32_bf16 v[2:5], v[226:229], v[174:177], v[2:5]
	s_setprio 0
	s_add_i32 s38, s38, 2
	s_add_u32 s34, s34, 0x100
	s_addc_u32 s35, s35, 0
	s_add_u32 s0, s0, 0x100
	s_addc_u32 s1, s1, 0
	s_cmp_gt_u32 s38, 13
	s_barrier
	s_cbranch_scc0 .LBB0_467
	v_mov_b32_e32 v0, v1
	s_lshl_b32 s30, s8, 8
	v_mbcnt_lo_u32_b32 v0, -1, v0
	s_cmp_eq_u32 s6, 0
	v_mbcnt_hi_u32_b32 v243, -1, v0
	s_cselect_b64 s[0:1], -1, 0
	v_and_or_b32 v244, v243, 15, s63
	s_and_b64 vcc, exec, s[0:1]
	s_cbranch_vccnz .LBB0_496
	s_cmp_eq_u32 s6, 3
	s_cselect_b64 s[0:1], -1, 0
	s_and_b64 s[0:1], s[0:1], s[12:13]
	s_andn2_b64 vcc, exec, s[0:1]
	s_mov_b64 s[0:1], -1
	s_cbranch_vccz .LBB0_509
	s_cmpk_lt_i32 s8, 0x80
	s_cselect_b64 s[8:9], -1, 0
	s_and_b32 s23, s30, 0x700
	s_cmp_eq_u32 s6, 1
	s_cselect_b64 s[38:39], -1, 0
	v_ashrrev_i32_e32 v162, 4, v243
	s_and_b64 vcc, exec, s[38:39]
	s_cbranch_vccnz .LBB0_497
	s_cmp_lg_u32 s6, 2
	s_cselect_b64 s[0:1], -1, 0
	s_cmp_eq_u32 s6, 2
	s_cselect_b64 s[6:7], -1, 0
	s_and_b64 s[6:7], s[6:7], s[12:13]
	s_andn2_b64 vcc, exec, s[6:7]
	s_mov_b64 s[38:39], -1
	s_cbranch_vccz .LBB0_495
	s_mov_b64 s[6:7], -1
	s_and_b64 vcc, exec, s[0:1]
	s_cbranch_vccz .LBB0_492
	s_andn2_b64 vcc, exec, s[16:17]
	s_cbranch_vccnz .LBB0_491
	s_mov_b32 s31, s97
	s_lshl_b64 s[0:1], s[30:31], 2
	s_add_u32 s14, s61, s0
	s_addc_u32 s15, s62, s1
	s_lshl_b32 s6, s23, 6
	v_cmp_lt_i32_e32 vcc, v231, v215
	s_add_u32 s0, s95, s6
	v_readlane_b32 s1, v255, 6
	v_cndmask_b32_e32 v138, v189, v231, vcc
	v_cmp_lt_i32_e32 vcc, v233, v215
	v_and_b32_e32 v0, -16, v243
	s_addc_u32 s1, s1, 0
	v_lshlrev_b32_e32 v164, 2, v138
	v_cndmask_b32_e32 v138, v189, v233, vcc
	v_lshlrev_b32_e32 v156, 5, v162
	v_lshl_add_u32 v0, v244, 6, v0
	s_add_u32 s6, s55, s6
	v_lshlrev_b32_e32 v163, 2, v138
	v_lshlrev_b32_e32 v138, 2, v244
	v_mov_b32_e32 v139, v1
	global_load_dwordx4 v[130:133], v156, s[64:65] offset:272
	global_load_dwordx4 v[134:137], v156, s[64:65] offset:256
	s_addc_u32 s7, s56, 0
	v_lshl_add_u64 v[154:155], s[14:15], 0, v[138:139]
	global_load_dwordx4 v[150:153], v0, s[0:1]
	global_load_dwordx4 v[146:149], v0, s[6:7]
	global_load_dwordx4 v[138:141], v0, s[0:1] offset:1024
	global_load_dwordx4 v[142:145], v0, s[6:7] offset:1024
	v_mul_f32_e32 v157, v127, v127
	v_fmac_f32_e32 v157, v126, v126
	v_fmac_f32_e32 v157, v128, v128
	v_fmac_f32_e32 v157, v129, v129
	v_fmac_f32_e32 v157, v122, v122
	v_fmac_f32_e32 v157, v123, v123
	v_fmac_f32_e32 v157, v124, v124
	v_fmac_f32_e32 v157, v125, v125
	v_fmac_f32_e32 v157, v118, v118
	v_fmac_f32_e32 v157, v119, v119
	v_fmac_f32_e32 v157, v120, v120
	v_fmac_f32_e32 v157, v121, v121
	v_fmac_f32_e32 v157, v114, v114
	v_fmac_f32_e32 v157, v115, v115
	v_fmac_f32_e32 v157, v116, v116
	v_fmac_f32_e32 v157, v117, v117
	ds_bpermute_b32 v158, v164, v157
	v_cmp_gt_u32_e32 vcc, 16, v243
	s_waitcnt lgkmcnt(0)
	v_add_f32_e32 v157, v157, v158
	ds_bpermute_b32 v158, v163, v157
	s_and_saveexec_b64 s[14:15], vcc
	s_cbranch_execz .LBB0_476
	s_waitcnt lgkmcnt(0)
	v_add_f32_e32 v157, v157, v158
	global_store_dword v[154:155], v157, off

; #define PG8_STAGE(bufoff, gbase, voff) do { _Pragma("unroll") for (int _i = 0; _i < 2; ++_i) \
;     __builtin_amdgcn_global_load_lds((const unsigned*)((const char*)(gbase) + (voff)[_i]), (LAS unsigned*)(lds + (bufoff) + ldsw + _i * 8192), 16, 0, 0); } while (0)
; #define PG8_LDA(dst, b, h) do { _Pragma("unroll") for (int m = 0; m < 4; ++m) _Pragma("unroll") for (int k = 0; k < 2; ++k) dst[m][k] = *(const LAS bf16x8*)(lds + PG8_SA(b, h) + aoff + m * 2048 + k * 1024); } while (0)
; #define PG8_LDB(dst, b, h) do { _Pragma("unroll") for (int n = 0; n < 2; ++n) _Pragma("unroll") for (int k = 0; k < 2; ++k) dst[n][k] = *(const LAS bf16x8*)(lds + PG8_SB(b, h) + boff + n * 2048 + k * 1024); } while (0)
; #define PG8_WAIT_V(n) asm volatile("s_waitcnt vmcnt(" #n ")" ::: "memory")
; #define PG8_WAIT_L(n) asm volatile("s_waitcnt lgkmcnt(" #n ")" ::: "memory")
; #define PG8_BAR __builtin_amdgcn_s_barrier()
; template <class Epi, class Sched>
; DI void gemm_phase(LAS unsigned char* lds, const int tid, const Gemm g, const Sched& S, const Epi& E) {
;     ...
;   for (;;) {
;     const bool has_next = S.next(ui + 1, nxt);
;     const char* nA = has_next ? (const char*)g.A + (size_t)nxt.pm * tstepA : cA; const char* nB = has_next ? (const char*)g.Bt + (size_t)nxt.pn * tstepB : cB;
; #pragma unroll 1
;     for (int t = 0; t < nt; t += 2) {
;       const bool last = (t == nt - 2);
;       const char* a1 = cA + (size_t)(t + 1) * kstep;
;       const char* a2 = last ? nA : cA + (size_t)(t + 2) * kstep; const char* b2 = last ? nB : cB + (size_t)(t + 2) * kstep;
;       const char* a3 = a2 + kstep; const char* b3 = b2 + kstep;
;       PG8_LDB(B0, 0, 0); PG8_SCHED; PG8_LDA(At, 0, 0); PG8_STAGE(PG8_SA(1, 1), a1 + hstepA, voffA);
;       PG8_WAIT_L(8); PG8_BAR; PG8_WAIT_L(0); PG8_MMA(0, 0, At, B0); PG8_BAR; PG8_SCHED;
;       PG8_LDB(B1, 0, 1); PG8_STAGE(PG8_SB(0, 0), b2, voffB);
;       PG8_BAR; PG8_WAIT_L(0); PG8_MMA(0, 1, At, B1); PG8_BAR;
;       PG8_LDA(At, 0, 1); PG8_STAGE(PG8_SA(0, 0), a2, voffA);
;       PG8_BAR; PG8_WAIT_L(0); PG8_MMA(1, 0, At, B0); PG8_BAR; PG8_SCHED;
;       PG8_STAGE(PG8_SB(0, 1), b2 + hstepB, voffB);
;       PG8_WAIT_V(6); PG8_BAR; PG8_MMA(1, 1, At, B1); PG8_BAR;
;       PG8_LDB(B0, 1, 0); PG8_SCHED; PG8_LDA(At, 1, 0); PG8_STAGE(PG8_SA(0, 1), a2 + hstepA, voffA);
;       PG8_WAIT_L(8); PG8_BAR; PG8_WAIT_L(0); PG8_MMA(0, 0, At, B0); PG8_BAR; PG8_SCHED;
.LBB0_589:
	s_add_i32 s30, s12, 2
	s_add_u32 s0, s10, 0x100
	s_addc_u32 s1, s11, 0
	s_add_i32 s31, 0, 0x10000
	v_add_u32_e32 v0, s31, v206
	ds_read_b128 v[130:133], v0
	ds_read_b128 v[134:137], v0 offset:1024
	ds_read_b128 v[138:141], v0 offset:2048
	ds_read_b128 v[142:145], v0 offset:3072
	s_cmp_eq_u32 s2, s12
	s_cselect_b32 s12, s24, s0
	s_cselect_b32 s13, s25, s1
	s_cselect_b32 s15, s9, s29
	s_cselect_b32 s14, s23, s28
	s_add_i32 m0, s59, 0xc000
	ds_read_b128 v[146:149], v207
	ds_read_b128 v[150:153], v207 offset:1024
	ds_read_b128 v[154:157], v207 offset:2048
	ds_read_b128 v[158:161], v207 offset:3072
	ds_read_b128 v[162:165], v207 offset:4096
	ds_read_b128 v[178:181], v207 offset:5120
	ds_read_b128 v[182:185], v207 offset:6144
	ds_read_b128 v[202:205], v207 offset:7168
	global_load_lds_dwordx4 v176, s[10:11]
	s_add_i32 m0, s59, 0xe000
	s_nop 0
	global_load_lds_dwordx4 v174, s[10:11]
	s_waitcnt lgkmcnt(8)
	s_barrier
	s_waitcnt lgkmcnt(0)
	s_setprio 1
	v_mfma_f32_16x16x32_bf16 v[126:129], v[130:133], v[146:149], v[126:129]
	v_mfma_f32_16x16x32_bf16 v[122:125], v[138:141], v[146:149], v[122:125]
	v_mfma_f32_16x16x32_bf16 v[110:113], v[130:133], v[154:157], v[110:113]
	v_mfma_f32_16x16x32_bf16 v[106:109], v[138:141], v[154:157], v[106:109]
	v_mfma_f32_16x16x32_bf16 v[94:97], v[130:133], v[162:165], v[94:97]
	v_mfma_f32_16x16x32_bf16 v[90:93], v[138:141], v[162:165], v[90:93]
	v_mfma_f32_16x16x32_bf16 v[78:81], v[130:133], v[182:185], v[78:81]
	v_mfma_f32_16x16x32_bf16 v[74:77], v[138:141], v[182:185], v[74:77]
	v_mfma_f32_16x16x32_bf16 v[126:129], v[134:137], v[150:153], v[126:129]
	v_mfma_f32_16x16x32_bf16 v[122:125], v[142:145], v[150:153], v[122:125]
	v_mfma_f32_16x16x32_bf16 v[110:113], v[134:137], v[158:161], v[110:113]
	v_mfma_f32_16x16x32_bf16 v[106:109], v[142:145], v[158:161], v[106:109]
	v_mfma_f32_16x16x32_bf16 v[94:97], v[134:137], v[178:181], v[94:97]
	v_mfma_f32_16x16x32_bf16 v[90:93], v[142:145], v[178:181], v[90:93]
	v_mfma_f32_16x16x32_bf16 v[78:81], v[134:137], v[202:205], v[78:81]
	v_mfma_f32_16x16x32_bf16 v[74:77], v[142:145], v[202:205], v[74:77]
	s_setprio 0
	s_barrier
	s_add_i32 s34, 0, 0x14000
	s_add_i32 s10, s31, s53
	v_add_u32_e32 v0, s34, v206
	s_add_u32 s98, s14, s50
	s_addc_u32 s99, s15, s51
	s_mov_b32 m0, s10
	ds_read_b128 v[208:211], v0
	ds_read_b128 v[226:229], v0 offset:1024
	ds_read_b128 v[238:241], v0 offset:2048
	ds_read_b128 v[242:245], v0 offset:3072
	global_load_lds_dwordx4 v168, s[14:15]
	s_add_i32 m0, s10, 0x2000
	s_nop 0
	global_load_lds_dwordx4 v172, s[14:15]
	s_barrier
	s_waitcnt lgkmcnt(0)
	s_setprio 1
	v_mfma_f32_16x16x32_bf16 v[118:121], v[208:211], v[146:149], v[118:121]
	v_mfma_f32_16x16x32_bf16 v[114:117], v[238:241], v[146:149], v[114:117]
	v_mfma_f32_16x16x32_bf16 v[102:105], v[208:211], v[154:157], v[102:105]
	v_mfma_f32_16x16x32_bf16 v[98:101], v[238:241], v[154:157], v[98:101]
	v_mfma_f32_16x16x32_bf16 v[86:89], v[208:211], v[162:165], v[86:89]
	v_mfma_f32_16x16x32_bf16 v[82:85], v[238:241], v[162:165], v[82:85]
	v_mfma_f32_16x16x32_bf16 v[70:73], v[208:211], v[182:185], v[70:73]
	v_mfma_f32_16x16x32_bf16 v[66:69], v[238:241], v[182:185], v[66:69]
	v_mfma_f32_16x16x32_bf16 v[118:121], v[226:229], v[150:153], v[118:121]
	v_mfma_f32_16x16x32_bf16 v[114:117], v[242:245], v[150:153], v[114:117]
	v_mfma_f32_16x16x32_bf16 v[102:105], v[226:229], v[158:161], v[102:105]
	v_mfma_f32_16x16x32_bf16 v[98:101], v[242:245], v[158:161], v[98:101]
	v_mfma_f32_16x16x32_bf16 v[86:89], v[226:229], v[178:181], v[86:89]
	v_mfma_f32_16x16x32_bf16 v[82:85], v[242:245], v[178:181], v[82:85]
	v_mfma_f32_16x16x32_bf16 v[70:73], v[226:229], v[202:205], v[70:73]
	v_mfma_f32_16x16x32_bf16 v[66:69], v[242:245], v[202:205], v[66:69]
	s_setprio 0
	s_mov_b32 m0, s59
	s_add_u32 s100, s12, s50
	s_addc_u32 s101, s13, s51
	s_barrier
	ds_read_b128 v[146:149], v207 offset:16384
	ds_read_b128 v[150:153], v207 offset:17408
	ds_read_b128 v[154:157], v207 offset:18432
	ds_read_b128 v[158:161], v207 offset:19456
	ds_read_b128 v[162:165], v207 offset:20480
	ds_read_b128 v[178:181], v207 offset:21504
	ds_read_b128 v[182:185], v207 offset:22528
	ds_read_b128 v[202:205], v207 offset:23552
	global_load_lds_dwordx4 v166, s[12:13]
	s_mov_b32 m0, s60
	s_nop 0
	global_load_lds_dwordx4 v170, s[12:13]
	s_barrier
	s_waitcnt lgkmcnt(0)
	s_setprio 1
	v_mfma_f32_16x16x32_bf16 v[62:65], v[130:133], v[146:149], v[62:65]
	v_mfma_f32_16x16x32_bf16 v[58:61], v[138:141], v[146:149], v[58:61]
	v_mfma_f32_16x16x32_bf16 v[46:49], v[130:133], v[154:157], v[46:49]
	v_mfma_f32_16x16x32_bf16 v[42:45], v[138:141], v[154:157], v[42:45]
	v_mfma_f32_16x16x32_bf16 v[30:33], v[130:133], v[162:165], v[30:33]
	v_mfma_f32_16x16x32_bf16 v[26:29], v[138:141], v[162:165], v[26:29]
	v_mfma_f32_16x16x32_bf16 v[14:17], v[130:133], v[182:185], v[14:17]
	v_mfma_f32_16x16x32_bf16 v[10:13], v[138:141], v[182:185], v[10:13]
	v_mfma_f32_16x16x32_bf16 v[62:65], v[134:137], v[150:153], v[62:65]
	v_mfma_f32_16x16x32_bf16 v[58:61], v[142:145], v[150:153], v[58:61]
	v_mfma_f32_16x16x32_bf16 v[46:49], v[134:137], v[158:161], v[46:49]
	v_mfma_f32_16x16x32_bf16 v[42:45], v[142:145], v[158:161], v[42:45]
	v_mfma_f32_16x16x32_bf16 v[30:33], v[134:137], v[178:181], v[30:33]
	v_mfma_f32_16x16x32_bf16 v[26:29], v[142:145], v[178:181], v[26:29]
	v_mfma_f32_16x16x32_bf16 v[14:17], v[134:137], v[202:205], v[14:17]
	v_mfma_f32_16x16x32_bf16 v[10:13], v[142:145], v[202:205], v[10:13]
	s_setprio 0
	s_barrier
	s_add_u32 s10, s14, s52
	s_addc_u32 s11, s15, 0
	s_add_i32 s14, s34, s53
	v_lshl_add_u64 v[216:217], s[10:11], 0, v[168:169]
	s_mov_b32 m0, s14
	v_lshl_add_u64 v[218:219], s[10:11], 0, v[172:173]
	global_load_lds_dwordx4 v[216:217], off
	s_add_i32 m0, s14, 0x2000
	s_nop 0
	global_load_lds_dwordx4 v[218:219], off
	s_waitcnt vmcnt(6)
	s_barrier
; #define PG8_STAGE(bufoff, gbase, voff) do { _Pragma("unroll") for (int _i = 0; _i < 2; ++_i) \
;     __builtin_amdgcn_global_load_lds((const unsigned*)((const char*)(gbase) + (voff)[_i]), (LAS unsigned*)(lds + (bufoff) + ldsw + _i * 8192), 16, 0, 0); } while (0)
; #define PG8_LDA(dst, b, h) do { _Pragma("unroll") for (int m = 0; m < 4; ++m) _Pragma("unroll") for (int k = 0; k < 2; ++k) dst[m][k] = *(const LAS bf16x8*)(lds + PG8_SA(b, h) + aoff + m * 2048 + k * 1024); } while (0)
; #define PG8_LDB(dst, b, h) do { _Pragma("unroll") for (int n = 0; n < 2; ++n) _Pragma("unroll") for (int k = 0; k < 2; ++k) dst[n][k] = *(const LAS bf16x8*)(lds + PG8_SB(b, h) + boff + n * 2048 + k * 1024); } while (0)
; #define PG8_MMA(ai, bj, At, Bt) do { __builtin_amdgcn_s_setprio(1); _Pragma("unroll") for (int m = 0; m < 4; ++m) _Pragma("unroll") for (int n = 0; n < 2; ++n) _Pragma("unroll") for (int k = 0; k < 2; ++k) \
;     acc[ai][bj][m][n] = __builtin_amdgcn_mfma_f32_16x16x32_bf16(Bt[n][k], At[m][k], acc[ai][bj][m][n], 0, 0, 0); __builtin_amdgcn_s_setprio(0); } while (0)
; #define PG8_WAIT_V(n) asm volatile("s_waitcnt vmcnt(" #n ")" ::: "memory")
; #define PG8_WAIT_L(n) asm volatile("s_waitcnt lgkmcnt(" #n ")" ::: "memory")
; #define PG8_BAR __builtin_amdgcn_s_barrier()
; #define PG8_SCHED __builtin_amdgcn_sched_barrier(0)
; template <class Epi, class Sched>
; DI void gemm_phase(LAS unsigned char* lds, const int tid, const Gemm g, const Sched& S, const Epi& E) {
;     ...
;       PG8_WAIT_V(6); PG8_BAR; PG8_MMA(1, 1, At, B1); PG8_BAR;
;       PG8_LDB(B0, 1, 0); PG8_SCHED; PG8_LDA(At, 1, 0); PG8_STAGE(PG8_SA(0, 1), a2 + hstepA, voffA);
;       PG8_WAIT_L(8); PG8_BAR; PG8_WAIT_L(0); PG8_MMA(0, 0, At, B0); PG8_BAR; PG8_SCHED;
;       PG8_LDB(B1, 1, 1); PG8_STAGE(PG8_SB(1, 0), b3, voffB);
;       PG8_BAR; PG8_WAIT_L(0); PG8_MMA(0, 1, At, B1); PG8_BAR;
;       PG8_LDA(At, 1, 1); PG8_STAGE(PG8_SA(1, 0), a3, voffA);
;       PG8_BAR; PG8_WAIT_L(0); PG8_MMA(1, 0, At, B0); PG8_BAR; PG8_SCHED;
	s_setprio 1
	v_mfma_f32_16x16x32_bf16 v[54:57], v[208:211], v[146:149], v[54:57]
	v_mfma_f32_16x16x32_bf16 v[50:53], v[238:241], v[146:149], v[50:53]
	v_mfma_f32_16x16x32_bf16 v[38:41], v[208:211], v[154:157], v[38:41]
	v_mfma_f32_16x16x32_bf16 v[34:37], v[238:241], v[154:157], v[34:37]
	v_mfma_f32_16x16x32_bf16 v[22:25], v[208:211], v[162:165], v[22:25]
	v_mfma_f32_16x16x32_bf16 v[18:21], v[238:241], v[162:165], v[18:21]
	v_mfma_f32_16x16x32_bf16 v[6:9], v[208:211], v[182:185], v[6:9]
	v_mfma_f32_16x16x32_bf16 v[2:5], v[238:241], v[182:185], v[2:5]
	v_mfma_f32_16x16x32_bf16 v[54:57], v[226:229], v[150:153], v[54:57]
	v_mfma_f32_16x16x32_bf16 v[50:53], v[242:245], v[150:153], v[50:53]
	v_mfma_f32_16x16x32_bf16 v[38:41], v[226:229], v[158:161], v[38:41]
	v_mfma_f32_16x16x32_bf16 v[34:37], v[242:245], v[158:161], v[34:37]
	v_mfma_f32_16x16x32_bf16 v[22:25], v[226:229], v[178:181], v[22:25]
	v_mfma_f32_16x16x32_bf16 v[18:21], v[242:245], v[178:181], v[18:21]
	v_mfma_f32_16x16x32_bf16 v[6:9], v[226:229], v[202:205], v[6:9]
	v_mfma_f32_16x16x32_bf16 v[2:5], v[242:245], v[202:205], v[2:5]
	s_setprio 0
	s_add_i32 s14, 0, 0x18000
	v_add_u32_e32 v0, s14, v206
	s_barrier
	ds_read_b128 v[130:133], v0
	ds_read_b128 v[134:137], v0 offset:1024
	ds_read_b128 v[138:141], v0 offset:2048
	ds_read_b128 v[142:145], v0 offset:3072
	s_add_u32 s10, s12, 0x18000
	s_addc_u32 s11, s13, 0
	s_mov_b32 m0, s61
	ds_read_b128 v[146:149], v207 offset:32768
	ds_read_b128 v[150:153], v207 offset:33792
	ds_read_b128 v[154:157], v207 offset:34816
	ds_read_b128 v[158:161], v207 offset:35840
	ds_read_b128 v[162:165], v207 offset:36864
	ds_read_b128 v[178:181], v207 offset:37888
	ds_read_b128 v[182:185], v207 offset:38912
	ds_read_b128 v[202:205], v207 offset:39936
	global_load_lds_dwordx4 v166, s[10:11]
	s_mov_b32 m0, s62
	s_nop 0
	global_load_lds_dwordx4 v170, s[10:11]
	s_waitcnt lgkmcnt(8)
	s_barrier
	s_waitcnt lgkmcnt(0)
	s_setprio 1
	v_mfma_f32_16x16x32_bf16 v[126:129], v[130:133], v[146:149], v[126:129]
	v_mfma_f32_16x16x32_bf16 v[122:125], v[138:141], v[146:149], v[122:125]
	v_mfma_f32_16x16x32_bf16 v[110:113], v[130:133], v[154:157], v[110:113]
	v_mfma_f32_16x16x32_bf16 v[106:109], v[138:141], v[154:157], v[106:109]
	v_mfma_f32_16x16x32_bf16 v[94:97], v[130:133], v[162:165], v[94:97]
	v_mfma_f32_16x16x32_bf16 v[90:93], v[138:141], v[162:165], v[90:93]
	v_mfma_f32_16x16x32_bf16 v[78:81], v[130:133], v[182:185], v[78:81]
	v_mfma_f32_16x16x32_bf16 v[74:77], v[138:141], v[182:185], v[74:77]
	v_mfma_f32_16x16x32_bf16 v[126:129], v[134:137], v[150:153], v[126:129]
	v_mfma_f32_16x16x32_bf16 v[122:125], v[142:145], v[150:153], v[122:125]
	v_mfma_f32_16x16x32_bf16 v[110:113], v[134:137], v[158:161], v[110:113]
	v_mfma_f32_16x16x32_bf16 v[106:109], v[142:145], v[158:161], v[106:109]
	v_mfma_f32_16x16x32_bf16 v[94:97], v[134:137], v[178:181], v[94:97]
	v_mfma_f32_16x16x32_bf16 v[90:93], v[142:145], v[178:181], v[90:93]
	v_mfma_f32_16x16x32_bf16 v[78:81], v[134:137], v[202:205], v[78:81]
	v_mfma_f32_16x16x32_bf16 v[74:77], v[142:145], v[202:205], v[74:77]
	s_setprio 0
	s_barrier
	s_add_i32 s10, 0, 0x1c000
	s_add_i32 s11, s14, s53
	v_add_u32_e32 v0, s10, v206
	s_mov_b32 m0, s11
	ds_read_b128 v[208:211], v0
	ds_read_b128 v[226:229], v0 offset:1024
	ds_read_b128 v[238:241], v0 offset:2048
	ds_read_b128 v[242:245], v0 offset:3072
	global_load_lds_dwordx4 v168, s[98:99]
	s_add_i32 m0, s11, 0x2000
	s_nop 0
	global_load_lds_dwordx4 v172, s[98:99]
	s_barrier
	s_waitcnt lgkmcnt(0)
	s_setprio 1
	v_mfma_f32_16x16x32_bf16 v[118:121], v[208:211], v[146:149], v[118:121]
	v_mfma_f32_16x16x32_bf16 v[114:117], v[238:241], v[146:149], v[114:117]
	v_mfma_f32_16x16x32_bf16 v[102:105], v[208:211], v[154:157], v[102:105]
	v_mfma_f32_16x16x32_bf16 v[98:101], v[238:241], v[154:157], v[98:101]
	v_mfma_f32_16x16x32_bf16 v[86:89], v[208:211], v[162:165], v[86:89]
	v_mfma_f32_16x16x32_bf16 v[82:85], v[238:241], v[162:165], v[82:85]
	v_mfma_f32_16x16x32_bf16 v[70:73], v[208:211], v[182:185], v[70:73]
	v_mfma_f32_16x16x32_bf16 v[66:69], v[238:241], v[182:185], v[66:69]
	v_mfma_f32_16x16x32_bf16 v[118:121], v[226:229], v[150:153], v[118:121]
	v_mfma_f32_16x16x32_bf16 v[114:117], v[242:245], v[150:153], v[114:117]
	v_mfma_f32_16x16x32_bf16 v[102:105], v[226:229], v[158:161], v[102:105]
	v_mfma_f32_16x16x32_bf16 v[98:101], v[242:245], v[158:161], v[98:101]
	v_mfma_f32_16x16x32_bf16 v[86:89], v[226:229], v[178:181], v[86:89]
	v_mfma_f32_16x16x32_bf16 v[82:85], v[242:245], v[178:181], v[82:85]
	v_mfma_f32_16x16x32_bf16 v[70:73], v[226:229], v[202:205], v[70:73]
	v_mfma_f32_16x16x32_bf16 v[66:69], v[242:245], v[202:205], v[66:69]
	s_setprio 0
	s_mov_b32 m0, s57
	s_barrier
	ds_read_b128 v[146:149], v207 offset:49152
	ds_read_b128 v[150:153], v207 offset:50176
	ds_read_b128 v[154:157], v207 offset:51200
	ds_read_b128 v[158:161], v207 offset:52224
	ds_read_b128 v[162:165], v207 offset:53248
	ds_read_b128 v[178:181], v207 offset:54272
	ds_read_b128 v[182:185], v207 offset:55296
	ds_read_b128 v[202:205], v207 offset:56320
	global_load_lds_dwordx4 v166, s[100:101]
	s_mov_b32 m0, s74
	s_nop 0
	global_load_lds_dwordx4 v170, s[100:101]
	s_barrier
; #define PG8_STAGE(bufoff, gbase, voff) do { _Pragma("unroll") for (int _i = 0; _i < 2; ++_i) \
;     __builtin_amdgcn_global_load_lds((const unsigned*)((const char*)(gbase) + (voff)[_i]), (LAS unsigned*)(lds + (bufoff) + ldsw + _i * 8192), 16, 0, 0); } while (0)
; #define PG8_MMA(ai, bj, At, Bt) do { __builtin_amdgcn_s_setprio(1); _Pragma("unroll") for (int m = 0; m < 4; ++m) _Pragma("unroll") for (int n = 0; n < 2; ++n) _Pragma("unroll") for (int k = 0; k < 2; ++k) \
;     acc[ai][bj][m][n] = __builtin_amdgcn_mfma_f32_16x16x32_bf16(Bt[n][k], At[m][k], acc[ai][bj][m][n], 0, 0, 0); __builtin_amdgcn_s_setprio(0); } while (0)
; #define PG8_WAIT_V(n) asm volatile("s_waitcnt vmcnt(" #n ")" ::: "memory")
; #define PG8_WAIT_L(n) asm volatile("s_waitcnt lgkmcnt(" #n ")" ::: "memory")
; #define PG8_BAR __builtin_amdgcn_s_barrier()
; #define PG8_SCHED __builtin_amdgcn_sched_barrier(0)
; DI void st8p(void* ub, unsigned voff, f32x4 a, f32x4 b) { u32x4 o = {pk(a[0], a[1]), pk(a[2], a[3]), pk(b[0], b[1]), pk(b[2], b[3])}; *(GAS u32x4*)((char*)ub + voff) = o; }
; template <class Epi, class Sched>
; DI void gemm_phase(LAS unsigned char* lds, const int tid, const Gemm g, const Sched& S, const Epi& E) {
;     ...
;       PG8_BAR; PG8_WAIT_L(0); PG8_MMA(1, 0, At, B0); PG8_BAR; PG8_SCHED;
;       PG8_STAGE(PG8_SB(1, 1), b3 + hstepB, voffB);
;       PG8_WAIT_V(6); PG8_BAR; PG8_MMA(1, 1, At, B1); PG8_BAR;
;     }
;     { int z_e = 0; asm volatile("" : "+v"(z_e)); const int lane_e = __builtin_amdgcn_mbcnt_hi(~0u, __builtin_amdgcn_mbcnt_lo(~0u, (unsigned)z_e));
;       E(acc, cur, wr, wc, lane_e & 15, lane_e >> 4); }
;     if (!has_next) break;
;   DI void operator()(const AccT& acc, const Unit& u, int wr, int wc, int fr, int fq) const {
;     ...
;       } else {
;         const char* base = (const char*)(V + (size_t)rowb * 512 + head * 64);
;         const unsigned o0 = (rl0 * 512u + fq * 8) * 2u;
;         f32x2 s2[2][4];
;         ROWS_LOOP s2[ai][m] = ld2p(sc_b + (ai * 128 + m * 16) * 8, rl0 * 8u);
;         ROWS_LOOP {
;           const float rs = rsqrtf((s2[ai][m][0] + s2[ai][m][1]) * (1.f / 128.f) + EPS);
;           char* rb = (char*)base + (size_t)(ai * 128 + m * 16) * 512 * 2;
; #pragma unroll
;           for (int bj = 0; bj < 2; ++bj) st8p(rb + bj * 64, o0, acc[ai][bj][m][0] * rs, acc[ai][bj][m][1] * rs);
	s_waitcnt lgkmcnt(0)
	s_setprio 1
	v_mfma_f32_16x16x32_bf16 v[62:65], v[130:133], v[146:149], v[62:65]
	v_mfma_f32_16x16x32_bf16 v[58:61], v[138:141], v[146:149], v[58:61]
	v_mfma_f32_16x16x32_bf16 v[46:49], v[130:133], v[154:157], v[46:49]
	v_mfma_f32_16x16x32_bf16 v[42:45], v[138:141], v[154:157], v[42:45]
	v_mfma_f32_16x16x32_bf16 v[30:33], v[130:133], v[162:165], v[30:33]
	v_mfma_f32_16x16x32_bf16 v[26:29], v[138:141], v[162:165], v[26:29]
	v_mfma_f32_16x16x32_bf16 v[14:17], v[130:133], v[182:185], v[14:17]
	v_mfma_f32_16x16x32_bf16 v[10:13], v[138:141], v[182:185], v[10:13]
	v_mfma_f32_16x16x32_bf16 v[62:65], v[134:137], v[150:153], v[62:65]
	v_mfma_f32_16x16x32_bf16 v[58:61], v[142:145], v[150:153], v[58:61]
	v_mfma_f32_16x16x32_bf16 v[46:49], v[134:137], v[158:161], v[46:49]
	v_mfma_f32_16x16x32_bf16 v[42:45], v[142:145], v[158:161], v[42:45]
	v_mfma_f32_16x16x32_bf16 v[30:33], v[134:137], v[178:181], v[30:33]
	v_mfma_f32_16x16x32_bf16 v[26:29], v[142:145], v[178:181], v[26:29]
	v_mfma_f32_16x16x32_bf16 v[14:17], v[134:137], v[202:205], v[14:17]
	v_mfma_f32_16x16x32_bf16 v[10:13], v[142:145], v[202:205], v[10:13]
	s_setprio 0
	s_barrier
	s_add_i32 s10, s10, s53
	v_lshl_add_u64 v[130:131], v[216:217], 0, s[50:51]
	s_mov_b32 m0, s10
	s_nop 0
	global_load_lds_dwordx4 v[130:131], off
	v_lshl_add_u64 v[130:131], v[218:219], 0, s[50:51]
	s_add_i32 m0, s10, 0x2000
	s_nop 0
	global_load_lds_dwordx4 v[130:131], off
	s_waitcnt vmcnt(6)
	s_barrier
	s_setprio 1
	v_mfma_f32_16x16x32_bf16 v[54:57], v[208:211], v[146:149], v[54:57]
	v_mfma_f32_16x16x32_bf16 v[50:53], v[238:241], v[146:149], v[50:53]
	v_mfma_f32_16x16x32_bf16 v[38:41], v[208:211], v[154:157], v[38:41]
	v_mfma_f32_16x16x32_bf16 v[34:37], v[238:241], v[154:157], v[34:37]
	v_mfma_f32_16x16x32_bf16 v[22:25], v[208:211], v[162:165], v[22:25]
	v_mfma_f32_16x16x32_bf16 v[18:21], v[238:241], v[162:165], v[18:21]
	v_mfma_f32_16x16x32_bf16 v[6:9], v[208:211], v[182:185], v[6:9]
	v_mfma_f32_16x16x32_bf16 v[2:5], v[238:241], v[182:185], v[2:5]
	v_mfma_f32_16x16x32_bf16 v[54:57], v[226:229], v[150:153], v[54:57]
	v_mfma_f32_16x16x32_bf16 v[50:53], v[242:245], v[150:153], v[50:53]
	v_mfma_f32_16x16x32_bf16 v[38:41], v[226:229], v[158:161], v[38:41]
	v_mfma_f32_16x16x32_bf16 v[34:37], v[242:245], v[158:161], v[34:37]
	v_mfma_f32_16x16x32_bf16 v[22:25], v[226:229], v[178:181], v[22:25]
	v_mfma_f32_16x16x32_bf16 v[18:21], v[242:245], v[178:181], v[18:21]
	v_mfma_f32_16x16x32_bf16 v[6:9], v[226:229], v[202:205], v[6:9]
	v_mfma_f32_16x16x32_bf16 v[2:5], v[242:245], v[202:205], v[2:5]
	s_setprio 0
	s_add_u32 s28, s28, 0x100
	s_addc_u32 s29, s29, 0
	s_cmp_ge_u32 s30, s88
	s_mov_b64 s[10:11], s[0:1]
	s_mov_b32 s12, s30
	s_barrier
	s_cbranch_scc0 .LBB0_589
	v_mov_b32_e32 v0, v1
	s_add_i32 s0, s8, s3
	v_mbcnt_lo_u32_b32 v0, -1, v0
	v_mbcnt_hi_u32_b32 v204, -1, v0
	s_lshl_b32 s96, s80, 8
	s_lshl_b32 s23, s0, 1
	v_ashrrev_i32_e32 v202, 4, v204
	s_cmp_gt_i32 s0, 3
	v_and_or_b32 v205, v204, 15, s56
	s_cbranch_scc0 .LBB0_596
	s_add_i32 s12, s23, s90
	s_lshl_b64 s[0:1], s[96:97], 3
	s_add_u32 s8, s84, s0
	s_addc_u32 s9, s36, s1
	s_mov_b64 s[0:1], -1
	s_and_b64 vcc, exec, s[18:19]
	v_lshlrev_b32_e32 v203, 3, v205
	s_cbranch_vccz .LBB0_593
	global_load_dwordx2 v[136:137], v203, s[8:9]
	global_load_dwordx2 v[146:147], v203, s[8:9] offset:128
	global_load_dwordx2 v[142:143], v203, s[8:9] offset:256
	global_load_dwordx2 v[144:145], v203, s[8:9] offset:384
	global_load_dwordx2 v[138:139], v203, s[8:9] offset:1024
	global_load_dwordx2 v[140:141], v203, s[8:9] offset:1152
	global_load_dwordx2 v[132:133], v203, s[8:9] offset:1280
	global_load_dwordx2 v[134:135], v203, s[8:9] offset:1408
	s_lshl_b64 s[0:1], s[96:97], 10
	s_add_u32 s10, s95, s0
	s_addc_u32 s11, s38, s1
	s_lshl_b32 s0, s12, 6
	s_mov_b32 s1, s97
	s_lshl_b64 s[0:1], s[0:1], 1
	s_add_u32 s10, s10, s0
	s_mov_b32 s0, 0x358637bd
	s_brev_b32 s14, 60
	s_mov_b32 s15, 0x3c2aaaab
	s_addc_u32 s11, s11, s1
	v_and_b32_e32 v0, -16, v204
	v_lshl_add_u32 v0, v205, 10, v0
	v_lshl_add_u64 v[130:131], s[10:11], 0, v[0:1]
	s_waitcnt vmcnt(0)
	v_mov_b32_e32 v149, v136
	v_mov_b32_e32 v148, v146
	v_mov_b32_e32 v136, v147
	v_pk_add_f32 v[146:147], v[148:149], v[136:137]
	v_mov_b64_e32 v[136:137], s[0:1]
	v_pk_fma_f32 v[150:151], v[146:147], s[14:15], v[136:137] op_sel_hi:[1,0,0]
	s_nop 0
	v_mul_f32_e32 v146, 0x4b800000, v151
	v_cmp_gt_f32_e64 s[0:1], s45, v151
	v_cmp_gt_f32_e32 vcc, s45, v150
	s_nop 0
	v_cndmask_b32_e64 v146, v151, v146, s[0:1]
	v_rsq_f32_e32 v146, v146
	s_nop 0
	v_mul_f32_e32 v147, 0x45800000, v146
	v_cndmask_b32_e64 v152, v146, v147, s[0:1]
	v_pk_mul_f32 v[148:149], v[128:129], v[152:153] op_sel_hi:[1,0]
	v_pk_mul_f32 v[146:147], v[126:127], v[152:153] op_sel_hi:[1,0]
	v_pk_mul_f32 v[154:155], v[124:125], v[152:153] op_sel_hi:[1,0]
	v_pk_mul_f32 v[156:157], v[122:123], v[152:153] op_sel_hi:[1,0]
	v_cvt_pk_bf16_f32 v146, v146, v147
	v_cvt_pk_bf16_f32 v147, v148, v149
	v_cvt_pk_bf16_f32 v148, v156, v157
	v_cvt_pk_bf16_f32 v149, v154, v155
	global_store_dwordx4 v0, v[146:149], s[10:11]
	v_pk_mul_f32 v[154:155], v[116:117], v[152:153] op_sel_hi:[1,0]
	s_movk_i32 s0, 0x4000
	v_pk_mul_f32 v[148:149], v[120:121], v[152:153] op_sel_hi:[1,0]
	v_pk_mul_f32 v[146:147], v[118:119], v[152:153] op_sel_hi:[1,0]
	v_pk_mul_f32 v[152:153], v[114:115], v[152:153] op_sel_hi:[1,0]
	v_cvt_pk_bf16_f32 v146, v146, v147
	v_cvt_pk_bf16_f32 v147, v148, v149
	v_cvt_pk_bf16_f32 v148, v152, v153
	v_cvt_pk_bf16_f32 v149, v154, v155
	global_store_dwordx4 v0, v[146:149], s[10:11] offset:64
	v_mul_f32_e32 v0, 0x4b800000, v150
	v_cndmask_b32_e32 v0, v150, v0, vcc
	v_rsq_f32_e32 v0, v0
	s_nop 0
; DI void st8p(void* ub, unsigned voff, f32x4 a, f32x4 b) { u32x4 o = {pk(a[0], a[1]), pk(a[2], a[3]), pk(b[0], b[1]), pk(b[2], b[3])}; *(GAS u32x4*)((char*)ub + voff) = o; }
; #define ROWS_LOOP _Pragma("unroll") for (int ai = 0; ai < 2; ++ai) _Pragma("unroll") for (int m = 0; m < 4; ++m)
;   DI void operator()(const AccT& acc, const Unit& u, int wr, int wc, int fr, int fq) const {
;     ...
;         ROWS_LOOP {
;           const float rs = rsqrtf((s2[ai][m][0] + s2[ai][m][1]) * (1.f / 128.f) + EPS);
;           char* rb = (char*)base + (size_t)(ai * 128 + m * 16) * 512 * 2;
; #pragma unroll
;           for (int bj = 0; bj < 2; ++bj) st8p(rb + bj * 64, o0, acc[ai][bj][m][0] * rs, acc[ai][bj][m][1] * rs);
	v_mul_f32_e32 v146, 0x45800000, v0
	v_cndmask_b32_e32 v0, v0, v146, vcc
	v_pk_mul_f32 v[148:149], v[112:113], v[0:1] op_sel_hi:[1,0]
	v_pk_mul_f32 v[146:147], v[110:111], v[0:1] op_sel_hi:[1,0]
	v_pk_mul_f32 v[150:151], v[108:109], v[0:1] op_sel_hi:[1,0]
	v_pk_mul_f32 v[152:153], v[106:107], v[0:1] op_sel_hi:[1,0]
	v_cvt_pk_bf16_f32 v146, v146, v147
	v_cvt_pk_bf16_f32 v147, v148, v149
	v_cvt_pk_bf16_f32 v149, v150, v151
	v_add_co_u32_e32 v150, vcc, s0, v130
	v_cvt_pk_bf16_f32 v148, v152, v153
	s_nop 0
	v_addc_co_u32_e32 v151, vcc, 0, v131, vcc
	global_store_dwordx4 v[150:151], v[146:149], off
	v_pk_mul_f32 v[152:153], v[100:101], v[0:1] op_sel_hi:[1,0]
	v_pk_mul_f32 v[154:155], v[98:99], v[0:1] op_sel_hi:[1,0]
	v_pk_mul_f32 v[148:149], v[104:105], v[0:1] op_sel_hi:[1,0]
	v_pk_mul_f32 v[146:147], v[102:103], v[0:1] op_sel_hi:[1,0]
	s_nop 0
	v_cvt_pk_bf16_f32 v146, v146, v147
	v_cvt_pk_bf16_f32 v147, v148, v149
	v_cvt_pk_bf16_f32 v148, v154, v155
	v_cvt_pk_bf16_f32 v149, v152, v153
	global_store_dwordx4 v[150:151], v[146:149], off offset:64
	s_nop 1
	v_mov_b32_e32 v146, v144
	v_mov_b32_e32 v147, v142
	v_mov_b32_e32 v142, v145
	v_pk_add_f32 v[142:143], v[146:147], v[142:143]
	s_nop 0
	v_pk_fma_f32 v[142:143], v[142:143], s[14:15], v[136:137] op_sel_hi:[1,0,0]
	s_nop 0
	v_mul_f32_e32 v0, 0x4b800000, v143
	v_cmp_gt_f32_e64 s[0:1], s45, v143
	v_cmp_gt_f32_e32 vcc, s45, v142
	s_nop 0
	v_cndmask_b32_e64 v0, v143, v0, s[0:1]
	v_rsq_f32_e32 v0, v0
	s_nop 0
	v_mul_f32_e32 v143, 0x45800000, v0
	v_cndmask_b32_e64 v0, v0, v143, s[0:1]
	v_pk_mul_f32 v[146:147], v[96:97], v[0:1] op_sel_hi:[1,0]
	v_pk_mul_f32 v[144:145], v[94:95], v[0:1] op_sel_hi:[1,0]
	v_pk_mul_f32 v[148:149], v[92:93], v[0:1] op_sel_hi:[1,0]
	s_mov_b32 s0, 0x8000
	v_pk_mul_f32 v[150:151], v[90:91], v[0:1] op_sel_hi:[1,0]
	v_cvt_pk_bf16_f32 v144, v144, v145
	v_cvt_pk_bf16_f32 v145, v146, v147
	v_cvt_pk_bf16_f32 v147, v148, v149
	v_add_co_u32_e64 v148, s[0:1], s0, v130
	v_cvt_pk_bf16_f32 v146, v150, v151
	s_nop 0
	v_addc_co_u32_e64 v149, s[0:1], 0, v131, s[0:1]
	global_store_dwordx4 v[148:149], v[144:147], off
	v_pk_mul_f32 v[150:151], v[84:85], v[0:1] op_sel_hi:[1,0]
	v_pk_mul_f32 v[152:153], v[82:83], v[0:1] op_sel_hi:[1,0]
	v_pk_mul_f32 v[146:147], v[88:89], v[0:1] op_sel_hi:[1,0]
	v_pk_mul_f32 v[144:145], v[86:87], v[0:1] op_sel_hi:[1,0]
	v_mul_f32_e32 v0, 0x4b800000, v142
	v_cndmask_b32_e32 v0, v142, v0, vcc
	v_rsq_f32_e32 v0, v0
	v_cvt_pk_bf16_f32 v144, v144, v145
	v_cvt_pk_bf16_f32 v145, v146, v147
	v_cvt_pk_bf16_f32 v146, v152, v153
	v_mul_f32_e32 v142, 0x45800000, v0
	v_cvt_pk_bf16_f32 v147, v150, v151
	v_cndmask_b32_e32 v0, v0, v142, vcc
	global_store_dwordx4 v[148:149], v[144:147], off offset:64
	v_pk_mul_f32 v[142:143], v[78:79], v[0:1] op_sel_hi:[1,0]
	s_mov_b32 s0, 0xc000
	v_pk_mul_f32 v[144:145], v[80:81], v[0:1] op_sel_hi:[1,0]
	v_pk_mul_f32 v[146:147], v[76:77], v[0:1] op_sel_hi:[1,0]
	v_pk_mul_f32 v[148:149], v[74:75], v[0:1] op_sel_hi:[1,0]
	v_cvt_pk_bf16_f32 v142, v142, v143
	v_cvt_pk_bf16_f32 v143, v144, v145
	v_cvt_pk_bf16_f32 v145, v146, v147
	v_add_co_u32_e32 v146, vcc, s0, v130
	v_cvt_pk_bf16_f32 v144, v148, v149
	s_nop 0
	v_addc_co_u32_e32 v147, vcc, 0, v131, vcc
	global_store_dwordx4 v[146:147], v[142:145], off
	v_pk_mul_f32 v[148:149], v[68:69], v[0:1] op_sel_hi:[1,0]
	v_pk_mul_f32 v[150:151], v[66:67], v[0:1] op_sel_hi:[1,0]
	v_pk_mul_f32 v[144:145], v[72:73], v[0:1] op_sel_hi:[1,0]
	v_pk_mul_f32 v[142:143], v[70:71], v[0:1] op_sel_hi:[1,0]
	s_nop 0
	v_cvt_pk_bf16_f32 v142, v142, v143
	v_cvt_pk_bf16_f32 v143, v144, v145
	v_cvt_pk_bf16_f32 v144, v150, v151
	v_cvt_pk_bf16_f32 v145, v148, v149
	global_store_dwordx4 v[146:147], v[142:145], off offset:64
	s_nop 1
	v_mov_b32_e32 v142, v140
	v_mov_b32_e32 v143, v138
	v_mov_b32_e32 v138, v141
	v_pk_add_f32 v[138:139], v[142:143], v[138:139]
	s_nop 0
	v_pk_fma_f32 v[142:143], v[138:139], s[14:15], v[136:137] op_sel_hi:[1,0,0]
	s_nop 0
	v_mul_f32_e32 v0, 0x4b800000, v143
	v_cmp_gt_f32_e64 s[0:1], s45, v143
	v_cmp_gt_f32_e32 vcc, s45, v142
	s_nop 0
	v_cndmask_b32_e64 v0, v143, v0, s[0:1]
	v_rsq_f32_e32 v0, v0
	s_nop 0
	v_mul_f32_e32 v138, 0x45800000, v0
	v_cndmask_b32_e64 v0, v0, v138, s[0:1]
	v_pk_mul_f32 v[140:141], v[64:65], v[0:1] op_sel_hi:[1,0]
	v_pk_mul_f32 v[138:139], v[62:63], v[0:1] op_sel_hi:[1,0]
	v_pk_mul_f32 v[144:145], v[60:61], v[0:1] op_sel_hi:[1,0]
	v_pk_mul_f32 v[146:147], v[58:59], v[0:1] op_sel_hi:[1,0]
	v_cvt_pk_bf16_f32 v138, v138, v139
	v_cvt_pk_bf16_f32 v139, v140, v141
; DI void st8p(void* ub, unsigned voff, f32x4 a, f32x4 b) { u32x4 o = {pk(a[0], a[1]), pk(a[2], a[3]), pk(b[0], b[1]), pk(b[2], b[3])}; *(GAS u32x4*)((char*)ub + voff) = o; }
; #define ROWS_LOOP _Pragma("unroll") for (int ai = 0; ai < 2; ++ai) _Pragma("unroll") for (int m = 0; m < 4; ++m)
;   DI void operator()(const AccT& acc, const Unit& u, int wr, int wc, int fr, int fq) const {
;     ...
;         ROWS_LOOP {
;           const float rs = rsqrtf((s2[ai][m][0] + s2[ai][m][1]) * (1.f / 128.f) + EPS);
;           char* rb = (char*)base + (size_t)(ai * 128 + m * 16) * 512 * 2;
; #pragma unroll
;           for (int bj = 0; bj < 2; ++bj) st8p(rb + bj * 64, o0, acc[ai][bj][m][0] * rs, acc[ai][bj][m][1] * rs);
	v_cvt_pk_bf16_f32 v141, v144, v145
	v_add_co_u32_e64 v144, s[0:1], s71, v130
	v_cvt_pk_bf16_f32 v140, v146, v147
	s_nop 0
	v_addc_co_u32_e64 v145, s[0:1], 0, v131, s[0:1]
	global_store_dwordx4 v[144:145], v[138:141], off
	v_pk_mul_f32 v[146:147], v[52:53], v[0:1] op_sel_hi:[1,0]
	v_pk_mul_f32 v[148:149], v[50:51], v[0:1] op_sel_hi:[1,0]
	v_pk_mul_f32 v[140:141], v[56:57], v[0:1] op_sel_hi:[1,0]
	v_pk_mul_f32 v[138:139], v[54:55], v[0:1] op_sel_hi:[1,0]
	v_mul_f32_e32 v0, 0x4b800000, v142
	v_cndmask_b32_e32 v0, v142, v0, vcc
	v_rsq_f32_e32 v0, v0
	v_cvt_pk_bf16_f32 v138, v138, v139
	v_cvt_pk_bf16_f32 v139, v140, v141
	v_cvt_pk_bf16_f32 v140, v148, v149
	v_cvt_pk_bf16_f32 v141, v146, v147
	global_store_dwordx4 v[144:145], v[138:141], off offset:64
	s_mov_b32 s0, 0x24000
	s_nop 0
	v_mul_f32_e32 v138, 0x45800000, v0
	v_cndmask_b32_e32 v0, v0, v138, vcc
	v_pk_mul_f32 v[140:141], v[48:49], v[0:1] op_sel_hi:[1,0]
	v_pk_mul_f32 v[138:139], v[46:47], v[0:1] op_sel_hi:[1,0]
	v_pk_mul_f32 v[142:143], v[44:45], v[0:1] op_sel_hi:[1,0]
	v_pk_mul_f32 v[144:145], v[42:43], v[0:1] op_sel_hi:[1,0]
	v_cvt_pk_bf16_f32 v138, v138, v139
	v_cvt_pk_bf16_f32 v139, v140, v141
	v_cvt_pk_bf16_f32 v141, v142, v143
	v_add_co_u32_e32 v142, vcc, s0, v130
	v_cvt_pk_bf16_f32 v140, v144, v145
	s_nop 0
	v_addc_co_u32_e32 v143, vcc, 0, v131, vcc
	global_store_dwordx4 v[142:143], v[138:141], off
	v_pk_mul_f32 v[144:145], v[36:37], v[0:1] op_sel_hi:[1,0]
	v_pk_mul_f32 v[146:147], v[34:35], v[0:1] op_sel_hi:[1,0]
	v_pk_mul_f32 v[140:141], v[40:41], v[0:1] op_sel_hi:[1,0]
	v_pk_mul_f32 v[138:139], v[38:39], v[0:1] op_sel_hi:[1,0]
	s_nop 0
	v_cvt_pk_bf16_f32 v138, v138, v139
	v_cvt_pk_bf16_f32 v139, v140, v141
	v_cvt_pk_bf16_f32 v140, v146, v147
	v_cvt_pk_bf16_f32 v141, v144, v145
	global_store_dwordx4 v[142:143], v[138:141], off offset:64
	s_nop 1
	v_mov_b32_e32 v138, v134
	v_mov_b32_e32 v139, v132
	v_mov_b32_e32 v132, v135
	v_pk_add_f32 v[132:133], v[138:139], v[132:133]
	s_nop 0
	v_pk_fma_f32 v[136:137], v[132:133], s[14:15], v[136:137] op_sel_hi:[1,0,0]
	s_nop 0
	v_mul_f32_e32 v0, 0x4b800000, v137
	v_cmp_gt_f32_e64 s[0:1], s45, v137
	v_cmp_gt_f32_e32 vcc, s45, v136
	s_nop 0
	v_cndmask_b32_e64 v0, v137, v0, s[0:1]
	v_rsq_f32_e32 v0, v0
	s_nop 0
	v_mul_f32_e32 v132, 0x45800000, v0
	v_cndmask_b32_e64 v0, v0, v132, s[0:1]
	v_pk_mul_f32 v[134:135], v[32:33], v[0:1] op_sel_hi:[1,0]
	v_pk_mul_f32 v[132:133], v[30:31], v[0:1] op_sel_hi:[1,0]
	v_pk_mul_f32 v[138:139], v[28:29], v[0:1] op_sel_hi:[1,0]
	s_mov_b32 s0, 0x28000
	v_pk_mul_f32 v[140:141], v[26:27], v[0:1] op_sel_hi:[1,0]
	v_cvt_pk_bf16_f32 v132, v132, v133
	v_cvt_pk_bf16_f32 v133, v134, v135
	v_cvt_pk_bf16_f32 v135, v138, v139
	v_add_co_u32_e64 v138, s[0:1], s0, v130
	v_cvt_pk_bf16_f32 v134, v140, v141
	s_nop 0
	v_addc_co_u32_e64 v139, s[0:1], 0, v131, s[0:1]
	global_store_dwordx4 v[138:139], v[132:135], off
	v_pk_mul_f32 v[140:141], v[20:21], v[0:1] op_sel_hi:[1,0]
	v_pk_mul_f32 v[142:143], v[18:19], v[0:1] op_sel_hi:[1,0]
	v_pk_mul_f32 v[134:135], v[24:25], v[0:1] op_sel_hi:[1,0]
	v_pk_mul_f32 v[132:133], v[22:23], v[0:1] op_sel_hi:[1,0]
	v_mul_f32_e32 v0, 0x4b800000, v136
	v_cndmask_b32_e32 v0, v136, v0, vcc
	v_rsq_f32_e32 v0, v0
	v_cvt_pk_bf16_f32 v132, v132, v133
	v_cvt_pk_bf16_f32 v133, v134, v135
	v_cvt_pk_bf16_f32 v134, v142, v143
	v_cvt_pk_bf16_f32 v135, v140, v141
	global_store_dwordx4 v[138:139], v[132:135], off offset:64
	s_mov_b32 s0, 0x2c000
	s_nop 0
	v_mul_f32_e32 v132, 0x45800000, v0
	v_cndmask_b32_e32 v0, v0, v132, vcc
	v_pk_mul_f32 v[134:135], v[16:17], v[0:1] op_sel_hi:[1,0]
	v_pk_mul_f32 v[132:133], v[14:15], v[0:1] op_sel_hi:[1,0]
	v_pk_mul_f32 v[136:137], v[12:13], v[0:1] op_sel_hi:[1,0]
	v_pk_mul_f32 v[138:139], v[10:11], v[0:1] op_sel_hi:[1,0]
	v_cvt_pk_bf16_f32 v132, v132, v133
	v_cvt_pk_bf16_f32 v133, v134, v135
	v_cvt_pk_bf16_f32 v135, v136, v137
	v_add_co_u32_e32 v136, vcc, s0, v130
	v_cvt_pk_bf16_f32 v134, v138, v139
	s_nop 0
	v_addc_co_u32_e32 v137, vcc, 0, v131, vcc
	global_store_dwordx4 v[136:137], v[132:135], off
	v_pk_mul_f32 v[136:137], v[4:5], v[0:1] op_sel_hi:[1,0]
	v_pk_mul_f32 v[140:141], v[2:3], v[0:1] op_sel_hi:[1,0]
	v_pk_mul_f32 v[132:133], v[8:9], v[0:1] op_sel_hi:[1,0]
	v_pk_mul_f32 v[134:135], v[6:7], v[0:1] op_sel_hi:[1,0]
	s_mov_b64 s[0:1], 0x2c040
	v_cvt_pk_bf16_f32 v138, v134, v135
	v_cvt_pk_bf16_f32 v139, v132, v133
	v_cvt_pk_bf16_f32 v140, v140, v141
	v_cvt_pk_bf16_f32 v141, v136, v137
	v_lshl_add_u64 v[142:143], v[130:131], 0, s[0:1]
	s_mov_b64 s[0:1], 0

; #define PG8_STAGE(bufoff, gbase, voff) do { _Pragma("unroll") for (int _i = 0; _i < 2; ++_i) \
;     __builtin_amdgcn_global_load_lds((const unsigned*)((const char*)(gbase) + (voff)[_i]), (LAS unsigned*)(lds + (bufoff) + ldsw + _i * 8192), 16, 0, 0); } while (0)
; #define PG8_LDA(dst, b, h) do { _Pragma("unroll") for (int m = 0; m < 4; ++m) _Pragma("unroll") for (int k = 0; k < 2; ++k) dst[m][k] = *(const LAS bf16x8*)(lds + PG8_SA(b, h) + aoff + m * 2048 + k * 1024); } while (0)
; #define PG8_LDB(dst, b, h) do { _Pragma("unroll") for (int n = 0; n < 2; ++n) _Pragma("unroll") for (int k = 0; k < 2; ++k) dst[n][k] = *(const LAS bf16x8*)(lds + PG8_SB(b, h) + boff + n * 2048 + k * 1024); } while (0)
; #define PG8_MMA(ai, bj, At, Bt) do { __builtin_amdgcn_s_setprio(1); _Pragma("unroll") for (int m = 0; m < 4; ++m) _Pragma("unroll") for (int n = 0; n < 2; ++n) _Pragma("unroll") for (int k = 0; k < 2; ++k) \
;     acc[ai][bj][m][n] = __builtin_amdgcn_mfma_f32_16x16x32_bf16(Bt[n][k], At[m][k], acc[ai][bj][m][n], 0, 0, 0); __builtin_amdgcn_s_setprio(0); } while (0)
; #define PG8_WAIT_L(n) asm volatile("s_waitcnt lgkmcnt(" #n ")" ::: "memory")
; #define PG8_BAR __builtin_amdgcn_s_barrier()
; template <class Epi, class Sched>
; DI void gemm_phase(LAS unsigned char* lds, const int tid, const Gemm g, const Sched& S, const Epi& E) {
;     ...
;   for (;;) {
;     const bool has_next = S.next(ui + 1, nxt);
;     const char* nA = has_next ? (const char*)g.A + (size_t)nxt.pm * tstepA : cA; const char* nB = has_next ? (const char*)g.Bt + (size_t)nxt.pn * tstepB : cB;
; #pragma unroll 1
;     for (int t = 0; t < nt; t += 2) {
;       const bool last = (t == nt - 2);
;       const char* a1 = cA + (size_t)(t + 1) * kstep;
;       const char* a2 = last ? nA : cA + (size_t)(t + 2) * kstep; const char* b2 = last ? nB : cB + (size_t)(t + 2) * kstep;
;       const char* a3 = a2 + kstep; const char* b3 = b2 + kstep;
;       PG8_LDB(B0, 0, 0); PG8_SCHED; PG8_LDA(At, 0, 0); PG8_STAGE(PG8_SA(1, 1), a1 + hstepA, voffA);
;       PG8_WAIT_L(8); PG8_BAR; PG8_WAIT_L(0); PG8_MMA(0, 0, At, B0); PG8_BAR; PG8_SCHED;
;       PG8_LDB(B1, 0, 1); PG8_STAGE(PG8_SB(0, 0), b2, voffB);
;       PG8_BAR; PG8_WAIT_L(0); PG8_MMA(0, 1, At, B1); PG8_BAR;
;       PG8_LDA(At, 0, 1); PG8_STAGE(PG8_SA(0, 0), a2, voffA);
;       PG8_BAR; PG8_WAIT_L(0); PG8_MMA(1, 0, At, B0); PG8_BAR; PG8_SCHED;
.LBB0_645:
	s_add_u32 s14, s12, 0xfffe0080
	s_addc_u32 s15, s13, -1
	s_add_i32 s40, 0, 0x10000
	v_add_u32_e32 v0, s40, v142
	ds_read_b128 v[144:147], v0
	ds_read_b128 v[148:151], v0 offset:1024
	ds_read_b128 v[152:155], v0 offset:2048
	ds_read_b128 v[156:159], v0 offset:3072
	s_cmp_eq_u32 s39, 4
	s_cselect_b32 s17, s7, s15
	s_cselect_b32 s16, s35, s14
	s_cselect_b32 s15, s5, s38
	s_cselect_b32 s14, s36, s37
	s_add_i32 m0, s22, 0xc000
	ds_read_b128 v[160:163], v143
	ds_read_b128 v[164:167], v143 offset:1024
	ds_read_b128 v[168:171], v143 offset:2048
	ds_read_b128 v[172:175], v143 offset:3072
	ds_read_b128 v[176:179], v143 offset:4096
	ds_read_b128 v[180:183], v143 offset:5120
	ds_read_b128 v[202:205], v143 offset:6144
	ds_read_b128 v[206:209], v143 offset:7168
	global_load_lds_dwordx4 v140, s[12:13]
	s_add_i32 m0, s22, 0xe000
	s_nop 0
	global_load_lds_dwordx4 v138, s[12:13]
	s_waitcnt lgkmcnt(8)
	s_barrier
	s_waitcnt lgkmcnt(0)
	s_setprio 1
	v_mfma_f32_16x16x32_bf16 v[126:129], v[144:147], v[160:163], v[126:129]
	v_mfma_f32_16x16x32_bf16 v[122:125], v[152:155], v[160:163], v[122:125]
	v_mfma_f32_16x16x32_bf16 v[118:121], v[144:147], v[168:171], v[118:121]
	v_mfma_f32_16x16x32_bf16 v[114:117], v[152:155], v[168:171], v[114:117]
	v_mfma_f32_16x16x32_bf16 v[102:105], v[144:147], v[176:179], v[102:105]
	v_mfma_f32_16x16x32_bf16 v[98:101], v[152:155], v[176:179], v[98:101]
	v_mfma_f32_16x16x32_bf16 v[86:89], v[144:147], v[202:205], v[86:89]
	v_mfma_f32_16x16x32_bf16 v[82:85], v[152:155], v[202:205], v[82:85]
	v_mfma_f32_16x16x32_bf16 v[126:129], v[148:151], v[164:167], v[126:129]
	v_mfma_f32_16x16x32_bf16 v[122:125], v[156:159], v[164:167], v[122:125]
	v_mfma_f32_16x16x32_bf16 v[118:121], v[148:151], v[172:175], v[118:121]
	v_mfma_f32_16x16x32_bf16 v[114:117], v[156:159], v[172:175], v[114:117]
	v_mfma_f32_16x16x32_bf16 v[102:105], v[148:151], v[180:183], v[102:105]
	v_mfma_f32_16x16x32_bf16 v[98:101], v[156:159], v[180:183], v[98:101]
	v_mfma_f32_16x16x32_bf16 v[86:89], v[148:151], v[206:209], v[86:89]
	v_mfma_f32_16x16x32_bf16 v[82:85], v[156:159], v[206:209], v[82:85]
	s_setprio 0
	s_barrier
	s_add_i32 s42, 0, 0x14000
	s_add_i32 s40, s40, s21
	v_add_u32_e32 v0, s42, v142
	s_add_u32 s98, s14, s50
	s_addc_u32 s99, s15, s51
	s_mov_b32 m0, s40
	ds_read_b128 v[210:213], v0
	ds_read_b128 v[226:229], v0 offset:1024
	ds_read_b128 v[238:241], v0 offset:2048
	ds_read_b128 v[242:245], v0 offset:3072
	global_load_lds_dwordx4 v134, s[14:15]
	s_add_i32 m0, s40, 0x2000
	s_nop 0
	global_load_lds_dwordx4 v130, s[14:15]
	s_barrier
	s_waitcnt lgkmcnt(0)
	s_setprio 1
	v_mfma_f32_16x16x32_bf16 v[110:113], v[210:213], v[160:163], v[110:113]
	v_mfma_f32_16x16x32_bf16 v[106:109], v[238:241], v[160:163], v[106:109]
	v_mfma_f32_16x16x32_bf16 v[94:97], v[210:213], v[168:171], v[94:97]
	v_mfma_f32_16x16x32_bf16 v[90:93], v[238:241], v[168:171], v[90:93]
	v_mfma_f32_16x16x32_bf16 v[78:81], v[210:213], v[176:179], v[78:81]
	v_mfma_f32_16x16x32_bf16 v[74:77], v[238:241], v[176:179], v[74:77]
	v_mfma_f32_16x16x32_bf16 v[70:73], v[210:213], v[202:205], v[70:73]
	v_mfma_f32_16x16x32_bf16 v[66:69], v[238:241], v[202:205], v[66:69]
	v_mfma_f32_16x16x32_bf16 v[110:113], v[226:229], v[164:167], v[110:113]
	v_mfma_f32_16x16x32_bf16 v[106:109], v[242:245], v[164:167], v[106:109]
	v_mfma_f32_16x16x32_bf16 v[94:97], v[226:229], v[172:175], v[94:97]
	v_mfma_f32_16x16x32_bf16 v[90:93], v[242:245], v[172:175], v[90:93]
	v_mfma_f32_16x16x32_bf16 v[78:81], v[226:229], v[180:183], v[78:81]
	v_mfma_f32_16x16x32_bf16 v[74:77], v[242:245], v[180:183], v[74:77]
	v_mfma_f32_16x16x32_bf16 v[70:73], v[226:229], v[206:209], v[70:73]
	v_mfma_f32_16x16x32_bf16 v[66:69], v[242:245], v[206:209], v[66:69]
	s_setprio 0
	s_mov_b32 m0, s22
	s_add_u32 s100, s16, s50
	s_addc_u32 s101, s17, s51
	s_barrier
	ds_read_b128 v[160:163], v143 offset:16384
	ds_read_b128 v[164:167], v143 offset:17408
	ds_read_b128 v[168:171], v143 offset:18432
	ds_read_b128 v[172:175], v143 offset:19456
	ds_read_b128 v[176:179], v143 offset:20480
	ds_read_b128 v[180:183], v143 offset:21504
	ds_read_b128 v[202:205], v143 offset:22528
	ds_read_b128 v[206:209], v143 offset:23552
	global_load_lds_dwordx4 v136, s[16:17]
	s_mov_b32 m0, s23
	s_nop 0
	global_load_lds_dwordx4 v132, s[16:17]
	s_barrier
	s_waitcnt lgkmcnt(0)
	s_setprio 1
	v_mfma_f32_16x16x32_bf16 v[62:65], v[144:147], v[160:163], v[62:65]
	v_mfma_f32_16x16x32_bf16 v[58:61], v[152:155], v[160:163], v[58:61]
	v_mfma_f32_16x16x32_bf16 v[54:57], v[144:147], v[168:171], v[54:57]
	v_mfma_f32_16x16x32_bf16 v[50:53], v[152:155], v[168:171], v[50:53]
	v_mfma_f32_16x16x32_bf16 v[38:41], v[144:147], v[176:179], v[38:41]
	v_mfma_f32_16x16x32_bf16 v[34:37], v[152:155], v[176:179], v[34:37]
	v_mfma_f32_16x16x32_bf16 v[22:25], v[144:147], v[202:205], v[22:25]
	v_mfma_f32_16x16x32_bf16 v[18:21], v[152:155], v[202:205], v[18:21]
	v_mfma_f32_16x16x32_bf16 v[62:65], v[148:151], v[164:167], v[62:65]
	v_mfma_f32_16x16x32_bf16 v[58:61], v[156:159], v[164:167], v[58:61]
	v_mfma_f32_16x16x32_bf16 v[54:57], v[148:151], v[172:175], v[54:57]
	v_mfma_f32_16x16x32_bf16 v[50:53], v[156:159], v[172:175], v[50:53]
	v_mfma_f32_16x16x32_bf16 v[38:41], v[148:151], v[180:183], v[38:41]
	v_mfma_f32_16x16x32_bf16 v[34:37], v[156:159], v[180:183], v[34:37]
	v_mfma_f32_16x16x32_bf16 v[22:25], v[148:151], v[206:209], v[22:25]
	v_mfma_f32_16x16x32_bf16 v[18:21], v[156:159], v[206:209], v[18:21]
	s_setprio 0
	s_barrier
	s_add_u32 s40, s14, 0x20000
	s_addc_u32 s41, s15, 0
	s_add_i32 s42, s42, s21
	s_mov_b32 m0, s42
	s_nop 0
	global_load_lds_dwordx4 v134, s[40:41]
	s_add_i32 m0, s42, 0x2000
	s_nop 0
	global_load_lds_dwordx4 v130, s[40:41]
	s_waitcnt vmcnt(6)
	s_barrier
; #define PG8_STAGE(bufoff, gbase, voff) do { _Pragma("unroll") for (int _i = 0; _i < 2; ++_i) \
;     __builtin_amdgcn_global_load_lds((const unsigned*)((const char*)(gbase) + (voff)[_i]), (LAS unsigned*)(lds + (bufoff) + ldsw + _i * 8192), 16, 0, 0); } while (0)
; #define PG8_LDA(dst, b, h) do { _Pragma("unroll") for (int m = 0; m < 4; ++m) _Pragma("unroll") for (int k = 0; k < 2; ++k) dst[m][k] = *(const LAS bf16x8*)(lds + PG8_SA(b, h) + aoff + m * 2048 + k * 1024); } while (0)
; #define PG8_LDB(dst, b, h) do { _Pragma("unroll") for (int n = 0; n < 2; ++n) _Pragma("unroll") for (int k = 0; k < 2; ++k) dst[n][k] = *(const LAS bf16x8*)(lds + PG8_SB(b, h) + boff + n * 2048 + k * 1024); } while (0)
; #define PG8_MMA(ai, bj, At, Bt) do { __builtin_amdgcn_s_setprio(1); _Pragma("unroll") for (int m = 0; m < 4; ++m) _Pragma("unroll") for (int n = 0; n < 2; ++n) _Pragma("unroll") for (int k = 0; k < 2; ++k) \
;     acc[ai][bj][m][n] = __builtin_amdgcn_mfma_f32_16x16x32_bf16(Bt[n][k], At[m][k], acc[ai][bj][m][n], 0, 0, 0); __builtin_amdgcn_s_setprio(0); } while (0)
; #define PG8_WAIT_V(n) asm volatile("s_waitcnt vmcnt(" #n ")" ::: "memory")
; #define PG8_WAIT_L(n) asm volatile("s_waitcnt lgkmcnt(" #n ")" ::: "memory")
; #define PG8_BAR __builtin_amdgcn_s_barrier()
; #define PG8_SCHED __builtin_amdgcn_sched_barrier(0)
; template <class Epi, class Sched>
; DI void gemm_phase(LAS unsigned char* lds, const int tid, const Gemm g, const Sched& S, const Epi& E) {
;     ...
;       PG8_WAIT_V(6); PG8_BAR; PG8_MMA(1, 1, At, B1); PG8_BAR;
;       PG8_LDB(B0, 1, 0); PG8_SCHED; PG8_LDA(At, 1, 0); PG8_STAGE(PG8_SA(0, 1), a2 + hstepA, voffA);
;       PG8_WAIT_L(8); PG8_BAR; PG8_WAIT_L(0); PG8_MMA(0, 0, At, B0); PG8_BAR; PG8_SCHED;
;       PG8_LDB(B1, 1, 1); PG8_STAGE(PG8_SB(1, 0), b3, voffB);
;       PG8_BAR; PG8_WAIT_L(0); PG8_MMA(0, 1, At, B1); PG8_BAR;
;       PG8_LDA(At, 1, 1); PG8_STAGE(PG8_SA(1, 0), a3, voffA);
;       PG8_BAR; PG8_WAIT_L(0); PG8_MMA(1, 0, At, B0); PG8_BAR; PG8_SCHED;
	s_setprio 1
	v_mfma_f32_16x16x32_bf16 v[46:49], v[210:213], v[160:163], v[46:49]
	v_mfma_f32_16x16x32_bf16 v[42:45], v[238:241], v[160:163], v[42:45]
	v_mfma_f32_16x16x32_bf16 v[30:33], v[210:213], v[168:171], v[30:33]
	v_mfma_f32_16x16x32_bf16 v[26:29], v[238:241], v[168:171], v[26:29]
	v_mfma_f32_16x16x32_bf16 v[14:17], v[210:213], v[176:179], v[14:17]
	v_mfma_f32_16x16x32_bf16 v[10:13], v[238:241], v[176:179], v[10:13]
	v_mfma_f32_16x16x32_bf16 v[6:9], v[210:213], v[202:205], v[6:9]
	v_mfma_f32_16x16x32_bf16 v[2:5], v[238:241], v[202:205], v[2:5]
	v_mfma_f32_16x16x32_bf16 v[46:49], v[226:229], v[164:167], v[46:49]
	v_mfma_f32_16x16x32_bf16 v[42:45], v[242:245], v[164:167], v[42:45]
	v_mfma_f32_16x16x32_bf16 v[30:33], v[226:229], v[172:175], v[30:33]
	v_mfma_f32_16x16x32_bf16 v[26:29], v[242:245], v[172:175], v[26:29]
	v_mfma_f32_16x16x32_bf16 v[14:17], v[226:229], v[180:183], v[14:17]
	v_mfma_f32_16x16x32_bf16 v[10:13], v[242:245], v[180:183], v[10:13]
	v_mfma_f32_16x16x32_bf16 v[6:9], v[226:229], v[206:209], v[6:9]
	v_mfma_f32_16x16x32_bf16 v[2:5], v[242:245], v[206:209], v[2:5]
	s_setprio 0
	s_add_i32 s40, 0, 0x18000
	v_add_u32_e32 v0, s40, v142
	s_barrier
	ds_read_b128 v[144:147], v0
	ds_read_b128 v[148:151], v0 offset:1024
	ds_read_b128 v[152:155], v0 offset:2048
	ds_read_b128 v[156:159], v0 offset:3072
	s_add_u32 s16, s16, 0x20000
	s_addc_u32 s17, s17, 0
	s_mov_b32 m0, s24
	ds_read_b128 v[160:163], v143 offset:32768
	ds_read_b128 v[164:167], v143 offset:33792
	ds_read_b128 v[168:171], v143 offset:34816
	ds_read_b128 v[172:175], v143 offset:35840
	ds_read_b128 v[176:179], v143 offset:36864
	ds_read_b128 v[180:183], v143 offset:37888
	ds_read_b128 v[202:205], v143 offset:38912
	ds_read_b128 v[206:209], v143 offset:39936
	global_load_lds_dwordx4 v136, s[16:17]
	s_mov_b32 m0, s25
	s_nop 0
	global_load_lds_dwordx4 v132, s[16:17]
	s_waitcnt lgkmcnt(8)
	s_barrier
	s_waitcnt lgkmcnt(0)
	s_setprio 1
	v_mfma_f32_16x16x32_bf16 v[126:129], v[144:147], v[160:163], v[126:129]
	v_mfma_f32_16x16x32_bf16 v[122:125], v[152:155], v[160:163], v[122:125]
	v_mfma_f32_16x16x32_bf16 v[118:121], v[144:147], v[168:171], v[118:121]
	v_mfma_f32_16x16x32_bf16 v[114:117], v[152:155], v[168:171], v[114:117]
	v_mfma_f32_16x16x32_bf16 v[102:105], v[144:147], v[176:179], v[102:105]
	v_mfma_f32_16x16x32_bf16 v[98:101], v[152:155], v[176:179], v[98:101]
	v_mfma_f32_16x16x32_bf16 v[86:89], v[144:147], v[202:205], v[86:89]
	v_mfma_f32_16x16x32_bf16 v[82:85], v[152:155], v[202:205], v[82:85]
	v_mfma_f32_16x16x32_bf16 v[126:129], v[148:151], v[164:167], v[126:129]
	v_mfma_f32_16x16x32_bf16 v[122:125], v[156:159], v[164:167], v[122:125]
	v_mfma_f32_16x16x32_bf16 v[118:121], v[148:151], v[172:175], v[118:121]
	v_mfma_f32_16x16x32_bf16 v[114:117], v[156:159], v[172:175], v[114:117]
	v_mfma_f32_16x16x32_bf16 v[102:105], v[148:151], v[180:183], v[102:105]
	v_mfma_f32_16x16x32_bf16 v[98:101], v[156:159], v[180:183], v[98:101]
	v_mfma_f32_16x16x32_bf16 v[86:89], v[148:151], v[206:209], v[86:89]
	v_mfma_f32_16x16x32_bf16 v[82:85], v[156:159], v[206:209], v[82:85]
	s_setprio 0
	s_barrier
	s_add_i32 s16, 0, 0x1c000
	s_add_i32 s17, s40, s21
	v_add_u32_e32 v0, s16, v142
	s_mov_b32 m0, s17
	ds_read_b128 v[210:213], v0
	ds_read_b128 v[226:229], v0 offset:1024
	ds_read_b128 v[238:241], v0 offset:2048
	ds_read_b128 v[242:245], v0 offset:3072
	global_load_lds_dwordx4 v134, s[98:99]
	s_add_i32 m0, s17, 0x2000
	s_nop 0
	global_load_lds_dwordx4 v130, s[98:99]
	s_barrier
	s_waitcnt lgkmcnt(0)
	s_setprio 1
	v_mfma_f32_16x16x32_bf16 v[110:113], v[210:213], v[160:163], v[110:113]
	v_mfma_f32_16x16x32_bf16 v[106:109], v[238:241], v[160:163], v[106:109]
	v_mfma_f32_16x16x32_bf16 v[94:97], v[210:213], v[168:171], v[94:97]
	v_mfma_f32_16x16x32_bf16 v[90:93], v[238:241], v[168:171], v[90:93]
	v_mfma_f32_16x16x32_bf16 v[78:81], v[210:213], v[176:179], v[78:81]
	v_mfma_f32_16x16x32_bf16 v[74:77], v[238:241], v[176:179], v[74:77]
	v_mfma_f32_16x16x32_bf16 v[70:73], v[210:213], v[202:205], v[70:73]
	v_mfma_f32_16x16x32_bf16 v[66:69], v[238:241], v[202:205], v[66:69]
	v_mfma_f32_16x16x32_bf16 v[110:113], v[226:229], v[164:167], v[110:113]
	v_mfma_f32_16x16x32_bf16 v[106:109], v[242:245], v[164:167], v[106:109]
	v_mfma_f32_16x16x32_bf16 v[94:97], v[226:229], v[172:175], v[94:97]
	v_mfma_f32_16x16x32_bf16 v[90:93], v[242:245], v[172:175], v[90:93]
	v_mfma_f32_16x16x32_bf16 v[78:81], v[226:229], v[180:183], v[78:81]
	v_mfma_f32_16x16x32_bf16 v[74:77], v[242:245], v[180:183], v[74:77]
	v_mfma_f32_16x16x32_bf16 v[70:73], v[226:229], v[206:209], v[70:73]
	v_mfma_f32_16x16x32_bf16 v[66:69], v[242:245], v[206:209], v[66:69]
	s_setprio 0
	s_mov_b32 m0, s28
	s_barrier
	ds_read_b128 v[160:163], v143 offset:49152
	ds_read_b128 v[164:167], v143 offset:50176
	ds_read_b128 v[168:171], v143 offset:51200
	ds_read_b128 v[172:175], v143 offset:52224
	ds_read_b128 v[176:179], v143 offset:53248
	ds_read_b128 v[180:183], v143 offset:54272
	ds_read_b128 v[202:205], v143 offset:55296
	ds_read_b128 v[206:209], v143 offset:56320
	global_load_lds_dwordx4 v136, s[100:101]
	s_mov_b32 m0, s29
	s_nop 0
	global_load_lds_dwordx4 v132, s[100:101]
	s_barrier
; #define PG8_STAGE(bufoff, gbase, voff) do { _Pragma("unroll") for (int _i = 0; _i < 2; ++_i) \
;     __builtin_amdgcn_global_load_lds((const unsigned*)((const char*)(gbase) + (voff)[_i]), (LAS unsigned*)(lds + (bufoff) + ldsw + _i * 8192), 16, 0, 0); } while (0)
; #define PG8_MMA(ai, bj, At, Bt) do { __builtin_amdgcn_s_setprio(1); _Pragma("unroll") for (int m = 0; m < 4; ++m) _Pragma("unroll") for (int n = 0; n < 2; ++n) _Pragma("unroll") for (int k = 0; k < 2; ++k) \
;     acc[ai][bj][m][n] = __builtin_amdgcn_mfma_f32_16x16x32_bf16(Bt[n][k], At[m][k], acc[ai][bj][m][n], 0, 0, 0); __builtin_amdgcn_s_setprio(0); } while (0)
; #define PG8_WAIT_V(n) asm volatile("s_waitcnt vmcnt(" #n ")" ::: "memory")
; #define PG8_WAIT_L(n) asm volatile("s_waitcnt lgkmcnt(" #n ")" ::: "memory")
; #define PG8_BAR __builtin_amdgcn_s_barrier()
; #define PG8_SCHED __builtin_amdgcn_sched_barrier(0)
; template <class Epi, class Sched>
; DI void gemm_phase(LAS unsigned char* lds, const int tid, const Gemm g, const Sched& S, const Epi& E) {
;     ...
;       PG8_BAR; PG8_WAIT_L(0); PG8_MMA(1, 0, At, B0); PG8_BAR; PG8_SCHED;
;       PG8_STAGE(PG8_SB(1, 1), b3 + hstepB, voffB);
;       PG8_WAIT_V(6); PG8_BAR; PG8_MMA(1, 1, At, B1); PG8_BAR;
	s_waitcnt lgkmcnt(0)
	s_setprio 1
	v_mfma_f32_16x16x32_bf16 v[62:65], v[144:147], v[160:163], v[62:65]
	v_mfma_f32_16x16x32_bf16 v[58:61], v[152:155], v[160:163], v[58:61]
	v_mfma_f32_16x16x32_bf16 v[54:57], v[144:147], v[168:171], v[54:57]
	v_mfma_f32_16x16x32_bf16 v[50:53], v[152:155], v[168:171], v[50:53]
	v_mfma_f32_16x16x32_bf16 v[38:41], v[144:147], v[176:179], v[38:41]
	v_mfma_f32_16x16x32_bf16 v[34:37], v[152:155], v[176:179], v[34:37]
	v_mfma_f32_16x16x32_bf16 v[22:25], v[144:147], v[202:205], v[22:25]
	v_mfma_f32_16x16x32_bf16 v[18:21], v[152:155], v[202:205], v[18:21]
	v_mfma_f32_16x16x32_bf16 v[62:65], v[148:151], v[164:167], v[62:65]
	v_mfma_f32_16x16x32_bf16 v[58:61], v[156:159], v[164:167], v[58:61]
	v_mfma_f32_16x16x32_bf16 v[54:57], v[148:151], v[172:175], v[54:57]
	v_mfma_f32_16x16x32_bf16 v[50:53], v[156:159], v[172:175], v[50:53]
	v_mfma_f32_16x16x32_bf16 v[38:41], v[148:151], v[180:183], v[38:41]
	v_mfma_f32_16x16x32_bf16 v[34:37], v[156:159], v[180:183], v[34:37]
	v_mfma_f32_16x16x32_bf16 v[22:25], v[148:151], v[206:209], v[22:25]
	v_mfma_f32_16x16x32_bf16 v[18:21], v[156:159], v[206:209], v[18:21]
	s_setprio 0
	s_barrier
	s_add_u32 s14, s14, 0x20080
	s_addc_u32 s15, s15, 0
	s_add_i32 s16, s16, s21
	s_mov_b32 m0, s16
	s_nop 0
	global_load_lds_dwordx4 v134, s[14:15]
	s_add_i32 m0, s16, 0x2000
	s_nop 0
	global_load_lds_dwordx4 v130, s[14:15]
	s_waitcnt vmcnt(6)
	s_barrier
	s_setprio 1
	v_mfma_f32_16x16x32_bf16 v[46:49], v[210:213], v[160:163], v[46:49]
	v_mfma_f32_16x16x32_bf16 v[42:45], v[238:241], v[160:163], v[42:45]
	v_mfma_f32_16x16x32_bf16 v[30:33], v[210:213], v[168:171], v[30:33]
	v_mfma_f32_16x16x32_bf16 v[26:29], v[238:241], v[168:171], v[26:29]
	v_mfma_f32_16x16x32_bf16 v[14:17], v[210:213], v[176:179], v[14:17]
	v_mfma_f32_16x16x32_bf16 v[10:13], v[238:241], v[176:179], v[10:13]
	v_mfma_f32_16x16x32_bf16 v[6:9], v[210:213], v[202:205], v[6:9]
	v_mfma_f32_16x16x32_bf16 v[2:5], v[238:241], v[202:205], v[2:5]
	v_mfma_f32_16x16x32_bf16 v[46:49], v[226:229], v[164:167], v[46:49]
	v_mfma_f32_16x16x32_bf16 v[42:45], v[242:245], v[164:167], v[42:45]
	v_mfma_f32_16x16x32_bf16 v[30:33], v[226:229], v[172:175], v[30:33]
	v_mfma_f32_16x16x32_bf16 v[26:29], v[242:245], v[172:175], v[26:29]
	v_mfma_f32_16x16x32_bf16 v[14:17], v[226:229], v[180:183], v[14:17]
	v_mfma_f32_16x16x32_bf16 v[10:13], v[242:245], v[180:183], v[10:13]
	v_mfma_f32_16x16x32_bf16 v[6:9], v[226:229], v[206:209], v[6:9]
	v_mfma_f32_16x16x32_bf16 v[2:5], v[242:245], v[206:209], v[2:5]
	s_setprio 0
	s_add_i32 s39, s39, 2
	s_add_u32 s37, s37, 0x100
	s_addc_u32 s38, s38, 0
	s_add_u32 s12, s12, 0x100
	s_addc_u32 s13, s13, 0
	s_cmp_gt_u32 s39, 5
	s_barrier
	s_cbranch_scc0 .LBB0_645
; DI void st8p(void* ub, unsigned voff, f32x4 a, f32x4 b) { u32x4 o = {pk(a[0], a[1]), pk(a[2], a[3]), pk(b[0], b[1]), pk(b[2], b[3])}; *(GAS u32x4*)((char*)ub + voff) = o; }
; #define ROWS_LOOP _Pragma("unroll") for (int ai = 0; ai < 2; ++ai) _Pragma("unroll") for (int m = 0; m < 4; ++m)
;   DI void operator()(const AccT& acc, const Unit& u, int wr, int wc, int fr, int fq) const {
;     const char* base = (const char*)(MIX + (ctx ? (size_t)(TL + u.pn * 256) : (size_t)(u.pn * 2048 + u.pm * 256)) * D);
;     const unsigned o0 = (unsigned)((wr * 64 + fr) * D + wc * 32 + fq * 8) * 2u;
;     ROWS_LOOP {
;       char* rb = (char*)base + (size_t)(ai * 128 + m * 16) * D * 2;
; #pragma unroll
;       for (int bj = 0; bj < 2; ++bj) st8p(rb + bj * 256, o0, acc[ai][bj][m][0], acc[ai][bj][m][1]);
;     }
;   }
	v_mov_b32_e32 v0, v1
	s_lshl_b32 s12, s34, 8
	v_mbcnt_lo_u32_b32 v0, -1, v0
	v_mbcnt_hi_u32_b32 v0, -1, v0
	s_ashr_i32 s13, s12, 31
	s_lshl_b64 s[12:13], s[12:13], 11
	v_lshlrev_b32_e32 v144, 11, v0
	s_add_u32 s12, s26, s12
	v_and_b32_e32 v144, 0x7800, v144
	v_and_b32_e32 v0, -16, v0
	s_addc_u32 s13, s27, s13
	v_add3_u32 v0, s30, v0, v144
	v_lshl_add_u64 v[144:145], s[12:13], 0, v[0:1]
	s_brev_b32 s5, 32
	s_mov_b64 s[12:13], 0x4000000
	v_cvt_pk_bf16_f32 v126, v126, v127
	v_cvt_pk_bf16_f32 v127, v128, v129
	v_cvt_pk_bf16_f32 v128, v122, v123
	v_add_co_u32_e32 v122, vcc, s5, v144
	v_lshl_add_u64 v[146:147], v[144:145], 0, s[12:13]
	s_nop 0
	v_addc_co_u32_e32 v123, vcc, 0, v145, vcc
	v_cvt_pk_bf16_f32 v110, v110, v111
	v_cvt_pk_bf16_f32 v111, v112, v113
	v_cvt_pk_bf16_f32 v112, v106, v107
	v_cvt_pk_bf16_f32 v113, v108, v109
	s_mov_b32 s5, 0x4008000
	global_store_dwordx4 v[146:147], v[110:113], off offset:256
	v_cvt_pk_bf16_f32 v94, v94, v95
	v_cvt_pk_bf16_f32 v95, v96, v97
	v_add_co_u32_e32 v110, vcc, s5, v144
	v_cvt_pk_bf16_f32 v96, v90, v91
	s_nop 0
	v_addc_co_u32_e32 v111, vcc, 0, v145, vcc
	v_cvt_pk_bf16_f32 v97, v92, v93
	s_mov_b32 s5, 0x4010000
	global_store_dwordx4 v[110:111], v[94:97], off offset:256
	v_cvt_pk_bf16_f32 v78, v78, v79
	v_cvt_pk_bf16_f32 v79, v80, v81
	v_add_co_u32_e32 v94, vcc, s5, v144
	v_cvt_pk_bf16_f32 v80, v74, v75
	s_nop 0
	v_addc_co_u32_e32 v95, vcc, 0, v145, vcc
	v_cvt_pk_bf16_f32 v81, v76, v77
	s_mov_b32 s5, 0x4018000
	global_store_dwordx4 v[94:95], v[78:81], off offset:256
	v_cvt_pk_bf16_f32 v62, v62, v63
	v_cvt_pk_bf16_f32 v63, v64, v65
	v_add_co_u32_e32 v78, vcc, s5, v144
	s_mov_b32 s5, 0x4040000
	s_nop 0
	v_addc_co_u32_e32 v79, vcc, 0, v145, vcc
	v_cvt_pk_bf16_f32 v64, v58, v59
	v_add_co_u32_e32 v58, vcc, s5, v144
	v_cvt_pk_bf16_f32 v46, v46, v47
	s_nop 0
	v_addc_co_u32_e32 v59, vcc, 0, v145, vcc
	v_cvt_pk_bf16_f32 v47, v48, v49
	v_cvt_pk_bf16_f32 v48, v42, v43
	v_cvt_pk_bf16_f32 v49, v44, v45
	s_mov_b32 s5, 0x4048000
	global_store_dwordx4 v[58:59], v[46:49], off offset:256
	v_cvt_pk_bf16_f32 v30, v30, v31
	v_cvt_pk_bf16_f32 v31, v32, v33
	v_add_co_u32_e32 v46, vcc, s5, v144
	v_cvt_pk_bf16_f32 v32, v26, v27
	s_nop 0
	v_addc_co_u32_e32 v47, vcc, 0, v145, vcc
	v_cvt_pk_bf16_f32 v33, v28, v29
	s_mov_b32 s5, 0x4050000
	global_store_dwordx4 v[46:47], v[30:33], off offset:256
	v_cvt_pk_bf16_f32 v14, v14, v15
	v_cvt_pk_bf16_f32 v15, v16, v17
	v_add_co_u32_e32 v30, vcc, s5, v144
	v_cvt_pk_bf16_f32 v16, v10, v11
	s_nop 0
	v_addc_co_u32_e32 v31, vcc, 0, v145, vcc
	v_cvt_pk_bf16_f32 v17, v12, v13
	s_mov_b32 s5, 0x4058000
	global_store_dwordx4 v[30:31], v[14:17], off offset:256
	v_cvt_pk_bf16_f32 v129, v124, v125
	v_cvt_pk_bf16_f32 v106, v118, v119
	v_add_co_u32_e32 v14, vcc, s5, v144
	v_cvt_pk_bf16_f32 v107, v120, v121
	s_nop 0
	v_addc_co_u32_e32 v15, vcc, 0, v145, vcc
	v_cvt_pk_bf16_f32 v108, v114, v115
	v_cvt_pk_bf16_f32 v109, v116, v117
	v_cvt_pk_bf16_f32 v90, v102, v103
	v_cvt_pk_bf16_f32 v91, v104, v105
	v_cvt_pk_bf16_f32 v92, v98, v99
	v_cvt_pk_bf16_f32 v93, v100, v101
	v_cvt_pk_bf16_f32 v74, v86, v87
	v_cvt_pk_bf16_f32 v75, v88, v89
	v_cvt_pk_bf16_f32 v76, v82, v83
	v_cvt_pk_bf16_f32 v77, v84, v85
	v_cvt_pk_bf16_f32 v70, v70, v71
	v_cvt_pk_bf16_f32 v71, v72, v73
	v_cvt_pk_bf16_f32 v72, v66, v67
	v_cvt_pk_bf16_f32 v73, v68, v69
	v_cvt_pk_bf16_f32 v65, v60, v61
	v_cvt_pk_bf16_f32 v42, v54, v55
	v_cvt_pk_bf16_f32 v43, v56, v57
	v_cvt_pk_bf16_f32 v44, v50, v51
	v_cvt_pk_bf16_f32 v45, v52, v53
	v_cvt_pk_bf16_f32 v26, v38, v39
	v_cvt_pk_bf16_f32 v27, v40, v41
	v_cvt_pk_bf16_f32 v28, v34, v35
	v_cvt_pk_bf16_f32 v29, v36, v37
	v_cvt_pk_bf16_f32 v10, v22, v23
	v_cvt_pk_bf16_f32 v11, v24, v25
	v_cvt_pk_bf16_f32 v12, v18, v19
	v_cvt_pk_bf16_f32 v13, v20, v21
	v_cvt_pk_bf16_f32 v6, v6, v7
	v_cvt_pk_bf16_f32 v7, v8, v9
	v_cvt_pk_bf16_f32 v8, v2, v3
	v_cvt_pk_bf16_f32 v9, v4, v5
	s_and_b64 vcc, exec, s[0:1]
	s_mov_b32 s34, s4
	s_mov_b64 s[12:13], s[10:11]
	s_mov_b64 s[16:17], s[8:9]
	global_store_dwordx4 v[122:123], v[126:129], off
	global_store_dwordx4 v[110:111], v[106:109], off
	global_store_dwordx4 v[94:95], v[90:93], off
	global_store_dwordx4 v[78:79], v[74:77], off
	global_store_dwordx4 v[78:79], v[70:73], off offset:256
	global_store_dwordx4 v[58:59], v[62:65], off
	global_store_dwordx4 v[46:47], v[42:45], off
	global_store_dwordx4 v[30:31], v[26:29], off
	global_store_dwordx4 v[14:15], v[10:13], off
	global_store_dwordx4 v[14:15], v[6:9], off offset:256
	s_cbranch_vccz .LBB0_642
	s_waitcnt vmcnt(0)
	s_cmpk_gt_u32 s2, 0xff
	s_cbranch_scc1 .LBB0_649
	s_barrier

; #define PG8_STAGE(bufoff, gbase, voff) do { _Pragma("unroll") for (int _i = 0; _i < 2; ++_i) \
;     __builtin_amdgcn_global_load_lds((const unsigned*)((const char*)(gbase) + (voff)[_i]), (LAS unsigned*)(lds + (bufoff) + ldsw + _i * 8192), 16, 0, 0); } while (0)
; #define PG8_LDA(dst, b, h) do { _Pragma("unroll") for (int m = 0; m < 4; ++m) _Pragma("unroll") for (int k = 0; k < 2; ++k) dst[m][k] = *(const LAS bf16x8*)(lds + PG8_SA(b, h) + aoff + m * 2048 + k * 1024); } while (0)
; #define PG8_LDB(dst, b, h) do { _Pragma("unroll") for (int n = 0; n < 2; ++n) _Pragma("unroll") for (int k = 0; k < 2; ++k) dst[n][k] = *(const LAS bf16x8*)(lds + PG8_SB(b, h) + boff + n * 2048 + k * 1024); } while (0)
; #define PG8_MMA(ai, bj, At, Bt) do { __builtin_amdgcn_s_setprio(1); _Pragma("unroll") for (int m = 0; m < 4; ++m) _Pragma("unroll") for (int n = 0; n < 2; ++n) _Pragma("unroll") for (int k = 0; k < 2; ++k) \
;     acc[ai][bj][m][n] = __builtin_amdgcn_mfma_f32_16x16x32_bf16(Bt[n][k], At[m][k], acc[ai][bj][m][n], 0, 0, 0); __builtin_amdgcn_s_setprio(0); } while (0)
; #define PG8_WAIT_L(n) asm volatile("s_waitcnt lgkmcnt(" #n ")" ::: "memory")
; #define PG8_BAR __builtin_amdgcn_s_barrier()
; template <class Epi, class Sched>
; DI void gemm_phase(LAS unsigned char* lds, const int tid, const Gemm g, const Sched& S, const Epi& E) {
;     ...
;   for (;;) {
;     const bool has_next = S.next(ui + 1, nxt);
;     const char* nA = has_next ? (const char*)g.A + (size_t)nxt.pm * tstepA : cA; const char* nB = has_next ? (const char*)g.Bt + (size_t)nxt.pn * tstepB : cB;
; #pragma unroll 1
;     for (int t = 0; t < nt; t += 2) {
;       const bool last = (t == nt - 2);
;       const char* a1 = cA + (size_t)(t + 1) * kstep;
;       const char* a2 = last ? nA : cA + (size_t)(t + 2) * kstep; const char* b2 = last ? nB : cB + (size_t)(t + 2) * kstep;
;       const char* a3 = a2 + kstep; const char* b3 = b2 + kstep;
;       PG8_LDB(B0, 0, 0); PG8_SCHED; PG8_LDA(At, 0, 0); PG8_STAGE(PG8_SA(1, 1), a1 + hstepA, voffA);
;       PG8_WAIT_L(8); PG8_BAR; PG8_WAIT_L(0); PG8_MMA(0, 0, At, B0); PG8_BAR; PG8_SCHED;
;       PG8_LDB(B1, 0, 1); PG8_STAGE(PG8_SB(0, 0), b2, voffB);
;       PG8_BAR; PG8_WAIT_L(0); PG8_MMA(0, 1, At, B1); PG8_BAR;
;       PG8_LDA(At, 0, 1); PG8_STAGE(PG8_SA(0, 0), a2, voffA);
;       PG8_BAR; PG8_WAIT_L(0); PG8_MMA(1, 0, At, B0); PG8_BAR; PG8_SCHED;
.LBB0_659:
	s_add_u32 s14, s12, 0xfff00080
	s_addc_u32 s15, s13, -1
	s_add_i32 s41, 0, 0x10000
	v_add_u32_e32 v0, s41, v142
	ds_read_b128 v[144:147], v0
	ds_read_b128 v[148:151], v0 offset:1024
	ds_read_b128 v[152:155], v0 offset:2048
	ds_read_b128 v[156:159], v0 offset:3072
	s_cmp_eq_u32 s40, 60
	s_cselect_b32 s17, s7, s15
	s_cselect_b32 s16, s36, s14
	s_cselect_b32 s15, s1, s39
	s_cselect_b32 s14, s37, s38
	s_add_i32 m0, s22, 0xc000
	ds_read_b128 v[160:163], v143
	ds_read_b128 v[164:167], v143 offset:1024
	ds_read_b128 v[168:171], v143 offset:2048
	ds_read_b128 v[172:175], v143 offset:3072
	ds_read_b128 v[176:179], v143 offset:4096
	ds_read_b128 v[180:183], v143 offset:5120
	ds_read_b128 v[202:205], v143 offset:6144
	ds_read_b128 v[206:209], v143 offset:7168
	global_load_lds_dwordx4 v140, s[12:13]
	s_add_i32 m0, s22, 0xe000
	s_nop 0
	global_load_lds_dwordx4 v138, s[12:13]
	s_waitcnt lgkmcnt(8)
	s_barrier
	s_waitcnt lgkmcnt(0)
	s_setprio 1
	v_mfma_f32_16x16x32_bf16 v[126:129], v[144:147], v[160:163], v[126:129]
	v_mfma_f32_16x16x32_bf16 v[122:125], v[152:155], v[160:163], v[122:125]
	v_mfma_f32_16x16x32_bf16 v[118:121], v[144:147], v[168:171], v[118:121]
	v_mfma_f32_16x16x32_bf16 v[114:117], v[152:155], v[168:171], v[114:117]
	v_mfma_f32_16x16x32_bf16 v[102:105], v[144:147], v[176:179], v[102:105]
	v_mfma_f32_16x16x32_bf16 v[98:101], v[152:155], v[176:179], v[98:101]
	v_mfma_f32_16x16x32_bf16 v[86:89], v[144:147], v[202:205], v[86:89]
	v_mfma_f32_16x16x32_bf16 v[82:85], v[152:155], v[202:205], v[82:85]
	v_mfma_f32_16x16x32_bf16 v[126:129], v[148:151], v[164:167], v[126:129]
	v_mfma_f32_16x16x32_bf16 v[122:125], v[156:159], v[164:167], v[122:125]
	v_mfma_f32_16x16x32_bf16 v[118:121], v[148:151], v[172:175], v[118:121]
	v_mfma_f32_16x16x32_bf16 v[114:117], v[156:159], v[172:175], v[114:117]
	v_mfma_f32_16x16x32_bf16 v[102:105], v[148:151], v[180:183], v[102:105]
	v_mfma_f32_16x16x32_bf16 v[98:101], v[156:159], v[180:183], v[98:101]
	v_mfma_f32_16x16x32_bf16 v[86:89], v[148:151], v[206:209], v[86:89]
	v_mfma_f32_16x16x32_bf16 v[82:85], v[156:159], v[206:209], v[82:85]
	s_setprio 0
	s_barrier
	s_add_i32 s44, 0, 0x14000
	s_add_i32 s41, s41, s21
	v_add_u32_e32 v0, s44, v142
	s_add_u32 s98, s14, s50
	s_addc_u32 s99, s15, s51
	s_mov_b32 m0, s41
	ds_read_b128 v[210:213], v0
	ds_read_b128 v[226:229], v0 offset:1024
	ds_read_b128 v[238:241], v0 offset:2048
	ds_read_b128 v[242:245], v0 offset:3072
	global_load_lds_dwordx4 v134, s[14:15]
	s_add_i32 m0, s41, 0x2000
	s_nop 0
	global_load_lds_dwordx4 v130, s[14:15]
	s_barrier
	s_waitcnt lgkmcnt(0)
	s_setprio 1
	v_mfma_f32_16x16x32_bf16 v[110:113], v[210:213], v[160:163], v[110:113]
	v_mfma_f32_16x16x32_bf16 v[106:109], v[238:241], v[160:163], v[106:109]
	v_mfma_f32_16x16x32_bf16 v[94:97], v[210:213], v[168:171], v[94:97]
	v_mfma_f32_16x16x32_bf16 v[90:93], v[238:241], v[168:171], v[90:93]
	v_mfma_f32_16x16x32_bf16 v[78:81], v[210:213], v[176:179], v[78:81]
	v_mfma_f32_16x16x32_bf16 v[74:77], v[238:241], v[176:179], v[74:77]
	v_mfma_f32_16x16x32_bf16 v[70:73], v[210:213], v[202:205], v[70:73]
	v_mfma_f32_16x16x32_bf16 v[66:69], v[238:241], v[202:205], v[66:69]
	v_mfma_f32_16x16x32_bf16 v[110:113], v[226:229], v[164:167], v[110:113]
	v_mfma_f32_16x16x32_bf16 v[106:109], v[242:245], v[164:167], v[106:109]
	v_mfma_f32_16x16x32_bf16 v[94:97], v[226:229], v[172:175], v[94:97]
	v_mfma_f32_16x16x32_bf16 v[90:93], v[242:245], v[172:175], v[90:93]
	v_mfma_f32_16x16x32_bf16 v[78:81], v[226:229], v[180:183], v[78:81]
	v_mfma_f32_16x16x32_bf16 v[74:77], v[242:245], v[180:183], v[74:77]
	v_mfma_f32_16x16x32_bf16 v[70:73], v[226:229], v[206:209], v[70:73]
	v_mfma_f32_16x16x32_bf16 v[66:69], v[242:245], v[206:209], v[66:69]
	s_setprio 0
	s_mov_b32 m0, s22
	s_add_u32 s100, s16, s50
	s_addc_u32 s101, s17, s51
	s_barrier
	ds_read_b128 v[160:163], v143 offset:16384
	ds_read_b128 v[164:167], v143 offset:17408
	ds_read_b128 v[168:171], v143 offset:18432
	ds_read_b128 v[172:175], v143 offset:19456
	ds_read_b128 v[176:179], v143 offset:20480
	ds_read_b128 v[180:183], v143 offset:21504
	ds_read_b128 v[202:205], v143 offset:22528
	ds_read_b128 v[206:209], v143 offset:23552
	global_load_lds_dwordx4 v136, s[16:17]
	s_mov_b32 m0, s23
	s_nop 0
	global_load_lds_dwordx4 v132, s[16:17]
	s_barrier
	s_waitcnt lgkmcnt(0)
	s_setprio 1
	v_mfma_f32_16x16x32_bf16 v[62:65], v[144:147], v[160:163], v[62:65]
	v_mfma_f32_16x16x32_bf16 v[58:61], v[152:155], v[160:163], v[58:61]
	v_mfma_f32_16x16x32_bf16 v[54:57], v[144:147], v[168:171], v[54:57]
	v_mfma_f32_16x16x32_bf16 v[50:53], v[152:155], v[168:171], v[50:53]
	v_mfma_f32_16x16x32_bf16 v[38:41], v[144:147], v[176:179], v[38:41]
	v_mfma_f32_16x16x32_bf16 v[34:37], v[152:155], v[176:179], v[34:37]
	v_mfma_f32_16x16x32_bf16 v[22:25], v[144:147], v[202:205], v[22:25]
	v_mfma_f32_16x16x32_bf16 v[18:21], v[152:155], v[202:205], v[18:21]
	v_mfma_f32_16x16x32_bf16 v[62:65], v[148:151], v[164:167], v[62:65]
	v_mfma_f32_16x16x32_bf16 v[58:61], v[156:159], v[164:167], v[58:61]
	v_mfma_f32_16x16x32_bf16 v[54:57], v[148:151], v[172:175], v[54:57]
	v_mfma_f32_16x16x32_bf16 v[50:53], v[156:159], v[172:175], v[50:53]
	v_mfma_f32_16x16x32_bf16 v[38:41], v[148:151], v[180:183], v[38:41]
	v_mfma_f32_16x16x32_bf16 v[34:37], v[156:159], v[180:183], v[34:37]
	v_mfma_f32_16x16x32_bf16 v[22:25], v[148:151], v[206:209], v[22:25]
	v_mfma_f32_16x16x32_bf16 v[18:21], v[156:159], v[206:209], v[18:21]
	s_setprio 0
	s_barrier
	s_add_u32 s42, s14, 0x100000
	s_addc_u32 s43, s15, 0
	s_add_i32 s41, s44, s21
	s_mov_b32 m0, s41
	s_nop 0
	global_load_lds_dwordx4 v134, s[42:43]
	s_add_i32 m0, s41, 0x2000
	s_nop 0
	global_load_lds_dwordx4 v130, s[42:43]
	s_waitcnt vmcnt(6)
	s_barrier
; #define PG8_STAGE(bufoff, gbase, voff) do { _Pragma("unroll") for (int _i = 0; _i < 2; ++_i) \
;     __builtin_amdgcn_global_load_lds((const unsigned*)((const char*)(gbase) + (voff)[_i]), (LAS unsigned*)(lds + (bufoff) + ldsw + _i * 8192), 16, 0, 0); } while (0)
; #define PG8_LDA(dst, b, h) do { _Pragma("unroll") for (int m = 0; m < 4; ++m) _Pragma("unroll") for (int k = 0; k < 2; ++k) dst[m][k] = *(const LAS bf16x8*)(lds + PG8_SA(b, h) + aoff + m * 2048 + k * 1024); } while (0)
; #define PG8_LDB(dst, b, h) do { _Pragma("unroll") for (int n = 0; n < 2; ++n) _Pragma("unroll") for (int k = 0; k < 2; ++k) dst[n][k] = *(const LAS bf16x8*)(lds + PG8_SB(b, h) + boff + n * 2048 + k * 1024); } while (0)
; #define PG8_MMA(ai, bj, At, Bt) do { __builtin_amdgcn_s_setprio(1); _Pragma("unroll") for (int m = 0; m < 4; ++m) _Pragma("unroll") for (int n = 0; n < 2; ++n) _Pragma("unroll") for (int k = 0; k < 2; ++k) \
;     acc[ai][bj][m][n] = __builtin_amdgcn_mfma_f32_16x16x32_bf16(Bt[n][k], At[m][k], acc[ai][bj][m][n], 0, 0, 0); __builtin_amdgcn_s_setprio(0); } while (0)
; #define PG8_WAIT_V(n) asm volatile("s_waitcnt vmcnt(" #n ")" ::: "memory")
; #define PG8_WAIT_L(n) asm volatile("s_waitcnt lgkmcnt(" #n ")" ::: "memory")
; #define PG8_BAR __builtin_amdgcn_s_barrier()
; #define PG8_SCHED __builtin_amdgcn_sched_barrier(0)
; template <class Epi, class Sched>
; DI void gemm_phase(LAS unsigned char* lds, const int tid, const Gemm g, const Sched& S, const Epi& E) {
;     ...
;       PG8_WAIT_V(6); PG8_BAR; PG8_MMA(1, 1, At, B1); PG8_BAR;
;       PG8_LDB(B0, 1, 0); PG8_SCHED; PG8_LDA(At, 1, 0); PG8_STAGE(PG8_SA(0, 1), a2 + hstepA, voffA);
;       PG8_WAIT_L(8); PG8_BAR; PG8_WAIT_L(0); PG8_MMA(0, 0, At, B0); PG8_BAR; PG8_SCHED;
;       PG8_LDB(B1, 1, 1); PG8_STAGE(PG8_SB(1, 0), b3, voffB);
;       PG8_BAR; PG8_WAIT_L(0); PG8_MMA(0, 1, At, B1); PG8_BAR;
;       PG8_LDA(At, 1, 1); PG8_STAGE(PG8_SA(1, 0), a3, voffA);
;       PG8_BAR; PG8_WAIT_L(0); PG8_MMA(1, 0, At, B0); PG8_BAR; PG8_SCHED;
	s_setprio 1
	v_mfma_f32_16x16x32_bf16 v[46:49], v[210:213], v[160:163], v[46:49]
	v_mfma_f32_16x16x32_bf16 v[42:45], v[238:241], v[160:163], v[42:45]
	v_mfma_f32_16x16x32_bf16 v[30:33], v[210:213], v[168:171], v[30:33]
	v_mfma_f32_16x16x32_bf16 v[26:29], v[238:241], v[168:171], v[26:29]
	v_mfma_f32_16x16x32_bf16 v[14:17], v[210:213], v[176:179], v[14:17]
	v_mfma_f32_16x16x32_bf16 v[10:13], v[238:241], v[176:179], v[10:13]
	v_mfma_f32_16x16x32_bf16 v[6:9], v[210:213], v[202:205], v[6:9]
	v_mfma_f32_16x16x32_bf16 v[2:5], v[238:241], v[202:205], v[2:5]
	v_mfma_f32_16x16x32_bf16 v[46:49], v[226:229], v[164:167], v[46:49]
	v_mfma_f32_16x16x32_bf16 v[42:45], v[242:245], v[164:167], v[42:45]
	v_mfma_f32_16x16x32_bf16 v[30:33], v[226:229], v[172:175], v[30:33]
	v_mfma_f32_16x16x32_bf16 v[26:29], v[242:245], v[172:175], v[26:29]
	v_mfma_f32_16x16x32_bf16 v[14:17], v[226:229], v[180:183], v[14:17]
	v_mfma_f32_16x16x32_bf16 v[10:13], v[242:245], v[180:183], v[10:13]
	v_mfma_f32_16x16x32_bf16 v[6:9], v[226:229], v[206:209], v[6:9]
	v_mfma_f32_16x16x32_bf16 v[2:5], v[242:245], v[206:209], v[2:5]
	s_setprio 0
	s_add_i32 s41, 0, 0x18000
	v_add_u32_e32 v0, s41, v142
	s_barrier
	ds_read_b128 v[144:147], v0
	ds_read_b128 v[148:151], v0 offset:1024
	ds_read_b128 v[152:155], v0 offset:2048
	ds_read_b128 v[156:159], v0 offset:3072
	s_add_u32 s16, s16, 0x100000
	s_addc_u32 s17, s17, 0
	s_mov_b32 m0, s24
	ds_read_b128 v[160:163], v143 offset:32768
	ds_read_b128 v[164:167], v143 offset:33792
	ds_read_b128 v[168:171], v143 offset:34816
	ds_read_b128 v[172:175], v143 offset:35840
	ds_read_b128 v[176:179], v143 offset:36864
	ds_read_b128 v[180:183], v143 offset:37888
	ds_read_b128 v[202:205], v143 offset:38912
	ds_read_b128 v[206:209], v143 offset:39936
	global_load_lds_dwordx4 v136, s[16:17]
	s_mov_b32 m0, s25
	s_nop 0
	global_load_lds_dwordx4 v132, s[16:17]
	s_waitcnt lgkmcnt(8)
	s_barrier
	s_waitcnt lgkmcnt(0)
	s_setprio 1
	v_mfma_f32_16x16x32_bf16 v[126:129], v[144:147], v[160:163], v[126:129]
	v_mfma_f32_16x16x32_bf16 v[122:125], v[152:155], v[160:163], v[122:125]
	v_mfma_f32_16x16x32_bf16 v[118:121], v[144:147], v[168:171], v[118:121]
	v_mfma_f32_16x16x32_bf16 v[114:117], v[152:155], v[168:171], v[114:117]
	v_mfma_f32_16x16x32_bf16 v[102:105], v[144:147], v[176:179], v[102:105]
	v_mfma_f32_16x16x32_bf16 v[98:101], v[152:155], v[176:179], v[98:101]
	v_mfma_f32_16x16x32_bf16 v[86:89], v[144:147], v[202:205], v[86:89]
	v_mfma_f32_16x16x32_bf16 v[82:85], v[152:155], v[202:205], v[82:85]
	v_mfma_f32_16x16x32_bf16 v[126:129], v[148:151], v[164:167], v[126:129]
	v_mfma_f32_16x16x32_bf16 v[122:125], v[156:159], v[164:167], v[122:125]
	v_mfma_f32_16x16x32_bf16 v[118:121], v[148:151], v[172:175], v[118:121]
	v_mfma_f32_16x16x32_bf16 v[114:117], v[156:159], v[172:175], v[114:117]
	v_mfma_f32_16x16x32_bf16 v[102:105], v[148:151], v[180:183], v[102:105]
	v_mfma_f32_16x16x32_bf16 v[98:101], v[156:159], v[180:183], v[98:101]
	v_mfma_f32_16x16x32_bf16 v[86:89], v[148:151], v[206:209], v[86:89]
	v_mfma_f32_16x16x32_bf16 v[82:85], v[156:159], v[206:209], v[82:85]
	s_setprio 0
	s_barrier
	s_add_i32 s16, 0, 0x1c000
	s_add_i32 s17, s41, s21
	v_add_u32_e32 v0, s16, v142
	s_mov_b32 m0, s17
	ds_read_b128 v[210:213], v0
	ds_read_b128 v[226:229], v0 offset:1024
	ds_read_b128 v[238:241], v0 offset:2048
	ds_read_b128 v[242:245], v0 offset:3072
	global_load_lds_dwordx4 v134, s[98:99]
	s_add_i32 m0, s17, 0x2000
	s_nop 0
	global_load_lds_dwordx4 v130, s[98:99]
	s_barrier
	s_waitcnt lgkmcnt(0)
	s_setprio 1
	v_mfma_f32_16x16x32_bf16 v[110:113], v[210:213], v[160:163], v[110:113]
	v_mfma_f32_16x16x32_bf16 v[106:109], v[238:241], v[160:163], v[106:109]
	v_mfma_f32_16x16x32_bf16 v[94:97], v[210:213], v[168:171], v[94:97]
	v_mfma_f32_16x16x32_bf16 v[90:93], v[238:241], v[168:171], v[90:93]
	v_mfma_f32_16x16x32_bf16 v[78:81], v[210:213], v[176:179], v[78:81]
	v_mfma_f32_16x16x32_bf16 v[74:77], v[238:241], v[176:179], v[74:77]
	v_mfma_f32_16x16x32_bf16 v[70:73], v[210:213], v[202:205], v[70:73]
	v_mfma_f32_16x16x32_bf16 v[66:69], v[238:241], v[202:205], v[66:69]
	v_mfma_f32_16x16x32_bf16 v[110:113], v[226:229], v[164:167], v[110:113]
	v_mfma_f32_16x16x32_bf16 v[106:109], v[242:245], v[164:167], v[106:109]
	v_mfma_f32_16x16x32_bf16 v[94:97], v[226:229], v[172:175], v[94:97]
	v_mfma_f32_16x16x32_bf16 v[90:93], v[242:245], v[172:175], v[90:93]
	v_mfma_f32_16x16x32_bf16 v[78:81], v[226:229], v[180:183], v[78:81]
	v_mfma_f32_16x16x32_bf16 v[74:77], v[242:245], v[180:183], v[74:77]
	v_mfma_f32_16x16x32_bf16 v[70:73], v[226:229], v[206:209], v[70:73]
	v_mfma_f32_16x16x32_bf16 v[66:69], v[242:245], v[206:209], v[66:69]
	s_setprio 0
	s_mov_b32 m0, s28
	s_barrier
	ds_read_b128 v[160:163], v143 offset:49152
	ds_read_b128 v[164:167], v143 offset:50176
	ds_read_b128 v[168:171], v143 offset:51200
	ds_read_b128 v[172:175], v143 offset:52224
	ds_read_b128 v[176:179], v143 offset:53248
	ds_read_b128 v[180:183], v143 offset:54272
	ds_read_b128 v[202:205], v143 offset:55296
	ds_read_b128 v[206:209], v143 offset:56320
	global_load_lds_dwordx4 v136, s[100:101]
	s_mov_b32 m0, s29
	s_nop 0
	global_load_lds_dwordx4 v132, s[100:101]
	s_barrier
; #define PG8_STAGE(bufoff, gbase, voff) do { _Pragma("unroll") for (int _i = 0; _i < 2; ++_i) \
;     __builtin_amdgcn_global_load_lds((const unsigned*)((const char*)(gbase) + (voff)[_i]), (LAS unsigned*)(lds + (bufoff) + ldsw + _i * 8192), 16, 0, 0); } while (0)
; #define PG8_MMA(ai, bj, At, Bt) do { __builtin_amdgcn_s_setprio(1); _Pragma("unroll") for (int m = 0; m < 4; ++m) _Pragma("unroll") for (int n = 0; n < 2; ++n) _Pragma("unroll") for (int k = 0; k < 2; ++k) \
;     acc[ai][bj][m][n] = __builtin_amdgcn_mfma_f32_16x16x32_bf16(Bt[n][k], At[m][k], acc[ai][bj][m][n], 0, 0, 0); __builtin_amdgcn_s_setprio(0); } while (0)
; #define PG8_WAIT_V(n) asm volatile("s_waitcnt vmcnt(" #n ")" ::: "memory")
; #define PG8_WAIT_L(n) asm volatile("s_waitcnt lgkmcnt(" #n ")" ::: "memory")
; #define PG8_BAR __builtin_amdgcn_s_barrier()
; #define PG8_SCHED __builtin_amdgcn_sched_barrier(0)
; template <class Epi, class Sched>
; DI void gemm_phase(LAS unsigned char* lds, const int tid, const Gemm g, const Sched& S, const Epi& E) {
;     ...
;       PG8_BAR; PG8_WAIT_L(0); PG8_MMA(1, 0, At, B0); PG8_BAR; PG8_SCHED;
;       PG8_STAGE(PG8_SB(1, 1), b3 + hstepB, voffB);
;       PG8_WAIT_V(6); PG8_BAR; PG8_MMA(1, 1, At, B1); PG8_BAR;
	s_waitcnt lgkmcnt(0)
	s_setprio 1
	v_mfma_f32_16x16x32_bf16 v[62:65], v[144:147], v[160:163], v[62:65]
	v_mfma_f32_16x16x32_bf16 v[58:61], v[152:155], v[160:163], v[58:61]
	v_mfma_f32_16x16x32_bf16 v[54:57], v[144:147], v[168:171], v[54:57]
	v_mfma_f32_16x16x32_bf16 v[50:53], v[152:155], v[168:171], v[50:53]
	v_mfma_f32_16x16x32_bf16 v[38:41], v[144:147], v[176:179], v[38:41]
	v_mfma_f32_16x16x32_bf16 v[34:37], v[152:155], v[176:179], v[34:37]
	v_mfma_f32_16x16x32_bf16 v[22:25], v[144:147], v[202:205], v[22:25]
	v_mfma_f32_16x16x32_bf16 v[18:21], v[152:155], v[202:205], v[18:21]
	v_mfma_f32_16x16x32_bf16 v[62:65], v[148:151], v[164:167], v[62:65]
	v_mfma_f32_16x16x32_bf16 v[58:61], v[156:159], v[164:167], v[58:61]
	v_mfma_f32_16x16x32_bf16 v[54:57], v[148:151], v[172:175], v[54:57]
	v_mfma_f32_16x16x32_bf16 v[50:53], v[156:159], v[172:175], v[50:53]
	v_mfma_f32_16x16x32_bf16 v[38:41], v[148:151], v[180:183], v[38:41]
	v_mfma_f32_16x16x32_bf16 v[34:37], v[156:159], v[180:183], v[34:37]
	v_mfma_f32_16x16x32_bf16 v[22:25], v[148:151], v[206:209], v[22:25]
	v_mfma_f32_16x16x32_bf16 v[18:21], v[156:159], v[206:209], v[18:21]
	s_setprio 0
	s_barrier
	s_add_u32 s14, s14, 0x100080
	s_addc_u32 s15, s15, 0
	s_add_i32 s16, s16, s21
	s_mov_b32 m0, s16
	s_nop 0
	global_load_lds_dwordx4 v134, s[14:15]
	s_add_i32 m0, s16, 0x2000
	s_nop 0
	global_load_lds_dwordx4 v130, s[14:15]
	s_waitcnt vmcnt(6)
	s_barrier
	s_setprio 1
	v_mfma_f32_16x16x32_bf16 v[46:49], v[210:213], v[160:163], v[46:49]
	v_mfma_f32_16x16x32_bf16 v[42:45], v[238:241], v[160:163], v[42:45]
	v_mfma_f32_16x16x32_bf16 v[30:33], v[210:213], v[168:171], v[30:33]
	v_mfma_f32_16x16x32_bf16 v[26:29], v[238:241], v[168:171], v[26:29]
	v_mfma_f32_16x16x32_bf16 v[14:17], v[210:213], v[176:179], v[14:17]
	v_mfma_f32_16x16x32_bf16 v[10:13], v[238:241], v[176:179], v[10:13]
	v_mfma_f32_16x16x32_bf16 v[6:9], v[210:213], v[202:205], v[6:9]
	v_mfma_f32_16x16x32_bf16 v[2:5], v[238:241], v[202:205], v[2:5]
	v_mfma_f32_16x16x32_bf16 v[46:49], v[226:229], v[164:167], v[46:49]
	v_mfma_f32_16x16x32_bf16 v[42:45], v[242:245], v[164:167], v[42:45]
	v_mfma_f32_16x16x32_bf16 v[30:33], v[226:229], v[172:175], v[30:33]
	v_mfma_f32_16x16x32_bf16 v[26:29], v[242:245], v[172:175], v[26:29]
	v_mfma_f32_16x16x32_bf16 v[14:17], v[226:229], v[180:183], v[14:17]
	v_mfma_f32_16x16x32_bf16 v[10:13], v[242:245], v[180:183], v[10:13]
	v_mfma_f32_16x16x32_bf16 v[6:9], v[226:229], v[206:209], v[6:9]
	v_mfma_f32_16x16x32_bf16 v[2:5], v[242:245], v[206:209], v[2:5]
	s_setprio 0
	s_add_i32 s40, s40, 2
	s_add_u32 s38, s38, 0x100
	s_addc_u32 s39, s39, 0
	s_add_u32 s12, s12, 0x100
	s_addc_u32 s13, s13, 0
	s_cmp_gt_u32 s40, 61
	s_barrier
	s_cbranch_scc0 .LBB0_659
; DI void st8p(void* ub, unsigned voff, f32x4 a, f32x4 b) { u32x4 o = {pk(a[0], a[1]), pk(a[2], a[3]), pk(b[0], b[1]), pk(b[2], b[3])}; *(GAS u32x4*)((char*)ub + voff) = o; }
; #define ROWS_LOOP _Pragma("unroll") for (int ai = 0; ai < 2; ++ai) _Pragma("unroll") for (int m = 0; m < 4; ++m)
;   DI void operator()(const AccT& acc, const Unit& u, int wr, int wc, int fr, int fq) const {
;     const char* base = (const char*)(MIX + (ctx ? (size_t)(TL + u.pn * 256) : (size_t)(u.pn * 2048 + u.pm * 256)) * D);
;     const unsigned o0 = (unsigned)((wr * 64 + fr) * D + wc * 32 + fq * 8) * 2u;
;     ROWS_LOOP {
;       char* rb = (char*)base + (size_t)(ai * 128 + m * 16) * D * 2;
; #pragma unroll
;       for (int bj = 0; bj < 2; ++bj) st8p(rb + bj * 256, o0, acc[ai][bj][m][0], acc[ai][bj][m][1]);
;     }
;   }
	v_mov_b32_e32 v0, v1
	s_lshl_b32 s1, s34, 11
	s_lshl_b32 s7, s35, 8
	v_mbcnt_lo_u32_b32 v0, -1, v0
	s_add_i32 s12, s7, s1
	v_mbcnt_hi_u32_b32 v0, -1, v0
	s_ashr_i32 s13, s12, 31
	s_lshl_b64 s[12:13], s[12:13], 11
	v_lshlrev_b32_e32 v144, 11, v0
	s_add_u32 s12, s26, s12
	v_and_b32_e32 v144, 0x7800, v144
	v_and_b32_e32 v0, -16, v0
	s_addc_u32 s13, s27, s13
	v_add3_u32 v0, s30, v0, v144
	v_lshl_add_u64 v[144:145], s[12:13], 0, v[0:1]
	v_cvt_pk_bf16_f32 v110, v110, v111
	v_cvt_pk_bf16_f32 v111, v112, v113
	v_cvt_pk_bf16_f32 v112, v106, v107
	v_cvt_pk_bf16_f32 v113, v108, v109
	s_mov_b32 s1, 0x8000
	global_store_dwordx4 v0, v[110:113], s[12:13] offset:256
	v_cvt_pk_bf16_f32 v94, v94, v95
	v_cvt_pk_bf16_f32 v95, v96, v97
	v_add_co_u32_e32 v110, vcc, s1, v144
	v_cvt_pk_bf16_f32 v96, v90, v91
	s_nop 0
	v_addc_co_u32_e32 v111, vcc, 0, v145, vcc
	v_cvt_pk_bf16_f32 v97, v92, v93
	global_store_dwordx4 v[110:111], v[94:97], off offset:256
	v_cvt_pk_bf16_f32 v78, v78, v79
	v_cvt_pk_bf16_f32 v79, v80, v81
	v_add_co_u32_e32 v94, vcc, s68, v144
	v_cvt_pk_bf16_f32 v80, v74, v75
	s_nop 0
	v_addc_co_u32_e32 v95, vcc, 0, v145, vcc
	v_cvt_pk_bf16_f32 v81, v76, v77
	s_mov_b32 s1, 0x18000
	global_store_dwordx4 v[94:95], v[78:81], off offset:256
	v_cvt_pk_bf16_f32 v62, v62, v63
	v_cvt_pk_bf16_f32 v63, v64, v65
	v_add_co_u32_e32 v78, vcc, s1, v144
	s_mov_b32 s1, 0x40000
	s_nop 0
	v_addc_co_u32_e32 v79, vcc, 0, v145, vcc
	v_cvt_pk_bf16_f32 v64, v58, v59
	v_add_co_u32_e32 v58, vcc, s1, v144
	v_cvt_pk_bf16_f32 v46, v46, v47
	s_nop 0
	v_addc_co_u32_e32 v59, vcc, 0, v145, vcc
	v_cvt_pk_bf16_f32 v47, v48, v49
	v_cvt_pk_bf16_f32 v48, v42, v43
	v_cvt_pk_bf16_f32 v49, v44, v45
	s_mov_b32 s1, 0x48000
	global_store_dwordx4 v[58:59], v[46:49], off offset:256
	v_cvt_pk_bf16_f32 v30, v30, v31
	v_cvt_pk_bf16_f32 v31, v32, v33
	v_add_co_u32_e32 v46, vcc, s1, v144
	v_cvt_pk_bf16_f32 v32, v26, v27
	s_nop 0
	v_addc_co_u32_e32 v47, vcc, 0, v145, vcc
	v_cvt_pk_bf16_f32 v33, v28, v29
	s_mov_b32 s1, 0x50000
	global_store_dwordx4 v[46:47], v[30:33], off offset:256
	v_cvt_pk_bf16_f32 v14, v14, v15
	v_cvt_pk_bf16_f32 v15, v16, v17
	v_add_co_u32_e32 v30, vcc, s1, v144
	v_cvt_pk_bf16_f32 v16, v10, v11
	s_nop 0
	v_addc_co_u32_e32 v31, vcc, 0, v145, vcc
	v_cvt_pk_bf16_f32 v17, v12, v13
	s_mov_b32 s1, 0x58000
	global_store_dwordx4 v[30:31], v[14:17], off offset:256
	v_cvt_pk_bf16_f32 v126, v126, v127
	v_cvt_pk_bf16_f32 v127, v128, v129
	v_add_co_u32_e32 v14, vcc, s1, v144
	v_cvt_pk_bf16_f32 v128, v122, v123
	v_cvt_pk_bf16_f32 v129, v124, v125
	v_addc_co_u32_e32 v15, vcc, 0, v145, vcc
	global_store_dwordx4 v0, v[126:129], s[12:13]
	v_cvt_pk_bf16_f32 v106, v118, v119
	v_cvt_pk_bf16_f32 v107, v120, v121
	v_cvt_pk_bf16_f32 v108, v114, v115
	v_cvt_pk_bf16_f32 v109, v116, v117
	v_cvt_pk_bf16_f32 v90, v102, v103
	v_cvt_pk_bf16_f32 v91, v104, v105
	v_cvt_pk_bf16_f32 v92, v98, v99
	v_cvt_pk_bf16_f32 v93, v100, v101
	v_cvt_pk_bf16_f32 v74, v86, v87
	v_cvt_pk_bf16_f32 v75, v88, v89
	v_cvt_pk_bf16_f32 v76, v82, v83
	v_cvt_pk_bf16_f32 v77, v84, v85
	v_cvt_pk_bf16_f32 v70, v70, v71
	v_cvt_pk_bf16_f32 v71, v72, v73
	v_cvt_pk_bf16_f32 v72, v66, v67
	v_cvt_pk_bf16_f32 v73, v68, v69
	v_cvt_pk_bf16_f32 v65, v60, v61
	v_cvt_pk_bf16_f32 v42, v54, v55
	v_cvt_pk_bf16_f32 v43, v56, v57
	v_cvt_pk_bf16_f32 v44, v50, v51
	v_cvt_pk_bf16_f32 v45, v52, v53
	v_cvt_pk_bf16_f32 v26, v38, v39
	v_cvt_pk_bf16_f32 v27, v40, v41
	v_cvt_pk_bf16_f32 v28, v34, v35
	v_cvt_pk_bf16_f32 v29, v36, v37
	v_cvt_pk_bf16_f32 v10, v22, v23
	v_cvt_pk_bf16_f32 v11, v24, v25
	v_cvt_pk_bf16_f32 v12, v18, v19
	v_cvt_pk_bf16_f32 v13, v20, v21
	v_cvt_pk_bf16_f32 v6, v6, v7
	v_cvt_pk_bf16_f32 v7, v8, v9
	v_cvt_pk_bf16_f32 v8, v2, v3
	v_cvt_pk_bf16_f32 v9, v4, v5
	s_and_b64 vcc, exec, s[4:5]
	s_mov_b32 s34, s0
	s_mov_b32 s35, s6
	s_mov_b64 s[12:13], s[10:11]
	s_mov_b64 s[16:17], s[8:9]
	global_store_dwordx4 v[110:111], v[106:109], off
	global_store_dwordx4 v[94:95], v[90:93], off
	global_store_dwordx4 v[78:79], v[74:77], off
	global_store_dwordx4 v[78:79], v[70:73], off offset:256
	global_store_dwordx4 v[58:59], v[62:65], off
	global_store_dwordx4 v[46:47], v[42:45], off
	global_store_dwordx4 v[30:31], v[26:29], off
	global_store_dwordx4 v[14:15], v[10:13], off
	global_store_dwordx4 v[14:15], v[6:9], off offset:256
	s_cbranch_vccz .LBB0_656
	s_waitcnt vmcnt(0)
	s_cmpk_gt_u32 s2, 0xff
	s_cbranch_scc1 .LBB0_663
	s_barrier

; DI float fexp2(float x) { return __builtin_amdgcn_exp2f(x); }
; #define AT_LDK(dst, k4_) _Pragma("unroll") for (int kc = 0; kc < NKC; ++kc) dst[kc] = *(const LAS bf16x8*)(kb + (((k4_) * 32 + r) * KS + kc * 16 + hh * 8) * 2)
; #define AT_MMK(src, k4_) do { _Pragma("unroll") for (int i = 0; i < 16; ++i) s[k4_][i] = 0.f; _Pragma("unroll") for (int kc = 0; kc < NKC; ++kc) s[k4_] = MFMA32(src[kc], qf[kc], s[k4_]); } while (0)
; template <int DK> ...
;     ...
;       { bf16x8 ka[NKC], kb2[NKC];
;         AT_LDK(ka, 0); __builtin_amdgcn_sched_barrier(0);
;         AT_LDK(kb2, 1); __builtin_amdgcn_sched_barrier(0); AT_MMK(ka, 0); __builtin_amdgcn_sched_barrier(0);
;         AT_LDK(ka, 2); __builtin_amdgcn_sched_barrier(0); AT_MMK(kb2, 1); __builtin_amdgcn_sched_barrier(0);
;         AT_LDK(kb2, 3); __builtin_amdgcn_sched_barrier(0); AT_MMK(ka, 2); __builtin_amdgcn_sched_barrier(0);
;         AT_MMK(kb2, 3); __builtin_amdgcn_sched_barrier(0); }
;     ...
;       if (masked) {
; #pragma unroll
;         for (int k4 = 0; k4 < 4; ++k4)
; #pragma unroll
;           for (int i = 0; i < 16; ++i) { const int dd = (tq0 + r) - (kpos_t + k4 * 32 + (i & 3) + 8 * (i >> 2) + 4 * hh); if (dd > 128 || dd < -128) s[k4][i] = -1e30f; }
;       }
;       float mx = -3e38f;
; #pragma unroll
;       for (int k4 = 0; k4 < 4; ++k4)
; #pragma unroll
;         for (int i = 0; i < 16; i += 2) mx = fmaxf(fmaxf(mx, s[k4][i]), s[k4][i + 1]);
;       mx = fmaxf(mx, __shfl_xor(mx, 32));
;       const float mnew = fmaxf(mrun, mx * cq), alpha = fexp2(mrun - mnew); mrun = mnew;
;       f32x2 ls2 = {0.f, 0.f}; const f32x2 cq2 = {cq, cq}, mn2 = {-mnew, -mnew};
; #pragma unroll
;       for (int k4 = 0; k4 < 4; ++k4)
; #pragma unroll
;         for (int i = 0; i < 16; i += 2) {
;           f32x2 xv = {s[k4][i], s[k4][i + 1]}; xv = xv * cq2 + mn2;
;           f32x2 pv = {fexp2(xv[0]), fexp2(xv[1])}; s[k4][i] = pv[0]; s[k4][i + 1] = pv[1]; ls2 += pv;
;         }
;       lrun = lrun * alpha + (ls2[0] + ls2[1]);
;       if (__builtin_amdgcn_ballot_w64(alpha != 1.f) != 0ull) { o0 *= alpha; o1 *= alpha; }
.LBB0_754:
	s_and_b32 s1, s6, 1
	s_mul_i32 s6, s1, 0xaa00
	s_add_i32 s6, s6, 0
	v_add3_u32 v162, s6, v146, v165
	ds_read_b128 v[34:37], v162
	ds_read_b128 v[38:41], v162 offset:32
	ds_read_b128 v[42:45], v162 offset:64
	ds_read_b128 v[46:49], v162 offset:96
	ds_read_b128 v[50:53], v162 offset:128
	ds_read_b128 v[54:57], v162 offset:160
	ds_read_b128 v[58:61], v162 offset:6656
	ds_read_b128 v[62:65], v162 offset:6688
	ds_read_b128 v[170:173], v162 offset:6720
	ds_read_b128 v[174:177], v162 offset:6752
	ds_read_b128 v[178:181], v162 offset:6784
	ds_read_b128 v[182:185], v162 offset:6816
	s_waitcnt lgkmcnt(11)
	v_mfma_f32_32x32x16_bf16 v[82:97], v[34:37], v[118:121], 0
	s_waitcnt lgkmcnt(10)
	v_mfma_f32_32x32x16_bf16 v[82:97], v[38:41], v[98:101], v[82:97]
	s_waitcnt lgkmcnt(9)
	v_mfma_f32_32x32x16_bf16 v[82:97], v[42:45], v[102:105], v[82:97]
	s_waitcnt lgkmcnt(8)
	v_mfma_f32_32x32x16_bf16 v[82:97], v[46:49], v[106:109], v[82:97]
	s_waitcnt lgkmcnt(7)
	v_mfma_f32_32x32x16_bf16 v[82:97], v[50:53], v[110:113], v[82:97]
	s_waitcnt lgkmcnt(6)
	v_mfma_f32_32x32x16_bf16 v[82:97], v[54:57], v[114:117], v[82:97]
	ds_read_b128 v[34:37], v162 offset:13312
	ds_read_b128 v[38:41], v162 offset:13344
	ds_read_b128 v[42:45], v162 offset:13376
	ds_read_b128 v[46:49], v162 offset:13408
	ds_read_b128 v[202:205], v162 offset:13440
	ds_read_b128 v[206:209], v162 offset:13472
	s_waitcnt lgkmcnt(11)
	v_mfma_f32_32x32x16_bf16 v[66:81], v[58:61], v[118:121], 0
	s_waitcnt lgkmcnt(10)
	v_mfma_f32_32x32x16_bf16 v[66:81], v[62:65], v[98:101], v[66:81]
	s_waitcnt lgkmcnt(9)
	v_mfma_f32_32x32x16_bf16 v[66:81], v[170:173], v[102:105], v[66:81]
	s_waitcnt lgkmcnt(8)
	v_mfma_f32_32x32x16_bf16 v[66:81], v[174:177], v[106:109], v[66:81]
	s_waitcnt lgkmcnt(7)
	v_mfma_f32_32x32x16_bf16 v[66:81], v[178:181], v[110:113], v[66:81]
	s_waitcnt lgkmcnt(6)
	v_mfma_f32_32x32x16_bf16 v[66:81], v[182:185], v[114:117], v[66:81]
	ds_read_b128 v[170:173], v162 offset:19968
	ds_read_b128 v[174:177], v162 offset:20000
	ds_read_b128 v[178:181], v162 offset:20032
	ds_read_b128 v[182:185], v162 offset:20064
	ds_read_b128 v[210:213], v162 offset:20096
	ds_read_b128 v[226:229], v162 offset:20128
	s_waitcnt lgkmcnt(11)
	v_mfma_f32_32x32x16_bf16 v[50:65], v[34:37], v[118:121], 0
	v_max3_f32 v162, v82, s56, v83
	v_max3_f32 v162, v162, v84, v85
	s_waitcnt lgkmcnt(10)
	v_mfma_f32_32x32x16_bf16 v[50:65], v[38:41], v[98:101], v[50:65]
	v_max3_f32 v162, v162, v86, v87
	v_max3_f32 v162, v162, v88, v89
	s_waitcnt lgkmcnt(9)
	v_mfma_f32_32x32x16_bf16 v[50:65], v[42:45], v[102:105], v[50:65]
	v_max3_f32 v162, v162, v90, v91
	v_max3_f32 v162, v162, v92, v93
	s_waitcnt lgkmcnt(8)
	v_mfma_f32_32x32x16_bf16 v[50:65], v[46:49], v[106:109], v[50:65]
	v_max3_f32 v162, v162, v94, v95
	v_max3_f32 v162, v162, v96, v97
	s_waitcnt lgkmcnt(7)
	v_mfma_f32_32x32x16_bf16 v[50:65], v[202:205], v[110:113], v[50:65]
	v_max3_f32 v162, v162, v66, v67
	v_max3_f32 v162, v162, v68, v69
	s_waitcnt lgkmcnt(6)
	v_mfma_f32_32x32x16_bf16 v[50:65], v[206:209], v[114:117], v[50:65]
	v_max3_f32 v162, v162, v70, v71
	v_max3_f32 v162, v162, v72, v73
	s_waitcnt lgkmcnt(5)
	v_mfma_f32_32x32x16_bf16 v[34:49], v[170:173], v[118:121], 0
	v_max3_f32 v162, v162, v74, v75
	v_max3_f32 v162, v162, v76, v77
	s_waitcnt lgkmcnt(4)
	v_mfma_f32_32x32x16_bf16 v[34:49], v[174:177], v[98:101], v[34:49]
	v_max3_f32 v162, v162, v78, v79
	v_max3_f32 v162, v162, v80, v81
	s_waitcnt lgkmcnt(3)
	v_mfma_f32_32x32x16_bf16 v[34:49], v[178:181], v[102:105], v[34:49]
	v_add3_u32 v169, s6, v164, v168
	v_add_u32_e32 v190, 0x6800, v169
	v_add_u32_e32 v169, 0x8800, v169
	s_waitcnt lgkmcnt(2)
	v_mfma_f32_32x32x16_bf16 v[34:49], v[182:185], v[106:109], v[34:49]
	v_max3_f32 v162, v162, v50, v51
	v_max3_f32 v162, v162, v52, v53
	s_waitcnt lgkmcnt(1)
	v_mfma_f32_32x32x16_bf16 v[34:49], v[210:213], v[110:113], v[34:49]
	v_max3_f32 v162, v162, v54, v55
	v_max3_f32 v162, v162, v56, v57
	s_waitcnt lgkmcnt(0)
	v_mfma_f32_32x32x16_bf16 v[34:49], v[226:229], v[114:117], v[34:49]
	v_max3_f32 v162, v162, v58, v59
	v_max3_f32 v162, v162, v60, v61
	v_max3_f32 v162, v162, v62, v63
	v_max3_f32 v162, v162, v64, v65
	ds_read2_b64 v[170:173], v190 offset1:2
	ds_read2_b64 v[174:177], v190 offset0:4 offset1:6
	ds_read2_b64 v[178:181], v169 offset0:32 offset1:34
	ds_read2_b64 v[182:185], v169 offset0:36 offset1:38
	s_nop 3
	v_max3_f32 v162, v162, v34, v35
	v_max3_f32 v162, v162, v36, v37
	v_max3_f32 v162, v162, v38, v39
	v_max3_f32 v162, v162, v40, v41
	v_max3_f32 v162, v162, v42, v43
	v_max3_f32 v162, v162, v44, v45
	v_max3_f32 v162, v162, v46, v47
	v_max3_f32 v162, v162, v48, v49
	v_mov_b32_e32 v210, v162
	s_nop 1
	v_permlane32_swap_b32_e32 v210, v162
	s_nop 0
	v_max_f32_e32 v162, v162, v210
	v_mul_f32_e32 v162, v150, v162
	v_max_f32_e32 v210, v160, v160
	v_max_f32_e32 v162, v210, v162
	v_sub_f32_e32 v160, v160, v162
	v_exp_f32_e32 v160, v160
	s_nop 0
	v_cmp_neq_f32_e32 vcc, 1.0, v160
	s_cbranch_vccz .Lmla_norescale
	v_pk_mul_f32 v[32:33], v[32:33], v[160:161] op_sel_hi:[1,0]
	v_pk_mul_f32 v[30:31], v[30:31], v[160:161] op_sel_hi:[1,0]
	v_pk_mul_f32 v[28:29], v[28:29], v[160:161] op_sel_hi:[1,0]
	v_pk_mul_f32 v[26:27], v[26:27], v[160:161] op_sel_hi:[1,0]
	v_pk_mul_f32 v[24:25], v[24:25], v[160:161] op_sel_hi:[1,0]
	v_pk_mul_f32 v[22:23], v[22:23], v[160:161] op_sel_hi:[1,0]
	v_pk_mul_f32 v[20:21], v[20:21], v[160:161] op_sel_hi:[1,0]
	v_pk_mul_f32 v[18:19], v[18:19], v[160:161] op_sel_hi:[1,0]
	v_pk_mul_f32 v[16:17], v[16:17], v[160:161] op_sel_hi:[1,0]
	v_pk_mul_f32 v[14:15], v[14:15], v[160:161] op_sel_hi:[1,0]
	v_pk_mul_f32 v[12:13], v[12:13], v[160:161] op_sel_hi:[1,0]
	v_pk_mul_f32 v[10:11], v[10:11], v[160:161] op_sel_hi:[1,0]
	v_pk_mul_f32 v[8:9], v[8:9], v[160:161] op_sel_hi:[1,0]
	v_pk_mul_f32 v[6:7], v[6:7], v[160:161] op_sel_hi:[1,0]
	v_pk_mul_f32 v[4:5], v[4:5], v[160:161] op_sel_hi:[1,0]
	v_pk_mul_f32 v[2:3], v[2:3], v[160:161] op_sel_hi:[1,0]
; DI float fexp2(float x) { return __builtin_amdgcn_exp2f(x); }
; template <int DK> ...
;     ...
;       const float mnew = fmaxf(mrun, mx * cq), alpha = fexp2(mrun - mnew); mrun = mnew;
;       f32x2 ls2 = {0.f, 0.f}; const f32x2 cq2 = {cq, cq}, mn2 = {-mnew, -mnew};
; #pragma unroll
;       for (int k4 = 0; k4 < 4; ++k4)
; #pragma unroll
;         for (int i = 0; i < 16; i += 2) {
;           f32x2 xv = {s[k4][i], s[k4][i + 1]}; xv = xv * cq2 + mn2;
;           f32x2 pv = {fexp2(xv[0]), fexp2(xv[1])}; s[k4][i] = pv[0]; s[k4][i + 1] = pv[1]; ls2 += pv;
;         }
;       lrun = lrun * alpha + (ls2[0] + ls2[1]);
;       if (__builtin_amdgcn_ballot_w64(alpha != 1.f) != 0ull) { o0 *= alpha; o1 *= alpha; }
;     ...
;       { bf16x8 va[2][2], vb2[2][2];
;         AT_LDV(va, 0); __builtin_amdgcn_sched_barrier(0);
;         AT_LDV(vb2, 1); __builtin_amdgcn_sched_barrier(0); AT_MMV(va, 0); __builtin_amdgcn_sched_barrier(0);
;         AT_LDV(va, 2); __builtin_amdgcn_sched_barrier(0); AT_MMV(vb2, 1); __builtin_amdgcn_sched_barrier(0);
;         AT_LDV(vb2, 3); __builtin_amdgcn_sched_barrier(0); AT_MMV(va, 2); __builtin_amdgcn_sched_barrier(0);
;         AT_MMV(vb2, 3); }
.Lmla_norescale:
	v_pk_fma_f32 v[82:83], v[150:151], v[82:83], v[162:163] op_sel_hi:[1,1,0] neg_lo:[0,0,1] neg_hi:[0,0,1]
	v_pk_fma_f32 v[84:85], v[150:151], v[84:85], v[162:163] op_sel_hi:[1,1,0] neg_lo:[0,0,1] neg_hi:[0,0,1]
	v_pk_fma_f32 v[86:87], v[150:151], v[86:87], v[162:163] op_sel_hi:[1,1,0] neg_lo:[0,0,1] neg_hi:[0,0,1]
	v_pk_fma_f32 v[88:89], v[150:151], v[88:89], v[162:163] op_sel_hi:[1,1,0] neg_lo:[0,0,1] neg_hi:[0,0,1]
	v_pk_fma_f32 v[90:91], v[150:151], v[90:91], v[162:163] op_sel_hi:[1,1,0] neg_lo:[0,0,1] neg_hi:[0,0,1]
	v_pk_fma_f32 v[92:93], v[150:151], v[92:93], v[162:163] op_sel_hi:[1,1,0] neg_lo:[0,0,1] neg_hi:[0,0,1]
	v_pk_fma_f32 v[94:95], v[150:151], v[94:95], v[162:163] op_sel_hi:[1,1,0] neg_lo:[0,0,1] neg_hi:[0,0,1]
	v_pk_fma_f32 v[96:97], v[150:151], v[96:97], v[162:163] op_sel_hi:[1,1,0] neg_lo:[0,0,1] neg_hi:[0,0,1]
	v_exp_f32_e32 v82, v82
	v_exp_f32_e32 v83, v83
	v_exp_f32_e32 v84, v84
	v_exp_f32_e32 v85, v85
	v_exp_f32_e32 v86, v86
	v_exp_f32_e32 v87, v87
	v_exp_f32_e32 v88, v88
	v_exp_f32_e32 v89, v89
	v_exp_f32_e32 v90, v90
	v_exp_f32_e32 v91, v91
	v_exp_f32_e32 v92, v92
	v_exp_f32_e32 v93, v93
	v_exp_f32_e32 v94, v94
	v_exp_f32_e32 v95, v95
	v_exp_f32_e32 v96, v96
	v_exp_f32_e32 v97, v97
	v_cvt_pk_bf16_f32 v238, v82, v83
	v_cvt_pk_bf16_f32 v239, v84, v85
	v_cvt_pk_bf16_f32 v240, v86, v87
	v_cvt_pk_bf16_f32 v241, v88, v89
	v_cvt_pk_bf16_f32 v242, v90, v91
	v_cvt_pk_bf16_f32 v243, v92, v93
	v_cvt_pk_bf16_f32 v244, v94, v95
	v_cvt_pk_bf16_f32 v245, v96, v97
	s_waitcnt lgkmcnt(0)
	v_mfma_f32_32x32x16_bf16 v[18:33], v[170:173], v[238:241], v[18:33]
	v_pk_fma_f32 v[66:67], v[150:151], v[66:67], v[162:163] op_sel_hi:[1,1,0] neg_lo:[0,0,1] neg_hi:[0,0,1]
	v_pk_fma_f32 v[68:69], v[150:151], v[68:69], v[162:163] op_sel_hi:[1,1,0] neg_lo:[0,0,1] neg_hi:[0,0,1]
	v_pk_fma_f32 v[70:71], v[150:151], v[70:71], v[162:163] op_sel_hi:[1,1,0] neg_lo:[0,0,1] neg_hi:[0,0,1]
	v_pk_fma_f32 v[72:73], v[150:151], v[72:73], v[162:163] op_sel_hi:[1,1,0] neg_lo:[0,0,1] neg_hi:[0,0,1]
	v_pk_fma_f32 v[74:75], v[150:151], v[74:75], v[162:163] op_sel_hi:[1,1,0] neg_lo:[0,0,1] neg_hi:[0,0,1]
	v_pk_fma_f32 v[76:77], v[150:151], v[76:77], v[162:163] op_sel_hi:[1,1,0] neg_lo:[0,0,1] neg_hi:[0,0,1]
	v_pk_fma_f32 v[78:79], v[150:151], v[78:79], v[162:163] op_sel_hi:[1,1,0] neg_lo:[0,0,1] neg_hi:[0,0,1]
	v_pk_fma_f32 v[80:81], v[150:151], v[80:81], v[162:163] op_sel_hi:[1,1,0] neg_lo:[0,0,1] neg_hi:[0,0,1]
	v_pk_add_f32 v[82:83], v[86:87], v[82:83]
	v_pk_add_f32 v[84:85], v[88:89], v[84:85]
	v_mfma_f32_32x32x16_bf16 v[2:17], v[178:181], v[238:241], v[2:17]
	v_exp_f32_e32 v66, v66
	v_exp_f32_e32 v67, v67
	v_exp_f32_e32 v68, v68
	v_exp_f32_e32 v69, v69
	v_exp_f32_e32 v70, v70
	v_exp_f32_e32 v71, v71
	v_exp_f32_e32 v72, v72
	v_exp_f32_e32 v73, v73
	v_pk_add_f32 v[82:83], v[90:91], v[82:83]
	v_pk_add_f32 v[84:85], v[92:93], v[84:85]
	v_mfma_f32_32x32x16_bf16 v[18:33], v[174:177], v[242:245], v[18:33]
	ds_read2_b64 v[170:173], v190 offset0:8 offset1:10
	ds_read2_b64 v[174:177], v190 offset0:12 offset1:14
	v_exp_f32_e32 v74, v74
	v_exp_f32_e32 v75, v75
	v_exp_f32_e32 v76, v76
	v_exp_f32_e32 v77, v77
	v_exp_f32_e32 v78, v78
	v_exp_f32_e32 v79, v79
	v_exp_f32_e32 v80, v80
	v_exp_f32_e32 v81, v81
	v_pk_add_f32 v[82:83], v[94:95], v[82:83]
	v_pk_add_f32 v[84:85], v[96:97], v[84:85]
	v_mfma_f32_32x32x16_bf16 v[2:17], v[182:185], v[242:245], v[2:17]
	ds_read2_b64 v[178:181], v169 offset0:40 offset1:42
	ds_read2_b64 v[182:185], v169 offset0:44 offset1:46
	v_cvt_pk_bf16_f32 v202, v66, v67
	v_cvt_pk_bf16_f32 v203, v68, v69
	v_cvt_pk_bf16_f32 v204, v70, v71
	v_cvt_pk_bf16_f32 v205, v72, v73
	v_cvt_pk_bf16_f32 v206, v74, v75
	v_cvt_pk_bf16_f32 v207, v76, v77
	v_cvt_pk_bf16_f32 v208, v78, v79
	v_cvt_pk_bf16_f32 v209, v80, v81
	v_pk_add_f32 v[82:83], v[84:85], v[82:83]
	s_waitcnt lgkmcnt(2)
	v_mfma_f32_32x32x16_bf16 v[18:33], v[170:173], v[202:205], v[18:33]
	v_pk_fma_f32 v[50:51], v[150:151], v[50:51], v[162:163] op_sel_hi:[1,1,0] neg_lo:[0,0,1] neg_hi:[0,0,1]
	v_pk_fma_f32 v[52:53], v[150:151], v[52:53], v[162:163] op_sel_hi:[1,1,0] neg_lo:[0,0,1] neg_hi:[0,0,1]
	v_pk_fma_f32 v[54:55], v[150:151], v[54:55], v[162:163] op_sel_hi:[1,1,0] neg_lo:[0,0,1] neg_hi:[0,0,1]
	v_pk_fma_f32 v[56:57], v[150:151], v[56:57], v[162:163] op_sel_hi:[1,1,0] neg_lo:[0,0,1] neg_hi:[0,0,1]
	v_pk_fma_f32 v[58:59], v[150:151], v[58:59], v[162:163] op_sel_hi:[1,1,0] neg_lo:[0,0,1] neg_hi:[0,0,1]
	v_pk_fma_f32 v[60:61], v[150:151], v[60:61], v[162:163] op_sel_hi:[1,1,0] neg_lo:[0,0,1] neg_hi:[0,0,1]
	v_pk_fma_f32 v[62:63], v[150:151], v[62:63], v[162:163] op_sel_hi:[1,1,0] neg_lo:[0,0,1] neg_hi:[0,0,1]
	v_pk_fma_f32 v[64:65], v[150:151], v[64:65], v[162:163] op_sel_hi:[1,1,0] neg_lo:[0,0,1] neg_hi:[0,0,1]
	v_pk_add_f32 v[66:67], v[70:71], v[66:67]
	v_pk_add_f32 v[68:69], v[72:73], v[68:69]
	s_waitcnt lgkmcnt(0)
; template <int DK> ...
;     ...
;       { bf16x8 va[2][2], vb2[2][2];
;         AT_LDV(va, 0); __builtin_amdgcn_sched_barrier(0);
;         AT_LDV(vb2, 1); __builtin_amdgcn_sched_barrier(0); AT_MMV(va, 0); __builtin_amdgcn_sched_barrier(0);
;         AT_LDV(va, 2); __builtin_amdgcn_sched_barrier(0); AT_MMV(vb2, 1); __builtin_amdgcn_sched_barrier(0);
;         AT_LDV(vb2, 3); __builtin_amdgcn_sched_barrier(0); AT_MMV(va, 2); __builtin_amdgcn_sched_barrier(0);
;         AT_MMV(vb2, 3); }
;     ...
;     }
;     if (t + 1 < nt) AT_LSTORE(buf ^ 1);
	v_mfma_f32_32x32x16_bf16 v[2:17], v[178:181], v[202:205], v[2:17]
	v_exp_f32_e32 v50, v50
	v_exp_f32_e32 v51, v51
	v_exp_f32_e32 v52, v52
	v_exp_f32_e32 v53, v53
	v_exp_f32_e32 v54, v54
	v_exp_f32_e32 v55, v55
	v_exp_f32_e32 v56, v56
	v_exp_f32_e32 v57, v57
	v_pk_add_f32 v[66:67], v[74:75], v[66:67]
	v_pk_add_f32 v[68:69], v[76:77], v[68:69]
	v_mfma_f32_32x32x16_bf16 v[18:33], v[174:177], v[206:209], v[18:33]
	ds_read2_b64 v[170:173], v190 offset0:16 offset1:18
	ds_read2_b64 v[174:177], v190 offset0:20 offset1:22
	v_exp_f32_e32 v58, v58
	v_exp_f32_e32 v59, v59
	v_exp_f32_e32 v60, v60
	v_exp_f32_e32 v61, v61
	v_exp_f32_e32 v62, v62
	v_exp_f32_e32 v63, v63
	v_exp_f32_e32 v64, v64
	v_exp_f32_e32 v65, v65
	v_pk_add_f32 v[66:67], v[78:79], v[66:67]
	v_pk_add_f32 v[68:69], v[80:81], v[68:69]
	v_mfma_f32_32x32x16_bf16 v[2:17], v[182:185], v[206:209], v[2:17]
	ds_read2_b64 v[178:181], v169 offset0:48 offset1:50
	ds_read2_b64 v[182:185], v169 offset0:52 offset1:54
	v_cvt_pk_bf16_f32 v238, v50, v51
	v_cvt_pk_bf16_f32 v239, v52, v53
	v_cvt_pk_bf16_f32 v240, v54, v55
	v_cvt_pk_bf16_f32 v241, v56, v57
	v_cvt_pk_bf16_f32 v242, v58, v59
	v_cvt_pk_bf16_f32 v243, v60, v61
	v_cvt_pk_bf16_f32 v244, v62, v63
	v_cvt_pk_bf16_f32 v245, v64, v65
	v_pk_add_f32 v[66:67], v[68:69], v[66:67]
	s_waitcnt lgkmcnt(2)
	v_mfma_f32_32x32x16_bf16 v[18:33], v[170:173], v[238:241], v[18:33]
	v_pk_fma_f32 v[34:35], v[150:151], v[34:35], v[162:163] op_sel_hi:[1,1,0] neg_lo:[0,0,1] neg_hi:[0,0,1]
	v_pk_fma_f32 v[36:37], v[150:151], v[36:37], v[162:163] op_sel_hi:[1,1,0] neg_lo:[0,0,1] neg_hi:[0,0,1]
	v_pk_fma_f32 v[38:39], v[150:151], v[38:39], v[162:163] op_sel_hi:[1,1,0] neg_lo:[0,0,1] neg_hi:[0,0,1]
	v_pk_fma_f32 v[40:41], v[150:151], v[40:41], v[162:163] op_sel_hi:[1,1,0] neg_lo:[0,0,1] neg_hi:[0,0,1]
	v_pk_fma_f32 v[42:43], v[150:151], v[42:43], v[162:163] op_sel_hi:[1,1,0] neg_lo:[0,0,1] neg_hi:[0,0,1]
	v_pk_fma_f32 v[44:45], v[150:151], v[44:45], v[162:163] op_sel_hi:[1,1,0] neg_lo:[0,0,1] neg_hi:[0,0,1]
	v_pk_fma_f32 v[46:47], v[150:151], v[46:47], v[162:163] op_sel_hi:[1,1,0] neg_lo:[0,0,1] neg_hi:[0,0,1]
	v_pk_fma_f32 v[48:49], v[150:151], v[48:49], v[162:163] op_sel_hi:[1,1,0] neg_lo:[0,0,1] neg_hi:[0,0,1]
	v_pk_add_f32 v[50:51], v[54:55], v[50:51]
	v_pk_add_f32 v[52:53], v[56:57], v[52:53]
	s_waitcnt lgkmcnt(0)
	v_mfma_f32_32x32x16_bf16 v[2:17], v[178:181], v[238:241], v[2:17]
	v_exp_f32_e32 v34, v34
	v_exp_f32_e32 v35, v35
	v_exp_f32_e32 v36, v36
	v_exp_f32_e32 v37, v37
	v_exp_f32_e32 v38, v38
	v_exp_f32_e32 v39, v39
	v_exp_f32_e32 v40, v40
	v_exp_f32_e32 v41, v41
	v_pk_add_f32 v[50:51], v[58:59], v[50:51]
	v_pk_add_f32 v[52:53], v[60:61], v[52:53]
	v_mfma_f32_32x32x16_bf16 v[18:33], v[174:177], v[242:245], v[18:33]
	ds_read2_b64 v[170:173], v190 offset0:24 offset1:26
	ds_read2_b64 v[174:177], v190 offset0:28 offset1:30
	v_exp_f32_e32 v42, v42
	v_exp_f32_e32 v43, v43
	v_exp_f32_e32 v44, v44
	v_exp_f32_e32 v45, v45
	v_exp_f32_e32 v46, v46
	v_exp_f32_e32 v47, v47
	v_exp_f32_e32 v48, v48
	v_exp_f32_e32 v49, v49
	v_pk_add_f32 v[50:51], v[62:63], v[50:51]
	v_pk_add_f32 v[52:53], v[64:65], v[52:53]
	v_mfma_f32_32x32x16_bf16 v[2:17], v[182:185], v[242:245], v[2:17]
	ds_read2_b64 v[178:181], v169 offset0:56 offset1:58
	ds_read2_b64 v[182:185], v169 offset0:60 offset1:62
	v_cvt_pk_bf16_f32 v202, v34, v35
	v_cvt_pk_bf16_f32 v203, v36, v37
	v_cvt_pk_bf16_f32 v204, v38, v39
	v_cvt_pk_bf16_f32 v205, v40, v41
	v_cvt_pk_bf16_f32 v206, v42, v43
	v_cvt_pk_bf16_f32 v207, v44, v45
	v_cvt_pk_bf16_f32 v208, v46, v47
	v_cvt_pk_bf16_f32 v209, v48, v49
	v_pk_add_f32 v[50:51], v[52:53], v[50:51]
	s_waitcnt lgkmcnt(2)
	v_mfma_f32_32x32x16_bf16 v[18:33], v[170:173], v[202:205], v[18:33]
	v_pk_add_f32 v[34:35], v[38:39], v[34:35]
	v_pk_add_f32 v[36:37], v[40:41], v[36:37]
	s_waitcnt lgkmcnt(0)
	v_mfma_f32_32x32x16_bf16 v[2:17], v[178:181], v[202:205], v[2:17]
	v_pk_add_f32 v[34:35], v[42:43], v[34:35]
	v_pk_add_f32 v[36:37], v[44:45], v[36:37]
	v_mfma_f32_32x32x16_bf16 v[18:33], v[174:177], v[206:209], v[18:33]
	v_pk_add_f32 v[34:35], v[46:47], v[34:35]
	v_pk_add_f32 v[36:37], v[48:49], v[36:37]
	s_andn2_b64 vcc, exec, s[4:5]
	v_mfma_f32_32x32x16_bf16 v[2:17], v[182:185], v[206:209], v[2:17]
	v_pk_add_f32 v[34:35], v[36:37], v[34:35]
	v_pk_add_f32 v[66:67], v[66:67], v[82:83]
	s_nop 0
	v_pk_add_f32 v[34:35], v[34:35], v[50:51]
	s_nop 1
	v_pk_add_f32 v[34:35], v[34:35], v[66:67]
	s_cbranch_vccnz .LBB0_758
	s_xor_b32 s1, s1, 1
	s_mul_i32 s1, s1, 0xaa00
	s_add_i32 s1, s1, 0
	v_add3_u32 v169, s1, v134, v137
	s_waitcnt vmcnt(6)
	ds_write_b128 v169, v[126:129]
	v_add3_u32 v169, s1, v136, v161
	s_waitcnt vmcnt(5)
	ds_write_b128 v169, v[122:125]
	v_add3_u32 v169, s1, v140, v163
	s_waitcnt vmcnt(4)
	ds_write_b128 v169, v[130:133]
	s_waitcnt vmcnt(3)
	v_and_b32_e32 v169, 0xffff, v152
	s_waitcnt vmcnt(2)
	v_lshl_or_b32 v170, v154, 16, v169
	s_waitcnt vmcnt(1)
	v_and_b32_e32 v169, 0xffff, v156
	s_waitcnt vmcnt(0)
	v_lshl_or_b32 v171, v158, 16, v169
	v_lshrrev_b32_e32 v169, 16, v152
	v_and_or_b32 v172, v154, s55, v169
	v_lshrrev_b32_e32 v169, 16, v156
	v_and_or_b32 v173, v158, s55, v169
	v_and_b32_e32 v169, 0xffff, v153
	v_lshl_or_b32 v174, v155, 16, v169
	v_and_b32_e32 v169, 0xffff, v157
	v_lshl_or_b32 v175, v159, 16, v169
	v_lshrrev_b32_e32 v169, 16, v153
	v_and_or_b32 v176, v155, s55, v169
	v_lshrrev_b32_e32 v169, 16, v157
	v_and_or_b32 v177, v159, s55, v169
	v_add_u32_e32 v169, s1, v147
	v_add_u32_e32 v169, 0x6800, v169
	ds_write2_b64 v169, v[170:171], v[172:173] offset1:33
	ds_write2_b64 v169, v[174:175], v[176:177] offset0:66 offset1:99

; #define PG8_STAGE(bufoff, gbase, voff) do { _Pragma("unroll") for (int _i = 0; _i < 2; ++_i) \
;     __builtin_amdgcn_global_load_lds((const unsigned*)((const char*)(gbase) + (voff)[_i]), (LAS unsigned*)(lds + (bufoff) + ldsw + _i * 8192), 16, 0, 0); } while (0)
; #define PG8_LDA(dst, b, h) do { _Pragma("unroll") for (int m = 0; m < 4; ++m) _Pragma("unroll") for (int k = 0; k < 2; ++k) dst[m][k] = *(const LAS bf16x8*)(lds + PG8_SA(b, h) + aoff + m * 2048 + k * 1024); } while (0)
; #define PG8_LDB(dst, b, h) do { _Pragma("unroll") for (int n = 0; n < 2; ++n) _Pragma("unroll") for (int k = 0; k < 2; ++k) dst[n][k] = *(const LAS bf16x8*)(lds + PG8_SB(b, h) + boff + n * 2048 + k * 1024); } while (0)
; #define PG8_MMA(ai, bj, At, Bt) do { __builtin_amdgcn_s_setprio(1); _Pragma("unroll") for (int m = 0; m < 4; ++m) _Pragma("unroll") for (int n = 0; n < 2; ++n) _Pragma("unroll") for (int k = 0; k < 2; ++k) \
;     acc[ai][bj][m][n] = __builtin_amdgcn_mfma_f32_16x16x32_bf16(Bt[n][k], At[m][k], acc[ai][bj][m][n], 0, 0, 0); __builtin_amdgcn_s_setprio(0); } while (0)
; #define PG8_WAIT_L(n) asm volatile("s_waitcnt lgkmcnt(" #n ")" ::: "memory")
; #define PG8_BAR __builtin_amdgcn_s_barrier()
; template <class Epi, class Sched>
; DI void gemm_phase(LAS unsigned char* lds, const int tid, const Gemm g, const Sched& S, const Epi& E) {
;     ...
;   for (;;) {
;     const bool has_next = S.next(ui + 1, nxt);
;     const char* nA = has_next ? (const char*)g.A + (size_t)nxt.pm * tstepA : cA; const char* nB = has_next ? (const char*)g.Bt + (size_t)nxt.pn * tstepB : cB;
; #pragma unroll 1
;     for (int t = 0; t < nt; t += 2) {
;       const bool last = (t == nt - 2);
;       const char* a1 = cA + (size_t)(t + 1) * kstep;
;       const char* a2 = last ? nA : cA + (size_t)(t + 2) * kstep; const char* b2 = last ? nB : cB + (size_t)(t + 2) * kstep;
;       const char* a3 = a2 + kstep; const char* b3 = b2 + kstep;
;       PG8_LDB(B0, 0, 0); PG8_SCHED; PG8_LDA(At, 0, 0); PG8_STAGE(PG8_SA(1, 1), a1 + hstepA, voffA);
;       PG8_WAIT_L(8); PG8_BAR; PG8_WAIT_L(0); PG8_MMA(0, 0, At, B0); PG8_BAR; PG8_SCHED;
;       PG8_LDB(B1, 0, 1); PG8_STAGE(PG8_SB(0, 0), b2, voffB);
;       PG8_BAR; PG8_WAIT_L(0); PG8_MMA(0, 1, At, B1); PG8_BAR;
;       PG8_LDA(At, 0, 1); PG8_STAGE(PG8_SA(0, 0), a2, voffA);
;       PG8_BAR; PG8_WAIT_L(0); PG8_MMA(1, 0, At, B0); PG8_BAR; PG8_SCHED;
.LBB0_824:
	s_add_i32 s88, s14, 2
	s_add_u32 s34, s30, 0x80
	s_addc_u32 s15, s31, 0
	s_add_i32 s89, 0, 0x10000
	v_add_u32_e32 v0, s89, v202
	ds_read_b128 v[130:133], v0
	ds_read_b128 v[134:137], v0 offset:1024
	ds_read_b128 v[138:141], v0 offset:2048
	ds_read_b128 v[142:145], v0 offset:3072
	s_cmp_eq_u32 s78, s14
	s_cselect_b32 s14, s0, s34
	s_cselect_b32 s15, s1, s15
	s_cselect_b32 s35, s7, s39
	s_cselect_b32 s34, s6, s38
	s_add_i32 m0, s58, 0xc000
	ds_read_b128 v[146:149], v203
	ds_read_b128 v[150:153], v203 offset:1024
	ds_read_b128 v[154:157], v203 offset:2048
	ds_read_b128 v[166:169], v203 offset:3072
	ds_read_b128 v[170:173], v203 offset:4096
	ds_read_b128 v[174:177], v203 offset:5120
	ds_read_b128 v[178:181], v203 offset:6144
	ds_read_b128 v[182:185], v203 offset:7168
	global_load_lds_dwordx4 v164, s[30:31]
	s_add_i32 m0, s58, 0xe000
	s_nop 0
	global_load_lds_dwordx4 v162, s[30:31]
	s_waitcnt lgkmcnt(8)
	s_barrier
	s_waitcnt lgkmcnt(0)
	s_setprio 1
	v_mfma_f32_16x16x32_bf16 v[126:129], v[130:133], v[146:149], v[126:129]
	v_mfma_f32_16x16x32_bf16 v[122:125], v[138:141], v[146:149], v[122:125]
	v_mfma_f32_16x16x32_bf16 v[118:121], v[130:133], v[154:157], v[118:121]
	v_mfma_f32_16x16x32_bf16 v[106:109], v[138:141], v[154:157], v[106:109]
	v_mfma_f32_16x16x32_bf16 v[102:105], v[130:133], v[170:173], v[102:105]
	v_mfma_f32_16x16x32_bf16 v[90:93], v[138:141], v[170:173], v[90:93]
	v_mfma_f32_16x16x32_bf16 v[82:85], v[130:133], v[178:181], v[82:85]
	v_mfma_f32_16x16x32_bf16 v[74:77], v[138:141], v[178:181], v[74:77]
	v_mfma_f32_16x16x32_bf16 v[126:129], v[134:137], v[150:153], v[126:129]
	v_mfma_f32_16x16x32_bf16 v[122:125], v[142:145], v[150:153], v[122:125]
	v_mfma_f32_16x16x32_bf16 v[118:121], v[134:137], v[166:169], v[118:121]
	v_mfma_f32_16x16x32_bf16 v[106:109], v[142:145], v[166:169], v[106:109]
	v_mfma_f32_16x16x32_bf16 v[102:105], v[134:137], v[174:177], v[102:105]
	v_mfma_f32_16x16x32_bf16 v[90:93], v[142:145], v[174:177], v[90:93]
	v_mfma_f32_16x16x32_bf16 v[82:85], v[134:137], v[182:185], v[82:85]
	v_mfma_f32_16x16x32_bf16 v[74:77], v[142:145], v[182:185], v[74:77]
	s_setprio 0
	s_barrier
	s_add_i32 s90, 0, 0x14000
	s_add_i32 s89, s89, s53
	v_add_u32_e32 v0, s90, v202
	s_add_u32 s98, s34, s50
	s_addc_u32 s99, s35, s51
	s_mov_b32 m0, s89
	ds_read_b128 v[198:201], v0
	ds_read_b128 v[204:207], v0 offset:1024
	ds_read_b128 v[208:211], v0 offset:2048
	ds_read_b128 v[216:219], v0 offset:3072
	global_load_lds_dwordx4 v160, s[34:35]
	s_add_i32 m0, s89, 0x2000
	s_nop 0
	global_load_lds_dwordx4 v158, s[34:35]
	s_barrier
	s_waitcnt lgkmcnt(0)
	s_setprio 1
	v_mfma_f32_16x16x32_bf16 v[114:117], v[198:201], v[146:149], v[114:117]
	v_mfma_f32_16x16x32_bf16 v[110:113], v[208:211], v[146:149], v[110:113]
	v_mfma_f32_16x16x32_bf16 v[98:101], v[198:201], v[154:157], v[98:101]
	v_mfma_f32_16x16x32_bf16 v[94:97], v[208:211], v[154:157], v[94:97]
	v_mfma_f32_16x16x32_bf16 v[86:89], v[198:201], v[170:173], v[86:89]
	v_mfma_f32_16x16x32_bf16 v[78:81], v[208:211], v[170:173], v[78:81]
	v_mfma_f32_16x16x32_bf16 v[70:73], v[198:201], v[178:181], v[70:73]
	v_mfma_f32_16x16x32_bf16 v[66:69], v[208:211], v[178:181], v[66:69]
	v_mfma_f32_16x16x32_bf16 v[114:117], v[204:207], v[150:153], v[114:117]
	v_mfma_f32_16x16x32_bf16 v[110:113], v[216:219], v[150:153], v[110:113]
	v_mfma_f32_16x16x32_bf16 v[98:101], v[204:207], v[166:169], v[98:101]
	v_mfma_f32_16x16x32_bf16 v[94:97], v[216:219], v[166:169], v[94:97]
	v_mfma_f32_16x16x32_bf16 v[86:89], v[204:207], v[174:177], v[86:89]
	v_mfma_f32_16x16x32_bf16 v[78:81], v[216:219], v[174:177], v[78:81]
	v_mfma_f32_16x16x32_bf16 v[70:73], v[204:207], v[182:185], v[70:73]
	v_mfma_f32_16x16x32_bf16 v[66:69], v[216:219], v[182:185], v[66:69]
	s_setprio 0
	s_mov_b32 m0, s58
	s_add_u32 s100, s14, s50
	s_addc_u32 s101, s15, s51
	s_barrier
	ds_read_b128 v[146:149], v203 offset:16384
	ds_read_b128 v[150:153], v203 offset:17408
	ds_read_b128 v[154:157], v203 offset:18432
	ds_read_b128 v[166:169], v203 offset:19456
	ds_read_b128 v[170:173], v203 offset:20480
	ds_read_b128 v[174:177], v203 offset:21504
	ds_read_b128 v[178:181], v203 offset:22528
	ds_read_b128 v[182:185], v203 offset:23552
	global_load_lds_dwordx4 v160, s[14:15]
	s_mov_b32 m0, s59
	s_nop 0
	global_load_lds_dwordx4 v158, s[14:15]
	s_barrier
	s_waitcnt lgkmcnt(0)
	s_setprio 1
	v_mfma_f32_16x16x32_bf16 v[62:65], v[130:133], v[146:149], v[62:65]
	v_mfma_f32_16x16x32_bf16 v[58:61], v[138:141], v[146:149], v[58:61]
	v_mfma_f32_16x16x32_bf16 v[54:57], v[130:133], v[154:157], v[54:57]
	v_mfma_f32_16x16x32_bf16 v[42:45], v[138:141], v[154:157], v[42:45]
	v_mfma_f32_16x16x32_bf16 v[38:41], v[130:133], v[170:173], v[38:41]
	v_mfma_f32_16x16x32_bf16 v[26:29], v[138:141], v[170:173], v[26:29]
	v_mfma_f32_16x16x32_bf16 v[22:25], v[130:133], v[178:181], v[22:25]
	v_mfma_f32_16x16x32_bf16 v[14:17], v[138:141], v[178:181], v[14:17]
	v_mfma_f32_16x16x32_bf16 v[62:65], v[134:137], v[150:153], v[62:65]
	v_mfma_f32_16x16x32_bf16 v[58:61], v[142:145], v[150:153], v[58:61]
	v_mfma_f32_16x16x32_bf16 v[54:57], v[134:137], v[166:169], v[54:57]
	v_mfma_f32_16x16x32_bf16 v[42:45], v[142:145], v[166:169], v[42:45]
	v_mfma_f32_16x16x32_bf16 v[38:41], v[134:137], v[174:177], v[38:41]
	v_mfma_f32_16x16x32_bf16 v[26:29], v[142:145], v[174:177], v[26:29]
	v_mfma_f32_16x16x32_bf16 v[22:25], v[134:137], v[182:185], v[22:25]
	v_mfma_f32_16x16x32_bf16 v[14:17], v[142:145], v[182:185], v[14:17]
	s_setprio 0
	s_barrier
	s_add_u32 s34, s34, s20
	s_addc_u32 s35, s35, 0
	s_add_i32 s89, s90, s53
	v_lshl_add_u64 v[226:227], s[34:35], 0, v[160:161]
	s_mov_b32 m0, s89
	v_lshl_add_u64 v[228:229], s[34:35], 0, v[158:159]
	global_load_lds_dwordx4 v[226:227], off
	s_add_i32 m0, s89, 0x2000
	s_nop 0
	global_load_lds_dwordx4 v[228:229], off
	s_waitcnt vmcnt(6)
	s_barrier
; #define PG8_STAGE(bufoff, gbase, voff) do { _Pragma("unroll") for (int _i = 0; _i < 2; ++_i) \
;     __builtin_amdgcn_global_load_lds((const unsigned*)((const char*)(gbase) + (voff)[_i]), (LAS unsigned*)(lds + (bufoff) + ldsw + _i * 8192), 16, 0, 0); } while (0)
; #define PG8_LDA(dst, b, h) do { _Pragma("unroll") for (int m = 0; m < 4; ++m) _Pragma("unroll") for (int k = 0; k < 2; ++k) dst[m][k] = *(const LAS bf16x8*)(lds + PG8_SA(b, h) + aoff + m * 2048 + k * 1024); } while (0)
; #define PG8_LDB(dst, b, h) do { _Pragma("unroll") for (int n = 0; n < 2; ++n) _Pragma("unroll") for (int k = 0; k < 2; ++k) dst[n][k] = *(const LAS bf16x8*)(lds + PG8_SB(b, h) + boff + n * 2048 + k * 1024); } while (0)
; #define PG8_MMA(ai, bj, At, Bt) do { __builtin_amdgcn_s_setprio(1); _Pragma("unroll") for (int m = 0; m < 4; ++m) _Pragma("unroll") for (int n = 0; n < 2; ++n) _Pragma("unroll") for (int k = 0; k < 2; ++k) \
;     acc[ai][bj][m][n] = __builtin_amdgcn_mfma_f32_16x16x32_bf16(Bt[n][k], At[m][k], acc[ai][bj][m][n], 0, 0, 0); __builtin_amdgcn_s_setprio(0); } while (0)
; #define PG8_WAIT_V(n) asm volatile("s_waitcnt vmcnt(" #n ")" ::: "memory")
; #define PG8_WAIT_L(n) asm volatile("s_waitcnt lgkmcnt(" #n ")" ::: "memory")
; #define PG8_BAR __builtin_amdgcn_s_barrier()
; #define PG8_SCHED __builtin_amdgcn_sched_barrier(0)
; template <class Epi, class Sched>
; DI void gemm_phase(LAS unsigned char* lds, const int tid, const Gemm g, const Sched& S, const Epi& E) {
;     ...
;       PG8_WAIT_V(6); PG8_BAR; PG8_MMA(1, 1, At, B1); PG8_BAR;
;       PG8_LDB(B0, 1, 0); PG8_SCHED; PG8_LDA(At, 1, 0); PG8_STAGE(PG8_SA(0, 1), a2 + hstepA, voffA);
;       PG8_WAIT_L(8); PG8_BAR; PG8_WAIT_L(0); PG8_MMA(0, 0, At, B0); PG8_BAR; PG8_SCHED;
;       PG8_LDB(B1, 1, 1); PG8_STAGE(PG8_SB(1, 0), b3, voffB);
;       PG8_BAR; PG8_WAIT_L(0); PG8_MMA(0, 1, At, B1); PG8_BAR;
	s_setprio 1
	v_mfma_f32_16x16x32_bf16 v[50:53], v[198:201], v[146:149], v[50:53]
	v_mfma_f32_16x16x32_bf16 v[46:49], v[208:211], v[146:149], v[46:49]
	v_mfma_f32_16x16x32_bf16 v[34:37], v[198:201], v[154:157], v[34:37]
	v_mfma_f32_16x16x32_bf16 v[30:33], v[208:211], v[154:157], v[30:33]
	v_mfma_f32_16x16x32_bf16 v[18:21], v[198:201], v[170:173], v[18:21]
	v_mfma_f32_16x16x32_bf16 v[10:13], v[208:211], v[170:173], v[10:13]
	v_mfma_f32_16x16x32_bf16 v[6:9], v[198:201], v[178:181], v[6:9]
	v_mfma_f32_16x16x32_bf16 v[2:5], v[208:211], v[178:181], v[2:5]
	v_mfma_f32_16x16x32_bf16 v[50:53], v[204:207], v[150:153], v[50:53]
	v_mfma_f32_16x16x32_bf16 v[46:49], v[216:219], v[150:153], v[46:49]
	v_mfma_f32_16x16x32_bf16 v[34:37], v[204:207], v[166:169], v[34:37]
	v_mfma_f32_16x16x32_bf16 v[30:33], v[216:219], v[166:169], v[30:33]
	v_mfma_f32_16x16x32_bf16 v[18:21], v[204:207], v[174:177], v[18:21]
	v_mfma_f32_16x16x32_bf16 v[10:13], v[216:219], v[174:177], v[10:13]
	v_mfma_f32_16x16x32_bf16 v[6:9], v[204:207], v[182:185], v[6:9]
	v_mfma_f32_16x16x32_bf16 v[2:5], v[216:219], v[182:185], v[2:5]
	s_setprio 0
	s_add_i32 s34, 0, 0x18000
	v_add_u32_e32 v0, s34, v202
	s_barrier
	ds_read_b128 v[130:133], v0
	ds_read_b128 v[134:137], v0 offset:1024
	ds_read_b128 v[138:141], v0 offset:2048
	ds_read_b128 v[142:145], v0 offset:3072
	s_add_u32 s14, s14, s20
	s_addc_u32 s15, s15, 0
	s_mov_b32 m0, s60
	ds_read_b128 v[146:149], v203 offset:32768
	ds_read_b128 v[150:153], v203 offset:33792
	ds_read_b128 v[154:157], v203 offset:34816
	ds_read_b128 v[166:169], v203 offset:35840
	ds_read_b128 v[170:173], v203 offset:36864
	ds_read_b128 v[174:177], v203 offset:37888
	ds_read_b128 v[178:181], v203 offset:38912
	ds_read_b128 v[182:185], v203 offset:39936
	global_load_lds_dwordx4 v160, s[14:15]
	s_mov_b32 m0, s61
	s_nop 0
	global_load_lds_dwordx4 v158, s[14:15]
	s_waitcnt lgkmcnt(8)
	s_barrier
	s_waitcnt lgkmcnt(0)
	s_setprio 1
	v_mfma_f32_16x16x32_bf16 v[126:129], v[130:133], v[146:149], v[126:129]
	v_mfma_f32_16x16x32_bf16 v[122:125], v[138:141], v[146:149], v[122:125]
	v_mfma_f32_16x16x32_bf16 v[118:121], v[130:133], v[154:157], v[118:121]
	v_mfma_f32_16x16x32_bf16 v[106:109], v[138:141], v[154:157], v[106:109]
	v_mfma_f32_16x16x32_bf16 v[102:105], v[130:133], v[170:173], v[102:105]
	v_mfma_f32_16x16x32_bf16 v[90:93], v[138:141], v[170:173], v[90:93]
	v_mfma_f32_16x16x32_bf16 v[82:85], v[130:133], v[178:181], v[82:85]
	v_mfma_f32_16x16x32_bf16 v[74:77], v[138:141], v[178:181], v[74:77]
	v_mfma_f32_16x16x32_bf16 v[126:129], v[134:137], v[150:153], v[126:129]
	v_mfma_f32_16x16x32_bf16 v[122:125], v[142:145], v[150:153], v[122:125]
	v_mfma_f32_16x16x32_bf16 v[118:121], v[134:137], v[166:169], v[118:121]
	v_mfma_f32_16x16x32_bf16 v[106:109], v[142:145], v[166:169], v[106:109]
	v_mfma_f32_16x16x32_bf16 v[102:105], v[134:137], v[174:177], v[102:105]
	v_mfma_f32_16x16x32_bf16 v[90:93], v[142:145], v[174:177], v[90:93]
	v_mfma_f32_16x16x32_bf16 v[82:85], v[134:137], v[182:185], v[82:85]
	v_mfma_f32_16x16x32_bf16 v[74:77], v[142:145], v[182:185], v[74:77]
	s_setprio 0
	s_barrier
	s_add_i32 s14, 0, 0x1c000
	s_add_i32 s15, s34, s53
	v_add_u32_e32 v0, s14, v202
	s_mov_b32 m0, s15
	ds_read_b128 v[198:201], v0
	ds_read_b128 v[204:207], v0 offset:1024
	ds_read_b128 v[208:211], v0 offset:2048
	ds_read_b128 v[216:219], v0 offset:3072
	global_load_lds_dwordx4 v160, s[98:99]
	s_add_i32 m0, s15, 0x2000
	s_nop 0
	global_load_lds_dwordx4 v158, s[98:99]
	s_barrier
; #define GAS __attribute__((address_space(1)))
; #define PG8_STAGE(bufoff, gbase, voff) do { _Pragma("unroll") for (int _i = 0; _i < 2; ++_i) \
;     __builtin_amdgcn_global_load_lds((const unsigned*)((const char*)(gbase) + (voff)[_i]), (LAS unsigned*)(lds + (bufoff) + ldsw + _i * 8192), 16, 0, 0); } while (0)
; #define PG8_LDA(dst, b, h) do { _Pragma("unroll") for (int m = 0; m < 4; ++m) _Pragma("unroll") for (int k = 0; k < 2; ++k) dst[m][k] = *(const LAS bf16x8*)(lds + PG8_SA(b, h) + aoff + m * 2048 + k * 1024); } while (0)
; #define PG8_WAIT_V(n) asm volatile("s_waitcnt vmcnt(" #n ")" ::: "memory")
; #define PG8_WAIT_L(n) asm volatile("s_waitcnt lgkmcnt(" #n ")" ::: "memory")
; #define PG8_BAR __builtin_amdgcn_s_barrier()
; #define PG8_SCHED __builtin_amdgcn_sched_barrier(0)
; template <class Epi, class Sched>
; DI void gemm_phase(LAS unsigned char* lds, const int tid, const Gemm g, const Sched& S, const Epi& E) {
;     ...
;       PG8_BAR; PG8_WAIT_L(0); PG8_MMA(0, 1, At, B1); PG8_BAR;
;       PG8_LDA(At, 1, 1); PG8_STAGE(PG8_SA(1, 0), a3, voffA);
;       PG8_BAR; PG8_WAIT_L(0); PG8_MMA(1, 0, At, B0); PG8_BAR; PG8_SCHED;
;       PG8_STAGE(PG8_SB(1, 1), b3 + hstepB, voffB);
;       PG8_WAIT_V(6); PG8_BAR; PG8_MMA(1, 1, At, B1); PG8_BAR;
;     }
;     { int z_e = 0; asm volatile("" : "+v"(z_e)); const int lane_e = __builtin_amdgcn_mbcnt_hi(~0u, __builtin_amdgcn_mbcnt_lo(~0u, (unsigned)z_e));
;       E(acc, cur, wr, wc, lane_e & 15, lane_e >> 4); }
;     if (!has_next) break;
;   DI void operator()(const AccT& acc, const Unit& u, int wr, int wc, int fr, int fq) const {
;     const int b = u.pm < 128 ? (u.pm >> 3) : 16;
;     const unsigned c0 = (unsigned)(wc * 32 + fq * 4) * 4u, o0 = (unsigned)((wr * 64 + fr) * D) * 4u + c0;
;     if (pctx) {
;       char* pb = (char*)(pctx + (size_t)(u.pm - 128) * 256 * D + u.pn * 256);
;       ROWS_LOOP {
;         char* rb = pb + (size_t)(ai * 128 + m * 16) * D * 4;
;         COLS_LOOP *(GAS f32x4*)(rb + (bj * 128 + n * 16) * 4 + o0) = acc[ai][bj][m][n];
;       }
;       return;
;     }
;     char* hb = (char*)((u.pm < 128 ? out + (size_t)u.pm * 256 * D : hctx + (size_t)(u.pm - 128) * 256 * D) + u.pn * 256);
;     const char* hs = (const char*)((u.pm < 128 ? hsrc + (size_t)u.pm * 256 * D : hctx + (size_t)(u.pm - 128) * 256 * D) + u.pn * 256);
;     const char* gp = (const char*)(gate + (size_t)b * NMODW + u.pn * 256);
	s_waitcnt lgkmcnt(0)
	s_setprio 1
	v_mfma_f32_16x16x32_bf16 v[114:117], v[198:201], v[146:149], v[114:117]
	v_mfma_f32_16x16x32_bf16 v[110:113], v[208:211], v[146:149], v[110:113]
	v_mfma_f32_16x16x32_bf16 v[98:101], v[198:201], v[154:157], v[98:101]
	v_mfma_f32_16x16x32_bf16 v[94:97], v[208:211], v[154:157], v[94:97]
	v_mfma_f32_16x16x32_bf16 v[86:89], v[198:201], v[170:173], v[86:89]
	v_mfma_f32_16x16x32_bf16 v[78:81], v[208:211], v[170:173], v[78:81]
	v_mfma_f32_16x16x32_bf16 v[70:73], v[198:201], v[178:181], v[70:73]
	v_mfma_f32_16x16x32_bf16 v[66:69], v[208:211], v[178:181], v[66:69]
	v_mfma_f32_16x16x32_bf16 v[114:117], v[204:207], v[150:153], v[114:117]
	v_mfma_f32_16x16x32_bf16 v[110:113], v[216:219], v[150:153], v[110:113]
	v_mfma_f32_16x16x32_bf16 v[98:101], v[204:207], v[166:169], v[98:101]
	v_mfma_f32_16x16x32_bf16 v[94:97], v[216:219], v[166:169], v[94:97]
	v_mfma_f32_16x16x32_bf16 v[86:89], v[204:207], v[174:177], v[86:89]
	v_mfma_f32_16x16x32_bf16 v[78:81], v[216:219], v[174:177], v[78:81]
	v_mfma_f32_16x16x32_bf16 v[70:73], v[204:207], v[182:185], v[70:73]
	v_mfma_f32_16x16x32_bf16 v[66:69], v[216:219], v[182:185], v[66:69]
	s_setprio 0
	s_mov_b32 m0, s75
	s_barrier
	ds_read_b128 v[146:149], v203 offset:49152
	ds_read_b128 v[150:153], v203 offset:50176
	ds_read_b128 v[154:157], v203 offset:51200
	ds_read_b128 v[166:169], v203 offset:52224
	ds_read_b128 v[170:173], v203 offset:53248
	ds_read_b128 v[174:177], v203 offset:54272
	ds_read_b128 v[178:181], v203 offset:55296
	ds_read_b128 v[182:185], v203 offset:56320
	global_load_lds_dwordx4 v160, s[100:101]
	s_mov_b32 m0, s76
	s_nop 0
	global_load_lds_dwordx4 v158, s[100:101]
	s_barrier
	s_waitcnt lgkmcnt(0)
	s_setprio 1
	v_mfma_f32_16x16x32_bf16 v[62:65], v[130:133], v[146:149], v[62:65]
	v_mfma_f32_16x16x32_bf16 v[58:61], v[138:141], v[146:149], v[58:61]
	v_mfma_f32_16x16x32_bf16 v[54:57], v[130:133], v[154:157], v[54:57]
	v_mfma_f32_16x16x32_bf16 v[42:45], v[138:141], v[154:157], v[42:45]
	v_mfma_f32_16x16x32_bf16 v[38:41], v[130:133], v[170:173], v[38:41]
	v_mfma_f32_16x16x32_bf16 v[26:29], v[138:141], v[170:173], v[26:29]
	v_mfma_f32_16x16x32_bf16 v[22:25], v[130:133], v[178:181], v[22:25]
	v_mfma_f32_16x16x32_bf16 v[14:17], v[138:141], v[178:181], v[14:17]
	v_mfma_f32_16x16x32_bf16 v[62:65], v[134:137], v[150:153], v[62:65]
	v_mfma_f32_16x16x32_bf16 v[58:61], v[142:145], v[150:153], v[58:61]
	v_mfma_f32_16x16x32_bf16 v[54:57], v[134:137], v[166:169], v[54:57]
	v_mfma_f32_16x16x32_bf16 v[42:45], v[142:145], v[166:169], v[42:45]
	v_mfma_f32_16x16x32_bf16 v[38:41], v[134:137], v[174:177], v[38:41]
	v_mfma_f32_16x16x32_bf16 v[26:29], v[142:145], v[174:177], v[26:29]
	v_mfma_f32_16x16x32_bf16 v[22:25], v[134:137], v[182:185], v[22:25]
	v_mfma_f32_16x16x32_bf16 v[14:17], v[142:145], v[182:185], v[14:17]
	s_setprio 0
	s_barrier
	s_add_i32 s14, s14, s53
	v_lshl_add_u64 v[130:131], v[226:227], 0, s[50:51]
	s_mov_b32 m0, s14
	s_nop 0
	global_load_lds_dwordx4 v[130:131], off
	v_lshl_add_u64 v[130:131], v[228:229], 0, s[50:51]
	s_add_i32 m0, s14, 0x2000
	s_nop 0
	global_load_lds_dwordx4 v[130:131], off
	s_waitcnt vmcnt(6)
	s_barrier
	s_setprio 1
	v_mfma_f32_16x16x32_bf16 v[50:53], v[198:201], v[146:149], v[50:53]
	v_mfma_f32_16x16x32_bf16 v[46:49], v[208:211], v[146:149], v[46:49]
	v_mfma_f32_16x16x32_bf16 v[34:37], v[198:201], v[154:157], v[34:37]
	v_mfma_f32_16x16x32_bf16 v[30:33], v[208:211], v[154:157], v[30:33]
	v_mfma_f32_16x16x32_bf16 v[18:21], v[198:201], v[170:173], v[18:21]
	v_mfma_f32_16x16x32_bf16 v[10:13], v[208:211], v[170:173], v[10:13]
	v_mfma_f32_16x16x32_bf16 v[6:9], v[198:201], v[178:181], v[6:9]
	v_mfma_f32_16x16x32_bf16 v[2:5], v[208:211], v[178:181], v[2:5]
	v_mfma_f32_16x16x32_bf16 v[50:53], v[204:207], v[150:153], v[50:53]
	v_mfma_f32_16x16x32_bf16 v[46:49], v[216:219], v[150:153], v[46:49]
	v_mfma_f32_16x16x32_bf16 v[34:37], v[204:207], v[166:169], v[34:37]
	v_mfma_f32_16x16x32_bf16 v[30:33], v[216:219], v[166:169], v[30:33]
	v_mfma_f32_16x16x32_bf16 v[18:21], v[204:207], v[174:177], v[18:21]
	v_mfma_f32_16x16x32_bf16 v[10:13], v[216:219], v[174:177], v[10:13]
	v_mfma_f32_16x16x32_bf16 v[6:9], v[204:207], v[182:185], v[6:9]
	v_mfma_f32_16x16x32_bf16 v[2:5], v[216:219], v[182:185], v[2:5]
	s_setprio 0
	s_add_u32 s38, s38, 0x100
	s_addc_u32 s39, s39, 0
	s_add_u32 s30, s30, 0x100
	s_addc_u32 s31, s31, 0
	s_cmp_ge_u32 s88, s74
	s_mov_b32 s14, s88
	s_barrier
	s_cbranch_scc0 .LBB0_824
	s_cmpk_lt_i32 s86, 0x80
	v_mov_b32_e32 v0, 0
	s_cselect_b64 s[30:31], -1, 0
	s_cmpk_gt_i32 s86, 0x7f
	s_mov_b64 s[14:15], 0x24000
	s_cbranch_scc1 .LBB0_827
	s_ashr_i32 s14, s86, 3
	s_mul_hi_i32 s15, s14, 0x2400
	s_mulk_i32 s14, 0x2400
